# EpiConv epilogue rewritten: token shift through a wave-private LDS strip (ds_write/read_b64) instead of DPP+cndmask, bit-identical math; dppzero dropped
# baseline (speedup 1.0000x reference)
;     __device__ __forceinline__ void operator()(const f32x4 (&acc)[2][2][4][2], const Unit& u, int wr, int wc, int fr, int fq) const {
;     ...
;         for (int bj = 0; bj < 2; ++bj) { const int col = bj * 2816 + ch0;
;             w0[bj] = *(const f32x4*)(cw + col); w1[bj] = *(const f32x4*)(cw + 5632 + col); w2[bj] = *(const f32x4*)(cw + 11264 + col); bb[bj] = *(const f32x4*)(cb + col); }
; #pragma unroll
;         for (int ai = 0; ai < 2; ++ai) { const int blk = ai * 2 + wr;
;             if (fr == 0) {
; #pragma unroll
;                 for (int bj = 0; bj < 2; ++bj)
; #pragma unroll
;                     for (int n = 0; n < 2; ++n) *(PG8_LAS f32x4*)(xb + ((((blk * 2 + 0) * 4 + wc) * 4 + fq) * 16 + (bj * 2 + n) * 4)) = acc[ai][bj][0][n]; }
;             if (fr == 15) {
; #pragma unroll
;                 for (int bj = 0; bj < 2; ++bj)
; #pragma unroll
;                     for (int n = 0; n < 2; ++n) *(PG8_LAS f32x4*)(xb + ((((blk * 2 + 1) * 4 + wc) * 4 + fq) * 16 + (bj * 2 + n) * 4)) = acc[ai][bj][3][n]; } }
;         asm volatile("s_waitcnt lgkmcnt(0)" ::: "memory"); __builtin_amdgcn_s_barrier(); asm volatile("" ::: "memory");
;     ...
;                     for (int bj = 0; bj < 2; ++bj) { const f32x4 cur = acc[ai][bj][m][n];
;                         f32x4 su = cur, sd = cur;
;                         if (m > 0) { if (fr == 15) su = acc[ai][bj][m > 0 ? m - 1 : 0][n]; }
;                         if (m < 3) { if (fr == 0) sd = acc[ai][bj][m < 3 ? m + 1 : 3][n]; }
;                         f32x4 up, dn;
;                         up[0] = dpp_ror1(su[0]); up[1] = dpp_ror1(su[1]); up[2] = dpp_ror1(su[2]); up[3] = dpp_ror1(su[3]);
;                         dn[0] = dpp_ror15(sd[0]); dn[1] = dpp_ror15(sd[1]); dn[2] = dpp_ror15(sd[2]); dn[3] = dpp_ror15(sd[3]);
;                         if (m == 0) { f32x4 halo = zero4; if (blk > 0) halo = *(const PG8_LAS f32x4*)(xb + (((((blk - 1) * 2 + 1) * 4 + wc) * 4 + fq) * 16 + (bj * 2 + n) * 4)); if (fr == 0) up = halo; }
;                         if (m == 3) { f32x4 halo = zero4; if (blk < 3) halo = *(const PG8_LAS f32x4*)(xb + (((((blk + 1) * 2 + 0) * 4 + wc) * 4 + fq) * 16 + (bj * 2 + n) * 4)); if (fr == 15) dn = halo; }
;                         if (edge) { if (!upok) up = zero4; if (!dnok) dn = zero4; }
;                         res[bj] = bb[bj] + w0[bj] * up + w1[bj] * cur + w2[bj] * dn; }
.LBB0_705:
	v_lshl_or_b32 v248, s2, 7, v229
	v_lshlrev_b32_e32 v247, 1, v248
	v_lshlrev_b32_e32 v248, 2, v248
	v_add_u32_e32 v249, 0x2c00, v248
	global_load_dwordx4 v[106:109], v248, s[62:63]
	global_load_dwordx4 v[110:113], v248, s[66:67]
	global_load_dwordx4 v[114:117], v248, s[68:69]
	global_load_dwordx4 v[118:121], v248, s[64:65]
	global_load_dwordx4 v[122:125], v249, s[62:63]
	global_load_dwordx4 v[126:129], v249, s[66:67]
	global_load_dwordx4 v[130:133], v249, s[68:69]
	global_load_dwordx4 v[134:137], v249, s[64:65]
	v_readlane_b32 s10, v254, 4
	v_readlane_b32 s11, v254, 5
	s_add_i32 s0, s78, s48
	s_mulk_i32 s0, 0x1600
	s_movk_i32 s29, 0x1600
	s_add_i32 s28, s93, -1
	v_add_u32_e32 v247, s0, v247
	v_mov_b32_e32 v202, 0
	v_mov_b32_e32 v203, 0
	v_and_b32_e32 v250, 7, v226
	v_lshlrev_b32_e32 v250, 3, v250
	v_add_u32_e32 v250, 0x27000, v250
	ds_write_b64 v250, v[202:203]
	s_mov_b64 exec, s[6:7]
	ds_write_b128 v238, v[166:169]
	ds_write_b128 v238, v[70:73] offset:16
	ds_write_b128 v238, v[162:165] offset:32
	ds_write_b128 v238, v[66:69] offset:48
	ds_write_b128 v239, v[102:105]
	ds_write_b128 v239, v[30:33] offset:16
	ds_write_b128 v239, v[98:101] offset:32
	ds_write_b128 v239, v[26:29] offset:48
	s_mov_b64 exec, s[4:5]
	ds_write_b128 v238, v[142:145] offset:1024
	ds_write_b128 v238, v[46:49] offset:1040
	ds_write_b128 v238, v[138:141] offset:1056
	ds_write_b128 v238, v[42:45] offset:1072
	ds_write_b128 v239, v[78:81] offset:1024
	ds_write_b128 v239, v[6:9] offset:1040
	ds_write_b128 v239, v[74:77] offset:1056
	ds_write_b128 v239, v[2:5] offset:1072
	s_mov_b64 exec, -1
	v_and_b32_e32 v250, 0xb00, v238
	v_lshlrev_b32_e32 v250, 3, v250
	v_bfe_u32 v251, v238, 6, 2
	v_lshl_add_u32 v250, v251, 3, v250
	v_lshl_add_u32 v250, v226, 5, v250
	v_add_u32_e32 v243, 0x20000, v250
	v_add_u32_e32 v244, 0xffffffe0, v243
	v_add_u32_e32 v250, 0xfffffc00, v238
	v_mov_b32_e32 v251, 0x27000
	v_cndmask_b32_e64 v245, v251, v250, s[74:75]
	v_add_u32_e32 v250, 0x800, v239
	v_cndmask_b32_e64 v246, v250, v251, s[74:75]
	s_waitcnt lgkmcnt(0)
	s_barrier
	s_cmp_lt_i32 s48, 1
	s_cbranch_scc1 .Lec_edge
	s_add_i32 s0, s48, 0x100
	s_cmp_ge_i32 s0, s93
	s_cbranch_scc1 .Lec_edge
	v_cmp_le_i32_e64 s[12:13], s54, v227
	v_cmp_gt_i32_e32 vcc, s55, v227
	s_and_b64 s[12:13], s[12:13], vcc
	v_cmp_le_i32_e64 s[14:15], s54, v231
	v_cmp_gt_i32_e32 vcc, s55, v231
	s_and_b64 s[14:15], s[14:15], vcc
	v_cmp_le_i32_e64 s[16:17], s54, v232
	v_cmp_gt_i32_e32 vcc, s55, v232
	s_and_b64 s[16:17], s[16:17], vcc
	v_cmp_le_i32_e64 s[18:19], s54, v233
	v_cmp_gt_i32_e32 vcc, s55, v233
	s_and_b64 s[18:19], s[18:19], vcc
	v_cmp_le_i32_e64 s[20:21], s54, v234
	v_cmp_gt_i32_e32 vcc, s55, v234
	s_and_b64 s[20:21], s[20:21], vcc
	v_cmp_le_i32_e64 s[22:23], s54, v235
	v_cmp_gt_i32_e32 vcc, s55, v235
	s_and_b64 s[22:23], s[22:23], vcc
	v_cmp_le_i32_e64 s[24:25], s54, v236
	v_cmp_gt_i32_e32 vcc, s55, v236
	s_and_b64 s[24:25], s[24:25], vcc
	v_cmp_le_i32_e64 s[26:27], s54, v237
	v_cmp_gt_i32_e32 vcc, s55, v237
	s_and_b64 s[26:27], s[26:27], vcc
	ds_write_b64 v243, v[166:167]
	ds_write_b64 v243, v[158:159] offset:512
	ds_write_b64 v243, v[150:151] offset:1024
	ds_write_b64 v243, v[142:143] offset:1536
	ds_read_b64 v[170:171], v244
	ds_read_b64 v[178:179], v243 offset:32
	ds_read_b64 v[198:199], v245
	ds_read_b64 v[172:173], v244 offset:512
	ds_read_b64 v[180:181], v243 offset:544
	ds_read_b64 v[174:175], v244 offset:1024
	ds_read_b64 v[194:195], v243 offset:1056
	ds_read_b64 v[176:177], v244 offset:1536
	ds_read_b64 v[196:197], v243 offset:1568
	ds_read_b64 v[200:201], v238 offset:2048
	s_waitcnt vmcnt(0)
	ds_write_b64 v243, v[168:169]
	ds_write_b64 v243, v[160:161] offset:512
	ds_write_b64 v243, v[152:153] offset:1024
	ds_write_b64 v243, v[144:145] offset:1536
	s_waitcnt lgkmcnt(11)
	v_cndmask_b32_e64 v170, v170, v198, s[6:7]
	v_cndmask_b32_e64 v171, v171, v199, s[6:7]
	v_pk_fma_f32 v[202:203], v[106:107], v[170:171], v[118:119]
	v_pk_fma_f32 v[166:167], v[166:167], v[110:111], v[202:203]
	v_pk_fma_f32 v[166:167], v[114:115], v[178:179], v[166:167]
	ds_read_b64 v[170:171], v244
	ds_read_b64 v[178:179], v243 offset:32
	ds_read_b64 v[198:199], v245 offset:8
	s_waitcnt lgkmcnt(12)
	v_pk_fma_f32 v[202:203], v[106:107], v[172:173], v[118:119]
	v_pk_fma_f32 v[158:159], v[158:159], v[110:111], v[202:203]
	v_pk_fma_f32 v[158:159], v[114:115], v[180:181], v[158:159]
	ds_read_b64 v[172:173], v244 offset:512
	ds_read_b64 v[180:181], v243 offset:544
	s_waitcnt lgkmcnt(12)
	v_pk_fma_f32 v[202:203], v[106:107], v[174:175], v[118:119]
	v_pk_fma_f32 v[150:151], v[150:151], v[110:111], v[202:203]
	v_pk_fma_f32 v[150:151], v[114:115], v[194:195], v[150:151]
	ds_read_b64 v[174:175], v244 offset:1024
	ds_read_b64 v[194:195], v243 offset:1056
	s_waitcnt lgkmcnt(11)
	v_cndmask_b32_e64 v196, v196, v200, s[4:5]
	v_cndmask_b32_e64 v197, v197, v201, s[4:5]
	v_pk_fma_f32 v[202:203], v[106:107], v[176:177], v[118:119]
	v_pk_fma_f32 v[142:143], v[142:143], v[110:111], v[202:203]
	v_pk_fma_f32 v[142:143], v[114:115], v[196:197], v[142:143]
	ds_read_b64 v[176:177], v244 offset:1536
	ds_read_b64 v[196:197], v243 offset:1568
	ds_read_b64 v[200:201], v238 offset:2056
	ds_write_b64 v243, v[162:163]
	ds_write_b64 v243, v[154:155] offset:512
	ds_write_b64 v243, v[146:147] offset:1024
	ds_write_b64 v243, v[138:139] offset:1536
	s_waitcnt lgkmcnt(11)
	v_cndmask_b32_e64 v170, v170, v198, s[6:7]
	v_cndmask_b32_e64 v171, v171, v199, s[6:7]
	v_pk_fma_f32 v[202:203], v[108:109], v[170:171], v[120:121]
	v_pk_fma_f32 v[168:169], v[168:169], v[112:113], v[202:203]
	v_pk_fma_f32 v[168:169], v[116:117], v[178:179], v[168:169]
	ds_read_b64 v[170:171], v244
	ds_read_b64 v[178:179], v243 offset:32
	ds_read_b64 v[198:199], v245 offset:32
	s_waitcnt lgkmcnt(12)
; #define PG8_LAS __attribute__((address_space(3)))
; __device__ __forceinline__ unsigned cvt_pk_bf16(float lo, float hi) { unsigned r; asm volatile("v_cvt_pk_bf16_f32 %0, %1, %2" : "=v"(r) : "v"(lo), "v"(hi)); return r; }
;     __device__ __forceinline__ void operator()(const f32x4 (&acc)[2][2][4][2], const Unit& u, int wr, int wc, int fr, int fq) const {
;     ...
;                 for (int m = 0; m < 4; ++m) { const int r = 128 * ai + 64 * wr + 16 * m + fr, t = tstart + r;
;                     const bool upok = t >= 1, dnok = (t + 1) < T, store_ok = (r >= vlo) && (r < vhi) && (t < T);
;                     f32x4 res[2];
; #pragma unroll
;                     for (int bj = 0; bj < 2; ++bj) { const f32x4 cur = acc[ai][bj][m][n];
;                         f32x4 su = cur, sd = cur;
;                         if (m > 0) { if (fr == 15) su = acc[ai][bj][m > 0 ? m - 1 : 0][n]; }
;                         if (m < 3) { if (fr == 0) sd = acc[ai][bj][m < 3 ? m + 1 : 3][n]; }
;                         f32x4 up, dn;
;                         up[0] = dpp_ror1(su[0]); up[1] = dpp_ror1(su[1]); up[2] = dpp_ror1(su[2]); up[3] = dpp_ror1(su[3]);
;                         dn[0] = dpp_ror15(sd[0]); dn[1] = dpp_ror15(sd[1]); dn[2] = dpp_ror15(sd[2]); dn[3] = dpp_ror15(sd[3]);
;                         if (m == 0) { f32x4 halo = zero4; if (blk > 0) halo = *(const PG8_LAS f32x4*)(xb + (((((blk - 1) * 2 + 1) * 4 + wc) * 4 + fq) * 16 + (bj * 2 + n) * 4)); if (fr == 0) up = halo; }
;                         if (m == 3) { f32x4 halo = zero4; if (blk < 3) halo = *(const PG8_LAS f32x4*)(xb + (((((blk + 1) * 2 + 0) * 4 + wc) * 4 + fq) * 16 + (bj * 2 + n) * 4)); if (fr == 15) dn = halo; }
;                         if (edge) { if (!upok) up = zero4; if (!dnok) dn = zero4; }
;                         res[bj] = bb[bj] + w0[bj] * up + w1[bj] * cur + w2[bj] * dn; }
;                     if (store_ok) {
;                         float o[4];
; #pragma unroll
;                         for (int j = 0; j < 4; ++j) { const float gg = res[1][j]; o[j] = gg * __builtin_amdgcn_rcpf(1.f + __expf(-gg)) * res[0][j]; }
;                         u32x2 w; w.x = cvt_pk_bf16(o[0], o[1]); w.y = cvt_pk_bf16(o[2], o[3]);
;                         *(u32x2*)(ACT + (size_t)(seqrow + t) * 2816 + ch0 + 4 * n) = w; } } }
	v_pk_fma_f32 v[202:203], v[108:109], v[172:173], v[120:121]
	v_pk_fma_f32 v[160:161], v[160:161], v[112:113], v[202:203]
	v_pk_fma_f32 v[160:161], v[116:117], v[180:181], v[160:161]
	ds_read_b64 v[172:173], v244 offset:512
	ds_read_b64 v[180:181], v243 offset:544
	s_waitcnt lgkmcnt(12)
	v_pk_fma_f32 v[202:203], v[108:109], v[174:175], v[120:121]
	v_pk_fma_f32 v[152:153], v[152:153], v[112:113], v[202:203]
	v_pk_fma_f32 v[152:153], v[116:117], v[194:195], v[152:153]
	ds_read_b64 v[174:175], v244 offset:1024
	ds_read_b64 v[194:195], v243 offset:1056
	s_waitcnt lgkmcnt(11)
	v_cndmask_b32_e64 v196, v196, v200, s[4:5]
	v_cndmask_b32_e64 v197, v197, v201, s[4:5]
	v_pk_fma_f32 v[202:203], v[108:109], v[176:177], v[120:121]
	v_pk_fma_f32 v[144:145], v[144:145], v[112:113], v[202:203]
	v_pk_fma_f32 v[144:145], v[116:117], v[196:197], v[144:145]
	ds_read_b64 v[176:177], v244 offset:1536
	ds_read_b64 v[196:197], v243 offset:1568
	ds_read_b64 v[200:201], v238 offset:2080
	ds_write_b64 v243, v[164:165]
	ds_write_b64 v243, v[156:157] offset:512
	ds_write_b64 v243, v[148:149] offset:1024
	ds_write_b64 v243, v[140:141] offset:1536
	s_waitcnt lgkmcnt(11)
	v_cndmask_b32_e64 v170, v170, v198, s[6:7]
	v_cndmask_b32_e64 v171, v171, v199, s[6:7]
	v_pk_fma_f32 v[202:203], v[122:123], v[170:171], v[134:135]
	v_pk_fma_f32 v[162:163], v[162:163], v[126:127], v[202:203]
	v_pk_fma_f32 v[162:163], v[130:131], v[178:179], v[162:163]
	ds_read_b64 v[170:171], v244
	ds_read_b64 v[178:179], v243 offset:32
	ds_read_b64 v[198:199], v245 offset:40
	s_waitcnt lgkmcnt(12)
	v_pk_fma_f32 v[202:203], v[122:123], v[172:173], v[134:135]
	v_pk_fma_f32 v[154:155], v[154:155], v[126:127], v[202:203]
	v_pk_fma_f32 v[154:155], v[130:131], v[180:181], v[154:155]
	ds_read_b64 v[172:173], v244 offset:512
	ds_read_b64 v[180:181], v243 offset:544
	s_waitcnt lgkmcnt(12)
	v_pk_fma_f32 v[202:203], v[122:123], v[174:175], v[134:135]
	v_pk_fma_f32 v[146:147], v[146:147], v[126:127], v[202:203]
	v_pk_fma_f32 v[146:147], v[130:131], v[194:195], v[146:147]
	ds_read_b64 v[174:175], v244 offset:1024
	ds_read_b64 v[194:195], v243 offset:1056
	s_waitcnt lgkmcnt(11)
	v_cndmask_b32_e64 v196, v196, v200, s[4:5]
	v_cndmask_b32_e64 v197, v197, v201, s[4:5]
	v_pk_fma_f32 v[202:203], v[122:123], v[176:177], v[134:135]
	v_pk_fma_f32 v[138:139], v[138:139], v[126:127], v[202:203]
	v_pk_fma_f32 v[138:139], v[130:131], v[196:197], v[138:139]
	ds_read_b64 v[176:177], v244 offset:1536
	ds_read_b64 v[196:197], v243 offset:1568
	ds_read_b64 v[200:201], v238 offset:2088
	ds_write_b64 v243, v[102:103]
	ds_write_b64 v243, v[94:95] offset:512
	ds_write_b64 v243, v[86:87] offset:1024
	ds_write_b64 v243, v[78:79] offset:1536
	s_waitcnt lgkmcnt(11)
	v_cndmask_b32_e64 v170, v170, v198, s[6:7]
	v_cndmask_b32_e64 v171, v171, v199, s[6:7]
	v_pk_fma_f32 v[202:203], v[124:125], v[170:171], v[136:137]
	v_pk_fma_f32 v[164:165], v[164:165], v[128:129], v[202:203]
	v_pk_fma_f32 v[164:165], v[132:133], v[178:179], v[164:165]
	ds_read_b64 v[170:171], v244
	ds_read_b64 v[178:179], v243 offset:32
	ds_read_b64 v[198:199], v238 offset:3072
	s_waitcnt lgkmcnt(12)
	v_pk_fma_f32 v[202:203], v[124:125], v[172:173], v[136:137]
	v_pk_fma_f32 v[156:157], v[156:157], v[128:129], v[202:203]
	v_pk_fma_f32 v[156:157], v[132:133], v[180:181], v[156:157]
	ds_read_b64 v[172:173], v244 offset:512
	ds_read_b64 v[180:181], v243 offset:544
	s_waitcnt lgkmcnt(12)
	v_pk_fma_f32 v[202:203], v[124:125], v[174:175], v[136:137]
	v_pk_fma_f32 v[148:149], v[148:149], v[128:129], v[202:203]
	v_pk_fma_f32 v[148:149], v[132:133], v[194:195], v[148:149]
	ds_read_b64 v[174:175], v244 offset:1024
	ds_read_b64 v[194:195], v243 offset:1056
	s_waitcnt lgkmcnt(11)
	v_cndmask_b32_e64 v196, v196, v200, s[4:5]
	v_cndmask_b32_e64 v197, v197, v201, s[4:5]
	v_pk_fma_f32 v[202:203], v[124:125], v[176:177], v[136:137]
	v_pk_fma_f32 v[140:141], v[140:141], v[128:129], v[202:203]
	v_pk_fma_f32 v[140:141], v[132:133], v[196:197], v[140:141]
	ds_read_b64 v[176:177], v244 offset:1536
	ds_read_b64 v[196:197], v243 offset:1568
	ds_read_b64 v[200:201], v246
	v_mul_f32_e32 v208, 0xbfb8aa3b, v162
	v_mul_f32_e32 v209, 0xbfb8aa3b, v163
	v_mul_f32_e32 v210, 0xbfb8aa3b, v164
	v_mul_f32_e32 v211, 0xbfb8aa3b, v165
	v_exp_f32_e32 v208, v208
	v_exp_f32_e32 v209, v209
	v_exp_f32_e32 v210, v210
	v_exp_f32_e32 v211, v211
	v_add_f32_e32 v208, 1.0, v208
	v_add_f32_e32 v209, 1.0, v209
	v_add_f32_e32 v210, 1.0, v210
	v_add_f32_e32 v211, 1.0, v211
	v_rcp_f32_e32 v208, v208
	v_rcp_f32_e32 v209, v209
	v_rcp_f32_e32 v210, v210
	v_rcp_f32_e32 v211, v211
	v_mul_f32_e32 v162, v162, v208
	v_mul_f32_e32 v163, v163, v209
	v_mul_f32_e32 v164, v164, v210
	v_mul_f32_e32 v165, v165, v211
	v_mul_f32_e32 v162, v166, v162
	v_mul_f32_e32 v163, v167, v163
	v_mul_f32_e32 v164, v168, v164
	v_mul_f32_e32 v165, v169, v165
	v_cvt_pk_bf16_f32 v212, v162, v163
	v_cvt_pk_bf16_f32 v213, v164, v165
	v_mad_u32_u24 v221, v227, s29, v247
	s_and_saveexec_b64 s[30:31], s[12:13]
	global_store_dwordx2 v221, v[212:213], s[10:11]
	s_mov_b64 exec, s[30:31]
	v_mul_f32_e32 v208, 0xbfb8aa3b, v154
	v_mul_f32_e32 v209, 0xbfb8aa3b, v155
	v_mul_f32_e32 v210, 0xbfb8aa3b, v156
	v_mul_f32_e32 v211, 0xbfb8aa3b, v157
	v_exp_f32_e32 v208, v208
	v_exp_f32_e32 v209, v209
	v_exp_f32_e32 v210, v210
	v_exp_f32_e32 v211, v211
	v_add_f32_e32 v208, 1.0, v208
	v_add_f32_e32 v209, 1.0, v209
	v_add_f32_e32 v210, 1.0, v210
	v_add_f32_e32 v211, 1.0, v211
	v_rcp_f32_e32 v208, v208
	v_rcp_f32_e32 v209, v209
	v_rcp_f32_e32 v210, v210
	v_rcp_f32_e32 v211, v211
	v_mul_f32_e32 v154, v154, v208
	v_mul_f32_e32 v155, v155, v209
	v_mul_f32_e32 v156, v156, v210
; #define PG8_LAS __attribute__((address_space(3)))
; __device__ __forceinline__ unsigned cvt_pk_bf16(float lo, float hi) { unsigned r; asm volatile("v_cvt_pk_bf16_f32 %0, %1, %2" : "=v"(r) : "v"(lo), "v"(hi)); return r; }
;     __device__ __forceinline__ void operator()(const f32x4 (&acc)[2][2][4][2], const Unit& u, int wr, int wc, int fr, int fq) const {
;     ...
;                 for (int m = 0; m < 4; ++m) { const int r = 128 * ai + 64 * wr + 16 * m + fr, t = tstart + r;
;                     const bool upok = t >= 1, dnok = (t + 1) < T, store_ok = (r >= vlo) && (r < vhi) && (t < T);
;                     f32x4 res[2];
; #pragma unroll
;                     for (int bj = 0; bj < 2; ++bj) { const f32x4 cur = acc[ai][bj][m][n];
;                         f32x4 su = cur, sd = cur;
;                         if (m > 0) { if (fr == 15) su = acc[ai][bj][m > 0 ? m - 1 : 0][n]; }
;                         if (m < 3) { if (fr == 0) sd = acc[ai][bj][m < 3 ? m + 1 : 3][n]; }
;                         f32x4 up, dn;
;                         up[0] = dpp_ror1(su[0]); up[1] = dpp_ror1(su[1]); up[2] = dpp_ror1(su[2]); up[3] = dpp_ror1(su[3]);
;                         dn[0] = dpp_ror15(sd[0]); dn[1] = dpp_ror15(sd[1]); dn[2] = dpp_ror15(sd[2]); dn[3] = dpp_ror15(sd[3]);
;                         if (m == 0) { f32x4 halo = zero4; if (blk > 0) halo = *(const PG8_LAS f32x4*)(xb + (((((blk - 1) * 2 + 1) * 4 + wc) * 4 + fq) * 16 + (bj * 2 + n) * 4)); if (fr == 0) up = halo; }
;                         if (m == 3) { f32x4 halo = zero4; if (blk < 3) halo = *(const PG8_LAS f32x4*)(xb + (((((blk + 1) * 2 + 0) * 4 + wc) * 4 + fq) * 16 + (bj * 2 + n) * 4)); if (fr == 15) dn = halo; }
;                         if (edge) { if (!upok) up = zero4; if (!dnok) dn = zero4; }
;                         res[bj] = bb[bj] + w0[bj] * up + w1[bj] * cur + w2[bj] * dn; }
;                     if (store_ok) {
;                         float o[4];
; #pragma unroll
;                         for (int j = 0; j < 4; ++j) { const float gg = res[1][j]; o[j] = gg * __builtin_amdgcn_rcpf(1.f + __expf(-gg)) * res[0][j]; }
;                         u32x2 w; w.x = cvt_pk_bf16(o[0], o[1]); w.y = cvt_pk_bf16(o[2], o[3]);
;                         *(u32x2*)(ACT + (size_t)(seqrow + t) * 2816 + ch0 + 4 * n) = w; } } }
	v_mul_f32_e32 v157, v157, v211
	v_mul_f32_e32 v154, v158, v154
	v_mul_f32_e32 v155, v159, v155
	v_mul_f32_e32 v156, v160, v156
	v_mul_f32_e32 v157, v161, v157
	v_cvt_pk_bf16_f32 v218, v154, v155
	v_cvt_pk_bf16_f32 v219, v156, v157
	v_mad_u32_u24 v40, v231, s29, v247
	s_and_saveexec_b64 s[30:31], s[14:15]
	global_store_dwordx2 v40, v[218:219], s[10:11]
	s_mov_b64 exec, s[30:31]
	v_mul_f32_e32 v208, 0xbfb8aa3b, v146
	v_mul_f32_e32 v209, 0xbfb8aa3b, v147
	v_mul_f32_e32 v210, 0xbfb8aa3b, v148
	v_mul_f32_e32 v211, 0xbfb8aa3b, v149
	v_exp_f32_e32 v208, v208
	v_exp_f32_e32 v209, v209
	v_exp_f32_e32 v210, v210
	v_exp_f32_e32 v211, v211
	v_add_f32_e32 v208, 1.0, v208
	v_add_f32_e32 v209, 1.0, v209
	v_add_f32_e32 v210, 1.0, v210
	v_add_f32_e32 v211, 1.0, v211
	v_rcp_f32_e32 v208, v208
	v_rcp_f32_e32 v209, v209
	v_rcp_f32_e32 v210, v210
	v_rcp_f32_e32 v211, v211
	v_mul_f32_e32 v146, v146, v208
	v_mul_f32_e32 v147, v147, v209
	v_mul_f32_e32 v148, v148, v210
	v_mul_f32_e32 v149, v149, v211
	v_mul_f32_e32 v146, v150, v146
	v_mul_f32_e32 v147, v151, v147
	v_mul_f32_e32 v148, v152, v148
	v_mul_f32_e32 v149, v153, v149
	v_cvt_pk_bf16_f32 v212, v146, v147
	v_cvt_pk_bf16_f32 v213, v148, v149
	v_mad_u32_u24 v221, v232, s29, v247
	s_and_saveexec_b64 s[30:31], s[16:17]
	global_store_dwordx2 v221, v[212:213], s[10:11]
	s_mov_b64 exec, s[30:31]
	v_mul_f32_e32 v208, 0xbfb8aa3b, v138
	v_mul_f32_e32 v209, 0xbfb8aa3b, v139
	v_mul_f32_e32 v210, 0xbfb8aa3b, v140
	v_mul_f32_e32 v211, 0xbfb8aa3b, v141
	v_exp_f32_e32 v208, v208
	v_exp_f32_e32 v209, v209
	v_exp_f32_e32 v210, v210
	v_exp_f32_e32 v211, v211
	v_add_f32_e32 v208, 1.0, v208
	v_add_f32_e32 v209, 1.0, v209
	v_add_f32_e32 v210, 1.0, v210
	v_add_f32_e32 v211, 1.0, v211
	v_rcp_f32_e32 v208, v208
	v_rcp_f32_e32 v209, v209
	v_rcp_f32_e32 v210, v210
	v_rcp_f32_e32 v211, v211
	v_mul_f32_e32 v138, v138, v208
	v_mul_f32_e32 v139, v139, v209
	v_mul_f32_e32 v140, v140, v210
	v_mul_f32_e32 v141, v141, v211
	v_mul_f32_e32 v138, v142, v138
	v_mul_f32_e32 v139, v143, v139
	v_mul_f32_e32 v140, v144, v140
	v_mul_f32_e32 v141, v145, v141
	v_cvt_pk_bf16_f32 v218, v138, v139
	v_cvt_pk_bf16_f32 v219, v140, v141
	v_mad_u32_u24 v40, v233, s29, v247
	s_and_saveexec_b64 s[30:31], s[18:19]
	global_store_dwordx2 v40, v[218:219], s[10:11]
	s_mov_b64 exec, s[30:31]
	global_load_dwordx4 v[138:141], v248, s[62:63] offset:16
	global_load_dwordx4 v[142:145], v248, s[66:67] offset:16
	global_load_dwordx4 v[146:149], v248, s[68:69] offset:16
	global_load_dwordx4 v[150:153], v248, s[64:65] offset:16
	global_load_dwordx4 v[154:157], v249, s[62:63] offset:16
	global_load_dwordx4 v[158:161], v249, s[66:67] offset:16
	global_load_dwordx4 v[162:165], v249, s[68:69] offset:16
	global_load_dwordx4 v[166:169], v249, s[64:65] offset:16
	ds_write_b64 v243, v[104:105]
	ds_write_b64 v243, v[96:97] offset:512
	ds_write_b64 v243, v[88:89] offset:1024
	ds_write_b64 v243, v[80:81] offset:1536
	s_waitcnt lgkmcnt(11)
	v_cndmask_b32_e64 v170, v170, v198, s[6:7]
	v_cndmask_b32_e64 v171, v171, v199, s[6:7]
	v_pk_fma_f32 v[202:203], v[106:107], v[170:171], v[118:119]
	v_pk_fma_f32 v[102:103], v[102:103], v[110:111], v[202:203]
	v_pk_fma_f32 v[102:103], v[114:115], v[178:179], v[102:103]
	ds_read_b64 v[170:171], v244
	ds_read_b64 v[178:179], v243 offset:32
	ds_read_b64 v[198:199], v238 offset:3080
	s_waitcnt lgkmcnt(12)
	v_pk_fma_f32 v[202:203], v[106:107], v[172:173], v[118:119]
	v_pk_fma_f32 v[94:95], v[94:95], v[110:111], v[202:203]
	v_pk_fma_f32 v[94:95], v[114:115], v[180:181], v[94:95]
	ds_read_b64 v[172:173], v244 offset:512
	ds_read_b64 v[180:181], v243 offset:544
	s_waitcnt lgkmcnt(12)
	v_pk_fma_f32 v[202:203], v[106:107], v[174:175], v[118:119]
	v_pk_fma_f32 v[86:87], v[86:87], v[110:111], v[202:203]
	v_pk_fma_f32 v[86:87], v[114:115], v[194:195], v[86:87]
	ds_read_b64 v[174:175], v244 offset:1024
	ds_read_b64 v[194:195], v243 offset:1056
	s_waitcnt lgkmcnt(11)
	v_cndmask_b32_e64 v196, v196, v200, s[4:5]
	v_cndmask_b32_e64 v197, v197, v201, s[4:5]
	v_pk_fma_f32 v[202:203], v[106:107], v[176:177], v[118:119]
	v_pk_fma_f32 v[78:79], v[78:79], v[110:111], v[202:203]
	v_pk_fma_f32 v[78:79], v[114:115], v[196:197], v[78:79]
	ds_read_b64 v[176:177], v244 offset:1536
	ds_read_b64 v[196:197], v243 offset:1568
	ds_read_b64 v[200:201], v246 offset:8
	ds_write_b64 v243, v[98:99]
	ds_write_b64 v243, v[90:91] offset:512
	ds_write_b64 v243, v[82:83] offset:1024
	ds_write_b64 v243, v[74:75] offset:1536
	s_waitcnt lgkmcnt(11)
	v_cndmask_b32_e64 v170, v170, v198, s[6:7]
	v_cndmask_b32_e64 v171, v171, v199, s[6:7]
	v_pk_fma_f32 v[202:203], v[108:109], v[170:171], v[120:121]
	v_pk_fma_f32 v[104:105], v[104:105], v[112:113], v[202:203]
	v_pk_fma_f32 v[104:105], v[116:117], v[178:179], v[104:105]
	ds_read_b64 v[170:171], v244
	ds_read_b64 v[178:179], v243 offset:32
	ds_read_b64 v[198:199], v238 offset:3104
	s_waitcnt lgkmcnt(12)
	v_pk_fma_f32 v[202:203], v[108:109], v[172:173], v[120:121]
	v_pk_fma_f32 v[96:97], v[96:97], v[112:113], v[202:203]
	v_pk_fma_f32 v[96:97], v[116:117], v[180:181], v[96:97]
	ds_read_b64 v[172:173], v244 offset:512
	ds_read_b64 v[180:181], v243 offset:544
	s_waitcnt lgkmcnt(12)
	v_pk_fma_f32 v[202:203], v[108:109], v[174:175], v[120:121]
	v_pk_fma_f32 v[88:89], v[88:89], v[112:113], v[202:203]
	v_pk_fma_f32 v[88:89], v[116:117], v[194:195], v[88:89]
	ds_read_b64 v[174:175], v244 offset:1024
	ds_read_b64 v[194:195], v243 offset:1056
	s_waitcnt lgkmcnt(11)
; #define PG8_LAS __attribute__((address_space(3)))
; __device__ __forceinline__ unsigned cvt_pk_bf16(float lo, float hi) { unsigned r; asm volatile("v_cvt_pk_bf16_f32 %0, %1, %2" : "=v"(r) : "v"(lo), "v"(hi)); return r; }
;     __device__ __forceinline__ void operator()(const f32x4 (&acc)[2][2][4][2], const Unit& u, int wr, int wc, int fr, int fq) const {
;     ...
;                 for (int m = 0; m < 4; ++m) { const int r = 128 * ai + 64 * wr + 16 * m + fr, t = tstart + r;
;                     const bool upok = t >= 1, dnok = (t + 1) < T, store_ok = (r >= vlo) && (r < vhi) && (t < T);
;                     f32x4 res[2];
; #pragma unroll
;                     for (int bj = 0; bj < 2; ++bj) { const f32x4 cur = acc[ai][bj][m][n];
;                         f32x4 su = cur, sd = cur;
;                         if (m > 0) { if (fr == 15) su = acc[ai][bj][m > 0 ? m - 1 : 0][n]; }
;                         if (m < 3) { if (fr == 0) sd = acc[ai][bj][m < 3 ? m + 1 : 3][n]; }
;                         f32x4 up, dn;
;                         up[0] = dpp_ror1(su[0]); up[1] = dpp_ror1(su[1]); up[2] = dpp_ror1(su[2]); up[3] = dpp_ror1(su[3]);
;                         dn[0] = dpp_ror15(sd[0]); dn[1] = dpp_ror15(sd[1]); dn[2] = dpp_ror15(sd[2]); dn[3] = dpp_ror15(sd[3]);
;                         if (m == 0) { f32x4 halo = zero4; if (blk > 0) halo = *(const PG8_LAS f32x4*)(xb + (((((blk - 1) * 2 + 1) * 4 + wc) * 4 + fq) * 16 + (bj * 2 + n) * 4)); if (fr == 0) up = halo; }
;                         if (m == 3) { f32x4 halo = zero4; if (blk < 3) halo = *(const PG8_LAS f32x4*)(xb + (((((blk + 1) * 2 + 0) * 4 + wc) * 4 + fq) * 16 + (bj * 2 + n) * 4)); if (fr == 15) dn = halo; }
;                         if (edge) { if (!upok) up = zero4; if (!dnok) dn = zero4; }
;                         res[bj] = bb[bj] + w0[bj] * up + w1[bj] * cur + w2[bj] * dn; }
;                     if (store_ok) {
;                         float o[4];
; #pragma unroll
;                         for (int j = 0; j < 4; ++j) { const float gg = res[1][j]; o[j] = gg * __builtin_amdgcn_rcpf(1.f + __expf(-gg)) * res[0][j]; }
;                         u32x2 w; w.x = cvt_pk_bf16(o[0], o[1]); w.y = cvt_pk_bf16(o[2], o[3]);
;                         *(u32x2*)(ACT + (size_t)(seqrow + t) * 2816 + ch0 + 4 * n) = w; } } }
	v_cndmask_b32_e64 v196, v196, v200, s[4:5]
	v_cndmask_b32_e64 v197, v197, v201, s[4:5]
	v_pk_fma_f32 v[202:203], v[108:109], v[176:177], v[120:121]
	v_pk_fma_f32 v[80:81], v[80:81], v[112:113], v[202:203]
	v_pk_fma_f32 v[80:81], v[116:117], v[196:197], v[80:81]
	ds_read_b64 v[176:177], v244 offset:1536
	ds_read_b64 v[196:197], v243 offset:1568
	ds_read_b64 v[200:201], v246 offset:32
	ds_write_b64 v243, v[100:101]
	ds_write_b64 v243, v[92:93] offset:512
	ds_write_b64 v243, v[84:85] offset:1024
	ds_write_b64 v243, v[76:77] offset:1536
	s_waitcnt lgkmcnt(11)
	v_cndmask_b32_e64 v170, v170, v198, s[6:7]
	v_cndmask_b32_e64 v171, v171, v199, s[6:7]
	v_pk_fma_f32 v[202:203], v[122:123], v[170:171], v[134:135]
	v_pk_fma_f32 v[98:99], v[98:99], v[126:127], v[202:203]
	v_pk_fma_f32 v[98:99], v[130:131], v[178:179], v[98:99]
	ds_read_b64 v[170:171], v244
	ds_read_b64 v[178:179], v243 offset:32
	ds_read_b64 v[198:199], v238 offset:3112
	s_waitcnt lgkmcnt(12)
	v_pk_fma_f32 v[202:203], v[122:123], v[172:173], v[134:135]
	v_pk_fma_f32 v[90:91], v[90:91], v[126:127], v[202:203]
	v_pk_fma_f32 v[90:91], v[130:131], v[180:181], v[90:91]
	ds_read_b64 v[172:173], v244 offset:512
	ds_read_b64 v[180:181], v243 offset:544
	s_waitcnt lgkmcnt(12)
	v_pk_fma_f32 v[202:203], v[122:123], v[174:175], v[134:135]
	v_pk_fma_f32 v[82:83], v[82:83], v[126:127], v[202:203]
	v_pk_fma_f32 v[82:83], v[130:131], v[194:195], v[82:83]
	ds_read_b64 v[174:175], v244 offset:1024
	ds_read_b64 v[194:195], v243 offset:1056
	s_waitcnt lgkmcnt(11)
	v_cndmask_b32_e64 v196, v196, v200, s[4:5]
	v_cndmask_b32_e64 v197, v197, v201, s[4:5]
	v_pk_fma_f32 v[202:203], v[122:123], v[176:177], v[134:135]
	v_pk_fma_f32 v[74:75], v[74:75], v[126:127], v[202:203]
	v_pk_fma_f32 v[74:75], v[130:131], v[196:197], v[74:75]
	ds_read_b64 v[176:177], v244 offset:1536
	ds_read_b64 v[196:197], v243 offset:1568
	ds_read_b64 v[200:201], v246 offset:40
	ds_write_b64 v243, v[70:71]
	ds_write_b64 v243, v[62:63] offset:512
	ds_write_b64 v243, v[54:55] offset:1024
	ds_write_b64 v243, v[46:47] offset:1536
	s_waitcnt lgkmcnt(11)
	v_cndmask_b32_e64 v170, v170, v198, s[6:7]
	v_cndmask_b32_e64 v171, v171, v199, s[6:7]
	v_pk_fma_f32 v[202:203], v[124:125], v[170:171], v[136:137]
	v_pk_fma_f32 v[100:101], v[100:101], v[128:129], v[202:203]
	v_pk_fma_f32 v[100:101], v[132:133], v[178:179], v[100:101]
	ds_read_b64 v[170:171], v244
	ds_read_b64 v[178:179], v243 offset:32
	ds_read_b64 v[198:199], v245 offset:16
	s_waitcnt lgkmcnt(12)
	v_pk_fma_f32 v[202:203], v[124:125], v[172:173], v[136:137]
	v_pk_fma_f32 v[92:93], v[92:93], v[128:129], v[202:203]
	v_pk_fma_f32 v[92:93], v[132:133], v[180:181], v[92:93]
	ds_read_b64 v[172:173], v244 offset:512
	ds_read_b64 v[180:181], v243 offset:544
	s_waitcnt lgkmcnt(12)
	v_pk_fma_f32 v[202:203], v[124:125], v[174:175], v[136:137]
	v_pk_fma_f32 v[84:85], v[84:85], v[128:129], v[202:203]
	v_pk_fma_f32 v[84:85], v[132:133], v[194:195], v[84:85]
	ds_read_b64 v[174:175], v244 offset:1024
	ds_read_b64 v[194:195], v243 offset:1056
	s_waitcnt lgkmcnt(11)
	v_cndmask_b32_e64 v196, v196, v200, s[4:5]
	v_cndmask_b32_e64 v197, v197, v201, s[4:5]
	v_pk_fma_f32 v[202:203], v[124:125], v[176:177], v[136:137]
	v_pk_fma_f32 v[76:77], v[76:77], v[128:129], v[202:203]
	v_pk_fma_f32 v[76:77], v[132:133], v[196:197], v[76:77]
	ds_read_b64 v[176:177], v244 offset:1536
	ds_read_b64 v[196:197], v243 offset:1568
	ds_read_b64 v[200:201], v238 offset:2064
	v_mul_f32_e32 v208, 0xbfb8aa3b, v98
	v_mul_f32_e32 v209, 0xbfb8aa3b, v99
	v_mul_f32_e32 v210, 0xbfb8aa3b, v100
	v_mul_f32_e32 v211, 0xbfb8aa3b, v101
	v_exp_f32_e32 v208, v208
	v_exp_f32_e32 v209, v209
	v_exp_f32_e32 v210, v210
	v_exp_f32_e32 v211, v211
	v_add_f32_e32 v208, 1.0, v208
	v_add_f32_e32 v209, 1.0, v209
	v_add_f32_e32 v210, 1.0, v210
	v_add_f32_e32 v211, 1.0, v211
	v_rcp_f32_e32 v208, v208
	v_rcp_f32_e32 v209, v209
	v_rcp_f32_e32 v210, v210
	v_rcp_f32_e32 v211, v211
	v_mul_f32_e32 v98, v98, v208
	v_mul_f32_e32 v99, v99, v209
	v_mul_f32_e32 v100, v100, v210
	v_mul_f32_e32 v101, v101, v211
	v_mul_f32_e32 v98, v102, v98
	v_mul_f32_e32 v99, v103, v99
	v_mul_f32_e32 v100, v104, v100
	v_mul_f32_e32 v101, v105, v101
	v_cvt_pk_bf16_f32 v212, v98, v99
	v_cvt_pk_bf16_f32 v213, v100, v101
	v_mad_u32_u24 v221, v234, s29, v247
	s_and_saveexec_b64 s[30:31], s[20:21]
	global_store_dwordx2 v221, v[212:213], s[10:11]
	s_mov_b64 exec, s[30:31]
	v_mul_f32_e32 v208, 0xbfb8aa3b, v90
	v_mul_f32_e32 v209, 0xbfb8aa3b, v91
	v_mul_f32_e32 v210, 0xbfb8aa3b, v92
	v_mul_f32_e32 v211, 0xbfb8aa3b, v93
	v_exp_f32_e32 v208, v208
	v_exp_f32_e32 v209, v209
	v_exp_f32_e32 v210, v210
	v_exp_f32_e32 v211, v211
	v_add_f32_e32 v208, 1.0, v208
	v_add_f32_e32 v209, 1.0, v209
	v_add_f32_e32 v210, 1.0, v210
	v_add_f32_e32 v211, 1.0, v211
	v_rcp_f32_e32 v208, v208
	v_rcp_f32_e32 v209, v209
	v_rcp_f32_e32 v210, v210
	v_rcp_f32_e32 v211, v211
	v_mul_f32_e32 v90, v90, v208
	v_mul_f32_e32 v91, v91, v209
	v_mul_f32_e32 v92, v92, v210
	v_mul_f32_e32 v93, v93, v211
	v_mul_f32_e32 v90, v94, v90
	v_mul_f32_e32 v91, v95, v91
	v_mul_f32_e32 v92, v96, v92
	v_mul_f32_e32 v93, v97, v93
	v_cvt_pk_bf16_f32 v218, v90, v91
	v_cvt_pk_bf16_f32 v219, v92, v93
	v_mad_u32_u24 v40, v235, s29, v247
	s_and_saveexec_b64 s[30:31], s[22:23]
	global_store_dwordx2 v40, v[218:219], s[10:11]
	s_mov_b64 exec, s[30:31]
	v_mul_f32_e32 v208, 0xbfb8aa3b, v82
	v_mul_f32_e32 v209, 0xbfb8aa3b, v83
	v_mul_f32_e32 v210, 0xbfb8aa3b, v84
	v_mul_f32_e32 v211, 0xbfb8aa3b, v85
	v_exp_f32_e32 v208, v208
	v_exp_f32_e32 v209, v209
	v_exp_f32_e32 v210, v210
	v_exp_f32_e32 v211, v211
	v_add_f32_e32 v208, 1.0, v208
	v_add_f32_e32 v209, 1.0, v209
; #define PG8_LAS __attribute__((address_space(3)))
; __device__ __forceinline__ unsigned cvt_pk_bf16(float lo, float hi) { unsigned r; asm volatile("v_cvt_pk_bf16_f32 %0, %1, %2" : "=v"(r) : "v"(lo), "v"(hi)); return r; }
;     __device__ __forceinline__ void operator()(const f32x4 (&acc)[2][2][4][2], const Unit& u, int wr, int wc, int fr, int fq) const {
;     ...
;                 for (int m = 0; m < 4; ++m) { const int r = 128 * ai + 64 * wr + 16 * m + fr, t = tstart + r;
;                     const bool upok = t >= 1, dnok = (t + 1) < T, store_ok = (r >= vlo) && (r < vhi) && (t < T);
;                     f32x4 res[2];
; #pragma unroll
;                     for (int bj = 0; bj < 2; ++bj) { const f32x4 cur = acc[ai][bj][m][n];
;                         f32x4 su = cur, sd = cur;
;                         if (m > 0) { if (fr == 15) su = acc[ai][bj][m > 0 ? m - 1 : 0][n]; }
;                         if (m < 3) { if (fr == 0) sd = acc[ai][bj][m < 3 ? m + 1 : 3][n]; }
;                         f32x4 up, dn;
;                         up[0] = dpp_ror1(su[0]); up[1] = dpp_ror1(su[1]); up[2] = dpp_ror1(su[2]); up[3] = dpp_ror1(su[3]);
;                         dn[0] = dpp_ror15(sd[0]); dn[1] = dpp_ror15(sd[1]); dn[2] = dpp_ror15(sd[2]); dn[3] = dpp_ror15(sd[3]);
;                         if (m == 0) { f32x4 halo = zero4; if (blk > 0) halo = *(const PG8_LAS f32x4*)(xb + (((((blk - 1) * 2 + 1) * 4 + wc) * 4 + fq) * 16 + (bj * 2 + n) * 4)); if (fr == 0) up = halo; }
;                         if (m == 3) { f32x4 halo = zero4; if (blk < 3) halo = *(const PG8_LAS f32x4*)(xb + (((((blk + 1) * 2 + 0) * 4 + wc) * 4 + fq) * 16 + (bj * 2 + n) * 4)); if (fr == 15) dn = halo; }
;                         if (edge) { if (!upok) up = zero4; if (!dnok) dn = zero4; }
;                         res[bj] = bb[bj] + w0[bj] * up + w1[bj] * cur + w2[bj] * dn; }
;                     if (store_ok) {
;                         float o[4];
; #pragma unroll
;                         for (int j = 0; j < 4; ++j) { const float gg = res[1][j]; o[j] = gg * __builtin_amdgcn_rcpf(1.f + __expf(-gg)) * res[0][j]; }
;                         u32x2 w; w.x = cvt_pk_bf16(o[0], o[1]); w.y = cvt_pk_bf16(o[2], o[3]);
;                         *(u32x2*)(ACT + (size_t)(seqrow + t) * 2816 + ch0 + 4 * n) = w; } } }
	v_add_f32_e32 v210, 1.0, v210
	v_add_f32_e32 v211, 1.0, v211
	v_rcp_f32_e32 v208, v208
	v_rcp_f32_e32 v209, v209
	v_rcp_f32_e32 v210, v210
	v_rcp_f32_e32 v211, v211
	v_mul_f32_e32 v82, v82, v208
	v_mul_f32_e32 v83, v83, v209
	v_mul_f32_e32 v84, v84, v210
	v_mul_f32_e32 v85, v85, v211
	v_mul_f32_e32 v82, v86, v82
	v_mul_f32_e32 v83, v87, v83
	v_mul_f32_e32 v84, v88, v84
	v_mul_f32_e32 v85, v89, v85
	v_cvt_pk_bf16_f32 v212, v82, v83
	v_cvt_pk_bf16_f32 v213, v84, v85
	v_mad_u32_u24 v221, v236, s29, v247
	s_and_saveexec_b64 s[30:31], s[24:25]
	global_store_dwordx2 v221, v[212:213], s[10:11]
	s_mov_b64 exec, s[30:31]
	v_mul_f32_e32 v208, 0xbfb8aa3b, v74
	v_mul_f32_e32 v209, 0xbfb8aa3b, v75
	v_mul_f32_e32 v210, 0xbfb8aa3b, v76
	v_mul_f32_e32 v211, 0xbfb8aa3b, v77
	v_exp_f32_e32 v208, v208
	v_exp_f32_e32 v209, v209
	v_exp_f32_e32 v210, v210
	v_exp_f32_e32 v211, v211
	v_add_f32_e32 v208, 1.0, v208
	v_add_f32_e32 v209, 1.0, v209
	v_add_f32_e32 v210, 1.0, v210
	v_add_f32_e32 v211, 1.0, v211
	v_rcp_f32_e32 v208, v208
	v_rcp_f32_e32 v209, v209
	v_rcp_f32_e32 v210, v210
	v_rcp_f32_e32 v211, v211
	v_mul_f32_e32 v74, v74, v208
	v_mul_f32_e32 v75, v75, v209
	v_mul_f32_e32 v76, v76, v210
	v_mul_f32_e32 v77, v77, v211
	v_mul_f32_e32 v74, v78, v74
	v_mul_f32_e32 v75, v79, v75
	v_mul_f32_e32 v76, v80, v76
	v_mul_f32_e32 v77, v81, v77
	v_cvt_pk_bf16_f32 v218, v74, v75
	v_cvt_pk_bf16_f32 v219, v76, v77
	v_mad_u32_u24 v40, v237, s29, v247
	s_and_saveexec_b64 s[30:31], s[26:27]
	global_store_dwordx2 v40, v[218:219], s[10:11]
	s_mov_b64 exec, s[30:31]
	s_waitcnt vmcnt(4)
	ds_write_b64 v243, v[72:73]
	ds_write_b64 v243, v[64:65] offset:512
	ds_write_b64 v243, v[56:57] offset:1024
	ds_write_b64 v243, v[48:49] offset:1536
	s_waitcnt lgkmcnt(11)
	v_cndmask_b32_e64 v170, v170, v198, s[6:7]
	v_cndmask_b32_e64 v171, v171, v199, s[6:7]
	v_pk_fma_f32 v[202:203], v[138:139], v[170:171], v[150:151]
	v_pk_fma_f32 v[70:71], v[70:71], v[142:143], v[202:203]
	v_pk_fma_f32 v[70:71], v[146:147], v[178:179], v[70:71]
	ds_read_b64 v[170:171], v244
	ds_read_b64 v[178:179], v243 offset:32
	ds_read_b64 v[198:199], v245 offset:24
	s_waitcnt lgkmcnt(12)
	v_pk_fma_f32 v[202:203], v[138:139], v[172:173], v[150:151]
	v_pk_fma_f32 v[62:63], v[62:63], v[142:143], v[202:203]
	v_pk_fma_f32 v[62:63], v[146:147], v[180:181], v[62:63]
	ds_read_b64 v[172:173], v244 offset:512
	ds_read_b64 v[180:181], v243 offset:544
	s_waitcnt lgkmcnt(12)
	v_pk_fma_f32 v[202:203], v[138:139], v[174:175], v[150:151]
	v_pk_fma_f32 v[54:55], v[54:55], v[142:143], v[202:203]
	v_pk_fma_f32 v[54:55], v[146:147], v[194:195], v[54:55]
	ds_read_b64 v[174:175], v244 offset:1024
	ds_read_b64 v[194:195], v243 offset:1056
	s_waitcnt lgkmcnt(11)
	v_cndmask_b32_e64 v196, v196, v200, s[4:5]
	v_cndmask_b32_e64 v197, v197, v201, s[4:5]
	v_pk_fma_f32 v[202:203], v[138:139], v[176:177], v[150:151]
	v_pk_fma_f32 v[46:47], v[46:47], v[142:143], v[202:203]
	v_pk_fma_f32 v[46:47], v[146:147], v[196:197], v[46:47]
	ds_read_b64 v[176:177], v244 offset:1536
	ds_read_b64 v[196:197], v243 offset:1568
	ds_read_b64 v[200:201], v238 offset:2072
	ds_write_b64 v243, v[66:67]
	ds_write_b64 v243, v[58:59] offset:512
	ds_write_b64 v243, v[50:51] offset:1024
	ds_write_b64 v243, v[42:43] offset:1536
	s_waitcnt lgkmcnt(11)
	v_cndmask_b32_e64 v170, v170, v198, s[6:7]
	v_cndmask_b32_e64 v171, v171, v199, s[6:7]
	v_pk_fma_f32 v[202:203], v[140:141], v[170:171], v[152:153]
	v_pk_fma_f32 v[72:73], v[72:73], v[144:145], v[202:203]
	v_pk_fma_f32 v[72:73], v[148:149], v[178:179], v[72:73]
	ds_read_b64 v[170:171], v244
	ds_read_b64 v[178:179], v243 offset:32
	ds_read_b64 v[198:199], v245 offset:48
	s_waitcnt lgkmcnt(12)
	v_pk_fma_f32 v[202:203], v[140:141], v[172:173], v[152:153]
	v_pk_fma_f32 v[64:65], v[64:65], v[144:145], v[202:203]
	v_pk_fma_f32 v[64:65], v[148:149], v[180:181], v[64:65]
	ds_read_b64 v[172:173], v244 offset:512
	ds_read_b64 v[180:181], v243 offset:544
	s_waitcnt lgkmcnt(12)
	v_pk_fma_f32 v[202:203], v[140:141], v[174:175], v[152:153]
	v_pk_fma_f32 v[56:57], v[56:57], v[144:145], v[202:203]
	v_pk_fma_f32 v[56:57], v[148:149], v[194:195], v[56:57]
	ds_read_b64 v[174:175], v244 offset:1024
	ds_read_b64 v[194:195], v243 offset:1056
	s_waitcnt lgkmcnt(11)
	v_cndmask_b32_e64 v196, v196, v200, s[4:5]
	v_cndmask_b32_e64 v197, v197, v201, s[4:5]
	v_pk_fma_f32 v[202:203], v[140:141], v[176:177], v[152:153]
	v_pk_fma_f32 v[48:49], v[48:49], v[144:145], v[202:203]
	v_pk_fma_f32 v[48:49], v[148:149], v[196:197], v[48:49]
	ds_read_b64 v[176:177], v244 offset:1536
	ds_read_b64 v[196:197], v243 offset:1568
	ds_read_b64 v[200:201], v238 offset:2096
	ds_write_b64 v243, v[68:69]
	ds_write_b64 v243, v[60:61] offset:512
	ds_write_b64 v243, v[52:53] offset:1024
	ds_write_b64 v243, v[44:45] offset:1536
	s_waitcnt lgkmcnt(11)
	v_cndmask_b32_e64 v170, v170, v198, s[6:7]
	v_cndmask_b32_e64 v171, v171, v199, s[6:7]
	v_pk_fma_f32 v[202:203], v[154:155], v[170:171], v[166:167]
	v_pk_fma_f32 v[66:67], v[66:67], v[158:159], v[202:203]
	v_pk_fma_f32 v[66:67], v[162:163], v[178:179], v[66:67]
	ds_read_b64 v[170:171], v244
	ds_read_b64 v[178:179], v243 offset:32
	ds_read_b64 v[198:199], v245 offset:56
	s_waitcnt lgkmcnt(12)
	v_pk_fma_f32 v[202:203], v[154:155], v[172:173], v[166:167]
	v_pk_fma_f32 v[58:59], v[58:59], v[158:159], v[202:203]
	v_pk_fma_f32 v[58:59], v[162:163], v[180:181], v[58:59]
	ds_read_b64 v[172:173], v244 offset:512
	ds_read_b64 v[180:181], v243 offset:544
	s_waitcnt lgkmcnt(12)
	v_pk_fma_f32 v[202:203], v[154:155], v[174:175], v[166:167]
	v_pk_fma_f32 v[50:51], v[50:51], v[158:159], v[202:203]
	v_pk_fma_f32 v[50:51], v[162:163], v[194:195], v[50:51]
	ds_read_b64 v[174:175], v244 offset:1024
	ds_read_b64 v[194:195], v243 offset:1056
	s_waitcnt lgkmcnt(11)
; #define PG8_LAS __attribute__((address_space(3)))
; __device__ __forceinline__ unsigned cvt_pk_bf16(float lo, float hi) { unsigned r; asm volatile("v_cvt_pk_bf16_f32 %0, %1, %2" : "=v"(r) : "v"(lo), "v"(hi)); return r; }
;     __device__ __forceinline__ void operator()(const f32x4 (&acc)[2][2][4][2], const Unit& u, int wr, int wc, int fr, int fq) const {
;     ...
;                 for (int m = 0; m < 4; ++m) { const int r = 128 * ai + 64 * wr + 16 * m + fr, t = tstart + r;
;                     const bool upok = t >= 1, dnok = (t + 1) < T, store_ok = (r >= vlo) && (r < vhi) && (t < T);
;                     f32x4 res[2];
; #pragma unroll
;                     for (int bj = 0; bj < 2; ++bj) { const f32x4 cur = acc[ai][bj][m][n];
;                         f32x4 su = cur, sd = cur;
;                         if (m > 0) { if (fr == 15) su = acc[ai][bj][m > 0 ? m - 1 : 0][n]; }
;                         if (m < 3) { if (fr == 0) sd = acc[ai][bj][m < 3 ? m + 1 : 3][n]; }
;                         f32x4 up, dn;
;                         up[0] = dpp_ror1(su[0]); up[1] = dpp_ror1(su[1]); up[2] = dpp_ror1(su[2]); up[3] = dpp_ror1(su[3]);
;                         dn[0] = dpp_ror15(sd[0]); dn[1] = dpp_ror15(sd[1]); dn[2] = dpp_ror15(sd[2]); dn[3] = dpp_ror15(sd[3]);
;                         if (m == 0) { f32x4 halo = zero4; if (blk > 0) halo = *(const PG8_LAS f32x4*)(xb + (((((blk - 1) * 2 + 1) * 4 + wc) * 4 + fq) * 16 + (bj * 2 + n) * 4)); if (fr == 0) up = halo; }
;                         if (m == 3) { f32x4 halo = zero4; if (blk < 3) halo = *(const PG8_LAS f32x4*)(xb + (((((blk + 1) * 2 + 0) * 4 + wc) * 4 + fq) * 16 + (bj * 2 + n) * 4)); if (fr == 15) dn = halo; }
;                         if (edge) { if (!upok) up = zero4; if (!dnok) dn = zero4; }
;                         res[bj] = bb[bj] + w0[bj] * up + w1[bj] * cur + w2[bj] * dn; }
;                     if (store_ok) {
;                         float o[4];
; #pragma unroll
;                         for (int j = 0; j < 4; ++j) { const float gg = res[1][j]; o[j] = gg * __builtin_amdgcn_rcpf(1.f + __expf(-gg)) * res[0][j]; }
;                         u32x2 w; w.x = cvt_pk_bf16(o[0], o[1]); w.y = cvt_pk_bf16(o[2], o[3]);
;                         *(u32x2*)(ACT + (size_t)(seqrow + t) * 2816 + ch0 + 4 * n) = w; } } }
	v_cndmask_b32_e64 v196, v196, v200, s[4:5]
	v_cndmask_b32_e64 v197, v197, v201, s[4:5]
	v_pk_fma_f32 v[202:203], v[154:155], v[176:177], v[166:167]
	v_pk_fma_f32 v[42:43], v[42:43], v[158:159], v[202:203]
	v_pk_fma_f32 v[42:43], v[162:163], v[196:197], v[42:43]
	ds_read_b64 v[176:177], v244 offset:1536
	ds_read_b64 v[196:197], v243 offset:1568
	ds_read_b64 v[200:201], v238 offset:2104
	ds_write_b64 v243, v[30:31]
	ds_write_b64 v243, v[22:23] offset:512
	ds_write_b64 v243, v[14:15] offset:1024
	ds_write_b64 v243, v[6:7] offset:1536
	s_waitcnt lgkmcnt(11)
	v_cndmask_b32_e64 v170, v170, v198, s[6:7]
	v_cndmask_b32_e64 v171, v171, v199, s[6:7]
	v_pk_fma_f32 v[202:203], v[156:157], v[170:171], v[168:169]
	v_pk_fma_f32 v[68:69], v[68:69], v[160:161], v[202:203]
	v_pk_fma_f32 v[68:69], v[164:165], v[178:179], v[68:69]
	ds_read_b64 v[170:171], v244
	ds_read_b64 v[178:179], v243 offset:32
	ds_read_b64 v[198:199], v238 offset:3088
	s_waitcnt lgkmcnt(12)
	v_pk_fma_f32 v[202:203], v[156:157], v[172:173], v[168:169]
	v_pk_fma_f32 v[60:61], v[60:61], v[160:161], v[202:203]
	v_pk_fma_f32 v[60:61], v[164:165], v[180:181], v[60:61]
	ds_read_b64 v[172:173], v244 offset:512
	ds_read_b64 v[180:181], v243 offset:544
	s_waitcnt lgkmcnt(12)
	v_pk_fma_f32 v[202:203], v[156:157], v[174:175], v[168:169]
	v_pk_fma_f32 v[52:53], v[52:53], v[160:161], v[202:203]
	v_pk_fma_f32 v[52:53], v[164:165], v[194:195], v[52:53]
	ds_read_b64 v[174:175], v244 offset:1024
	ds_read_b64 v[194:195], v243 offset:1056
	s_waitcnt lgkmcnt(11)
	v_cndmask_b32_e64 v196, v196, v200, s[4:5]
	v_cndmask_b32_e64 v197, v197, v201, s[4:5]
	v_pk_fma_f32 v[202:203], v[156:157], v[176:177], v[168:169]
	v_pk_fma_f32 v[44:45], v[44:45], v[160:161], v[202:203]
	v_pk_fma_f32 v[44:45], v[164:165], v[196:197], v[44:45]
	ds_read_b64 v[176:177], v244 offset:1536
	ds_read_b64 v[196:197], v243 offset:1568
	ds_read_b64 v[200:201], v246 offset:16
	v_mul_f32_e32 v208, 0xbfb8aa3b, v66
	v_mul_f32_e32 v209, 0xbfb8aa3b, v67
	v_mul_f32_e32 v210, 0xbfb8aa3b, v68
	v_mul_f32_e32 v211, 0xbfb8aa3b, v69
	v_exp_f32_e32 v208, v208
	v_exp_f32_e32 v209, v209
	v_exp_f32_e32 v210, v210
	v_exp_f32_e32 v211, v211
	v_add_f32_e32 v208, 1.0, v208
	v_add_f32_e32 v209, 1.0, v209
	v_add_f32_e32 v210, 1.0, v210
	v_add_f32_e32 v211, 1.0, v211
	v_rcp_f32_e32 v208, v208
	v_rcp_f32_e32 v209, v209
	v_rcp_f32_e32 v210, v210
	v_rcp_f32_e32 v211, v211
	v_mul_f32_e32 v66, v66, v208
	v_mul_f32_e32 v67, v67, v209
	v_mul_f32_e32 v68, v68, v210
	v_mul_f32_e32 v69, v69, v211
	v_mul_f32_e32 v66, v70, v66
	v_mul_f32_e32 v67, v71, v67
	v_mul_f32_e32 v68, v72, v68
	v_mul_f32_e32 v69, v73, v69
	v_cvt_pk_bf16_f32 v212, v66, v67
	v_cvt_pk_bf16_f32 v213, v68, v69
	v_mad_u32_u24 v221, v227, s29, v247
	s_and_saveexec_b64 s[30:31], s[12:13]
	global_store_dwordx2 v221, v[212:213], s[10:11] offset:8
	s_mov_b64 exec, s[30:31]
	v_mul_f32_e32 v208, 0xbfb8aa3b, v58
	v_mul_f32_e32 v209, 0xbfb8aa3b, v59
	v_mul_f32_e32 v210, 0xbfb8aa3b, v60
	v_mul_f32_e32 v211, 0xbfb8aa3b, v61
	v_exp_f32_e32 v208, v208
	v_exp_f32_e32 v209, v209
	v_exp_f32_e32 v210, v210
	v_exp_f32_e32 v211, v211
	v_add_f32_e32 v208, 1.0, v208
	v_add_f32_e32 v209, 1.0, v209
	v_add_f32_e32 v210, 1.0, v210
	v_add_f32_e32 v211, 1.0, v211
	v_rcp_f32_e32 v208, v208
	v_rcp_f32_e32 v209, v209
	v_rcp_f32_e32 v210, v210
	v_rcp_f32_e32 v211, v211
	v_mul_f32_e32 v58, v58, v208
	v_mul_f32_e32 v59, v59, v209
	v_mul_f32_e32 v60, v60, v210
	v_mul_f32_e32 v61, v61, v211
	v_mul_f32_e32 v58, v62, v58
	v_mul_f32_e32 v59, v63, v59
	v_mul_f32_e32 v60, v64, v60
	v_mul_f32_e32 v61, v65, v61
	v_cvt_pk_bf16_f32 v218, v58, v59
	v_cvt_pk_bf16_f32 v219, v60, v61
	v_mad_u32_u24 v40, v231, s29, v247
	s_and_saveexec_b64 s[30:31], s[14:15]
	global_store_dwordx2 v40, v[218:219], s[10:11] offset:8
	s_mov_b64 exec, s[30:31]
	v_mul_f32_e32 v208, 0xbfb8aa3b, v50
	v_mul_f32_e32 v209, 0xbfb8aa3b, v51
	v_mul_f32_e32 v210, 0xbfb8aa3b, v52
	v_mul_f32_e32 v211, 0xbfb8aa3b, v53
	v_exp_f32_e32 v208, v208
	v_exp_f32_e32 v209, v209
	v_exp_f32_e32 v210, v210
	v_exp_f32_e32 v211, v211
	v_add_f32_e32 v208, 1.0, v208
	v_add_f32_e32 v209, 1.0, v209
	v_add_f32_e32 v210, 1.0, v210
	v_add_f32_e32 v211, 1.0, v211
	v_rcp_f32_e32 v208, v208
	v_rcp_f32_e32 v209, v209
	v_rcp_f32_e32 v210, v210
	v_rcp_f32_e32 v211, v211
	v_mul_f32_e32 v50, v50, v208
	v_mul_f32_e32 v51, v51, v209
	v_mul_f32_e32 v52, v52, v210
	v_mul_f32_e32 v53, v53, v211
	v_mul_f32_e32 v50, v54, v50
	v_mul_f32_e32 v51, v55, v51
	v_mul_f32_e32 v52, v56, v52
	v_mul_f32_e32 v53, v57, v53
	v_cvt_pk_bf16_f32 v212, v50, v51
	v_cvt_pk_bf16_f32 v213, v52, v53
	v_mad_u32_u24 v221, v232, s29, v247
	s_and_saveexec_b64 s[30:31], s[16:17]
	global_store_dwordx2 v221, v[212:213], s[10:11] offset:8
	s_mov_b64 exec, s[30:31]
	v_mul_f32_e32 v208, 0xbfb8aa3b, v42
	v_mul_f32_e32 v209, 0xbfb8aa3b, v43
	v_mul_f32_e32 v210, 0xbfb8aa3b, v44
	v_mul_f32_e32 v211, 0xbfb8aa3b, v45
	v_exp_f32_e32 v208, v208
	v_exp_f32_e32 v209, v209
	v_exp_f32_e32 v210, v210
	v_exp_f32_e32 v211, v211
	v_add_f32_e32 v208, 1.0, v208
	v_add_f32_e32 v209, 1.0, v209
	v_add_f32_e32 v210, 1.0, v210
	v_add_f32_e32 v211, 1.0, v211
	v_rcp_f32_e32 v208, v208
	v_rcp_f32_e32 v209, v209
	v_rcp_f32_e32 v210, v210
	v_rcp_f32_e32 v211, v211
	v_mul_f32_e32 v42, v42, v208
	v_mul_f32_e32 v43, v43, v209
	v_mul_f32_e32 v44, v44, v210
	v_mul_f32_e32 v45, v45, v211
	v_mul_f32_e32 v42, v46, v42
	v_mul_f32_e32 v43, v47, v43
	v_mul_f32_e32 v44, v48, v44
	v_mul_f32_e32 v45, v49, v45
	v_cvt_pk_bf16_f32 v218, v42, v43
	v_cvt_pk_bf16_f32 v219, v44, v45
	v_mad_u32_u24 v40, v233, s29, v247
	s_and_saveexec_b64 s[30:31], s[18:19]
	global_store_dwordx2 v40, v[218:219], s[10:11] offset:8
	s_mov_b64 exec, s[30:31]
	ds_write_b64 v243, v[32:33]
	ds_write_b64 v243, v[24:25] offset:512
	ds_write_b64 v243, v[16:17] offset:1024
	ds_write_b64 v243, v[8:9] offset:1536
	s_waitcnt lgkmcnt(11)
; #define PG8_LAS __attribute__((address_space(3)))
; __device__ __forceinline__ unsigned cvt_pk_bf16(float lo, float hi) { unsigned r; asm volatile("v_cvt_pk_bf16_f32 %0, %1, %2" : "=v"(r) : "v"(lo), "v"(hi)); return r; }
;     __device__ __forceinline__ void operator()(const f32x4 (&acc)[2][2][4][2], const Unit& u, int wr, int wc, int fr, int fq) const {
;     ...
;                 for (int m = 0; m < 4; ++m) { const int r = 128 * ai + 64 * wr + 16 * m + fr, t = tstart + r;
;                     const bool upok = t >= 1, dnok = (t + 1) < T, store_ok = (r >= vlo) && (r < vhi) && (t < T);
;                     f32x4 res[2];
; #pragma unroll
;                     for (int bj = 0; bj < 2; ++bj) { const f32x4 cur = acc[ai][bj][m][n];
;                         f32x4 su = cur, sd = cur;
;                         if (m > 0) { if (fr == 15) su = acc[ai][bj][m > 0 ? m - 1 : 0][n]; }
;                         if (m < 3) { if (fr == 0) sd = acc[ai][bj][m < 3 ? m + 1 : 3][n]; }
;                         f32x4 up, dn;
;                         up[0] = dpp_ror1(su[0]); up[1] = dpp_ror1(su[1]); up[2] = dpp_ror1(su[2]); up[3] = dpp_ror1(su[3]);
;                         dn[0] = dpp_ror15(sd[0]); dn[1] = dpp_ror15(sd[1]); dn[2] = dpp_ror15(sd[2]); dn[3] = dpp_ror15(sd[3]);
;                         if (m == 0) { f32x4 halo = zero4; if (blk > 0) halo = *(const PG8_LAS f32x4*)(xb + (((((blk - 1) * 2 + 1) * 4 + wc) * 4 + fq) * 16 + (bj * 2 + n) * 4)); if (fr == 0) up = halo; }
;                         if (m == 3) { f32x4 halo = zero4; if (blk < 3) halo = *(const PG8_LAS f32x4*)(xb + (((((blk + 1) * 2 + 0) * 4 + wc) * 4 + fq) * 16 + (bj * 2 + n) * 4)); if (fr == 15) dn = halo; }
;                         if (edge) { if (!upok) up = zero4; if (!dnok) dn = zero4; }
;                         res[bj] = bb[bj] + w0[bj] * up + w1[bj] * cur + w2[bj] * dn; }
;                     if (store_ok) {
;                         float o[4];
; #pragma unroll
;                         for (int j = 0; j < 4; ++j) { const float gg = res[1][j]; o[j] = gg * __builtin_amdgcn_rcpf(1.f + __expf(-gg)) * res[0][j]; }
;                         u32x2 w; w.x = cvt_pk_bf16(o[0], o[1]); w.y = cvt_pk_bf16(o[2], o[3]);
;                         *(u32x2*)(ACT + (size_t)(seqrow + t) * 2816 + ch0 + 4 * n) = w; } } }
	v_cndmask_b32_e64 v170, v170, v198, s[6:7]
	v_cndmask_b32_e64 v171, v171, v199, s[6:7]
	v_pk_fma_f32 v[202:203], v[138:139], v[170:171], v[150:151]
	v_pk_fma_f32 v[30:31], v[30:31], v[142:143], v[202:203]
	v_pk_fma_f32 v[30:31], v[146:147], v[178:179], v[30:31]
	ds_read_b64 v[170:171], v244
	ds_read_b64 v[178:179], v243 offset:32
	ds_read_b64 v[198:199], v238 offset:3096
	s_waitcnt lgkmcnt(12)
	v_pk_fma_f32 v[202:203], v[138:139], v[172:173], v[150:151]
	v_pk_fma_f32 v[22:23], v[22:23], v[142:143], v[202:203]
	v_pk_fma_f32 v[22:23], v[146:147], v[180:181], v[22:23]
	ds_read_b64 v[172:173], v244 offset:512
	ds_read_b64 v[180:181], v243 offset:544
	s_waitcnt lgkmcnt(12)
	v_pk_fma_f32 v[202:203], v[138:139], v[174:175], v[150:151]
	v_pk_fma_f32 v[14:15], v[14:15], v[142:143], v[202:203]
	v_pk_fma_f32 v[14:15], v[146:147], v[194:195], v[14:15]
	ds_read_b64 v[174:175], v244 offset:1024
	ds_read_b64 v[194:195], v243 offset:1056
	s_waitcnt lgkmcnt(11)
	v_cndmask_b32_e64 v196, v196, v200, s[4:5]
	v_cndmask_b32_e64 v197, v197, v201, s[4:5]
	v_pk_fma_f32 v[202:203], v[138:139], v[176:177], v[150:151]
	v_pk_fma_f32 v[6:7], v[6:7], v[142:143], v[202:203]
	v_pk_fma_f32 v[6:7], v[146:147], v[196:197], v[6:7]
	ds_read_b64 v[176:177], v244 offset:1536
	ds_read_b64 v[196:197], v243 offset:1568
	ds_read_b64 v[200:201], v246 offset:24
	ds_write_b64 v243, v[26:27]
	ds_write_b64 v243, v[18:19] offset:512
	ds_write_b64 v243, v[10:11] offset:1024
	ds_write_b64 v243, v[2:3] offset:1536
	s_waitcnt lgkmcnt(11)
	v_cndmask_b32_e64 v170, v170, v198, s[6:7]
	v_cndmask_b32_e64 v171, v171, v199, s[6:7]
	v_pk_fma_f32 v[202:203], v[140:141], v[170:171], v[152:153]
	v_pk_fma_f32 v[32:33], v[32:33], v[144:145], v[202:203]
	v_pk_fma_f32 v[32:33], v[148:149], v[178:179], v[32:33]
	ds_read_b64 v[170:171], v244
	ds_read_b64 v[178:179], v243 offset:32
	ds_read_b64 v[198:199], v238 offset:3120
	s_waitcnt lgkmcnt(12)
	v_pk_fma_f32 v[202:203], v[140:141], v[172:173], v[152:153]
	v_pk_fma_f32 v[24:25], v[24:25], v[144:145], v[202:203]
	v_pk_fma_f32 v[24:25], v[148:149], v[180:181], v[24:25]
	ds_read_b64 v[172:173], v244 offset:512
	ds_read_b64 v[180:181], v243 offset:544
	s_waitcnt lgkmcnt(12)
	v_pk_fma_f32 v[202:203], v[140:141], v[174:175], v[152:153]
	v_pk_fma_f32 v[16:17], v[16:17], v[144:145], v[202:203]
	v_pk_fma_f32 v[16:17], v[148:149], v[194:195], v[16:17]
	ds_read_b64 v[174:175], v244 offset:1024
	ds_read_b64 v[194:195], v243 offset:1056
	s_waitcnt lgkmcnt(11)
	v_cndmask_b32_e64 v196, v196, v200, s[4:5]
	v_cndmask_b32_e64 v197, v197, v201, s[4:5]
	v_pk_fma_f32 v[202:203], v[140:141], v[176:177], v[152:153]
	v_pk_fma_f32 v[8:9], v[8:9], v[144:145], v[202:203]
	v_pk_fma_f32 v[8:9], v[148:149], v[196:197], v[8:9]
	ds_read_b64 v[176:177], v244 offset:1536
	ds_read_b64 v[196:197], v243 offset:1568
	ds_read_b64 v[200:201], v246 offset:48
	ds_write_b64 v243, v[28:29]
	ds_write_b64 v243, v[20:21] offset:512
	ds_write_b64 v243, v[12:13] offset:1024
	ds_write_b64 v243, v[4:5] offset:1536
	s_waitcnt lgkmcnt(11)
	v_cndmask_b32_e64 v170, v170, v198, s[6:7]
	v_cndmask_b32_e64 v171, v171, v199, s[6:7]
	v_pk_fma_f32 v[202:203], v[154:155], v[170:171], v[166:167]
	v_pk_fma_f32 v[26:27], v[26:27], v[158:159], v[202:203]
	v_pk_fma_f32 v[26:27], v[162:163], v[178:179], v[26:27]
	ds_read_b64 v[170:171], v244
	ds_read_b64 v[178:179], v243 offset:32
	ds_read_b64 v[198:199], v238 offset:3128
	s_waitcnt lgkmcnt(12)
	v_pk_fma_f32 v[202:203], v[154:155], v[172:173], v[166:167]
	v_pk_fma_f32 v[18:19], v[18:19], v[158:159], v[202:203]
	v_pk_fma_f32 v[18:19], v[162:163], v[180:181], v[18:19]
	ds_read_b64 v[172:173], v244 offset:512
	ds_read_b64 v[180:181], v243 offset:544
	s_waitcnt lgkmcnt(12)
	v_pk_fma_f32 v[202:203], v[154:155], v[174:175], v[166:167]
	v_pk_fma_f32 v[10:11], v[10:11], v[158:159], v[202:203]
	v_pk_fma_f32 v[10:11], v[162:163], v[194:195], v[10:11]
	ds_read_b64 v[174:175], v244 offset:1024
	ds_read_b64 v[194:195], v243 offset:1056
	s_waitcnt lgkmcnt(11)
	v_cndmask_b32_e64 v196, v196, v200, s[4:5]
	v_cndmask_b32_e64 v197, v197, v201, s[4:5]
	v_pk_fma_f32 v[202:203], v[154:155], v[176:177], v[166:167]
	v_pk_fma_f32 v[2:3], v[2:3], v[158:159], v[202:203]
	v_pk_fma_f32 v[2:3], v[162:163], v[196:197], v[2:3]
	ds_read_b64 v[176:177], v244 offset:1536
	ds_read_b64 v[196:197], v243 offset:1568
	ds_read_b64 v[200:201], v246 offset:56
	s_waitcnt lgkmcnt(7)
	v_cndmask_b32_e64 v170, v170, v198, s[6:7]
	v_cndmask_b32_e64 v171, v171, v199, s[6:7]
	v_pk_fma_f32 v[202:203], v[156:157], v[170:171], v[168:169]
	v_pk_fma_f32 v[28:29], v[28:29], v[160:161], v[202:203]
	v_pk_fma_f32 v[28:29], v[164:165], v[178:179], v[28:29]
	s_waitcnt lgkmcnt(5)
	v_pk_fma_f32 v[202:203], v[156:157], v[172:173], v[168:169]
	v_pk_fma_f32 v[20:21], v[20:21], v[160:161], v[202:203]
	v_pk_fma_f32 v[20:21], v[164:165], v[180:181], v[20:21]
	s_waitcnt lgkmcnt(3)
	v_pk_fma_f32 v[202:203], v[156:157], v[174:175], v[168:169]
	v_pk_fma_f32 v[12:13], v[12:13], v[160:161], v[202:203]
	v_pk_fma_f32 v[12:13], v[164:165], v[194:195], v[12:13]
	s_waitcnt lgkmcnt(0)
; #define PG8_LAS __attribute__((address_space(3)))
; __device__ __forceinline__ unsigned cvt_pk_bf16(float lo, float hi) { unsigned r; asm volatile("v_cvt_pk_bf16_f32 %0, %1, %2" : "=v"(r) : "v"(lo), "v"(hi)); return r; }
;     __device__ __forceinline__ void operator()(const f32x4 (&acc)[2][2][4][2], const Unit& u, int wr, int wc, int fr, int fq) const {
;     ...
;                 for (int m = 0; m < 4; ++m) { const int r = 128 * ai + 64 * wr + 16 * m + fr, t = tstart + r;
;                     const bool upok = t >= 1, dnok = (t + 1) < T, store_ok = (r >= vlo) && (r < vhi) && (t < T);
;                     f32x4 res[2];
; #pragma unroll
;                     for (int bj = 0; bj < 2; ++bj) { const f32x4 cur = acc[ai][bj][m][n];
;                         f32x4 su = cur, sd = cur;
;                         if (m > 0) { if (fr == 15) su = acc[ai][bj][m > 0 ? m - 1 : 0][n]; }
;                         if (m < 3) { if (fr == 0) sd = acc[ai][bj][m < 3 ? m + 1 : 3][n]; }
;                         f32x4 up, dn;
;                         up[0] = dpp_ror1(su[0]); up[1] = dpp_ror1(su[1]); up[2] = dpp_ror1(su[2]); up[3] = dpp_ror1(su[3]);
;                         dn[0] = dpp_ror15(sd[0]); dn[1] = dpp_ror15(sd[1]); dn[2] = dpp_ror15(sd[2]); dn[3] = dpp_ror15(sd[3]);
;                         if (m == 0) { f32x4 halo = zero4; if (blk > 0) halo = *(const PG8_LAS f32x4*)(xb + (((((blk - 1) * 2 + 1) * 4 + wc) * 4 + fq) * 16 + (bj * 2 + n) * 4)); if (fr == 0) up = halo; }
;                         if (m == 3) { f32x4 halo = zero4; if (blk < 3) halo = *(const PG8_LAS f32x4*)(xb + (((((blk + 1) * 2 + 0) * 4 + wc) * 4 + fq) * 16 + (bj * 2 + n) * 4)); if (fr == 15) dn = halo; }
;                         if (edge) { if (!upok) up = zero4; if (!dnok) dn = zero4; }
;                         res[bj] = bb[bj] + w0[bj] * up + w1[bj] * cur + w2[bj] * dn; }
;                     if (store_ok) {
;                         float o[4];
; #pragma unroll
;                         for (int j = 0; j < 4; ++j) { const float gg = res[1][j]; o[j] = gg * __builtin_amdgcn_rcpf(1.f + __expf(-gg)) * res[0][j]; }
;                         u32x2 w; w.x = cvt_pk_bf16(o[0], o[1]); w.y = cvt_pk_bf16(o[2], o[3]);
;                         *(u32x2*)(ACT + (size_t)(seqrow + t) * 2816 + ch0 + 4 * n) = w; } } }
	v_cndmask_b32_e64 v196, v196, v200, s[4:5]
	v_cndmask_b32_e64 v197, v197, v201, s[4:5]
	v_pk_fma_f32 v[202:203], v[156:157], v[176:177], v[168:169]
	v_pk_fma_f32 v[4:5], v[4:5], v[160:161], v[202:203]
	v_pk_fma_f32 v[4:5], v[164:165], v[196:197], v[4:5]
	v_mul_f32_e32 v208, 0xbfb8aa3b, v26
	v_mul_f32_e32 v209, 0xbfb8aa3b, v27
	v_mul_f32_e32 v210, 0xbfb8aa3b, v28
	v_mul_f32_e32 v211, 0xbfb8aa3b, v29
	v_exp_f32_e32 v208, v208
	v_exp_f32_e32 v209, v209
	v_exp_f32_e32 v210, v210
	v_exp_f32_e32 v211, v211
	v_add_f32_e32 v208, 1.0, v208
	v_add_f32_e32 v209, 1.0, v209
	v_add_f32_e32 v210, 1.0, v210
	v_add_f32_e32 v211, 1.0, v211
	v_rcp_f32_e32 v208, v208
	v_rcp_f32_e32 v209, v209
	v_rcp_f32_e32 v210, v210
	v_rcp_f32_e32 v211, v211
	v_mul_f32_e32 v26, v26, v208
	v_mul_f32_e32 v27, v27, v209
	v_mul_f32_e32 v28, v28, v210
	v_mul_f32_e32 v29, v29, v211
	v_mul_f32_e32 v26, v30, v26
	v_mul_f32_e32 v27, v31, v27
	v_mul_f32_e32 v28, v32, v28
	v_mul_f32_e32 v29, v33, v29
	v_cvt_pk_bf16_f32 v212, v26, v27
	v_cvt_pk_bf16_f32 v213, v28, v29
	v_mad_u32_u24 v221, v234, s29, v247
	s_and_saveexec_b64 s[30:31], s[20:21]
	global_store_dwordx2 v221, v[212:213], s[10:11] offset:8
	s_mov_b64 exec, s[30:31]
	v_mul_f32_e32 v208, 0xbfb8aa3b, v18
	v_mul_f32_e32 v209, 0xbfb8aa3b, v19
	v_mul_f32_e32 v210, 0xbfb8aa3b, v20
	v_mul_f32_e32 v211, 0xbfb8aa3b, v21
	v_exp_f32_e32 v208, v208
	v_exp_f32_e32 v209, v209
	v_exp_f32_e32 v210, v210
	v_exp_f32_e32 v211, v211
	v_add_f32_e32 v208, 1.0, v208
	v_add_f32_e32 v209, 1.0, v209
	v_add_f32_e32 v210, 1.0, v210
	v_add_f32_e32 v211, 1.0, v211
	v_rcp_f32_e32 v208, v208
	v_rcp_f32_e32 v209, v209
	v_rcp_f32_e32 v210, v210
	v_rcp_f32_e32 v211, v211
	v_mul_f32_e32 v18, v18, v208
	v_mul_f32_e32 v19, v19, v209
	v_mul_f32_e32 v20, v20, v210
	v_mul_f32_e32 v21, v21, v211
	v_mul_f32_e32 v18, v22, v18
	v_mul_f32_e32 v19, v23, v19
	v_mul_f32_e32 v20, v24, v20
	v_mul_f32_e32 v21, v25, v21
	v_cvt_pk_bf16_f32 v218, v18, v19
	v_cvt_pk_bf16_f32 v219, v20, v21
	v_mad_u32_u24 v40, v235, s29, v247
	s_and_saveexec_b64 s[30:31], s[22:23]
	global_store_dwordx2 v40, v[218:219], s[10:11] offset:8
	s_mov_b64 exec, s[30:31]
	v_mul_f32_e32 v208, 0xbfb8aa3b, v10
	v_mul_f32_e32 v209, 0xbfb8aa3b, v11
	v_mul_f32_e32 v210, 0xbfb8aa3b, v12
	v_mul_f32_e32 v211, 0xbfb8aa3b, v13
	v_exp_f32_e32 v208, v208
	v_exp_f32_e32 v209, v209
	v_exp_f32_e32 v210, v210
	v_exp_f32_e32 v211, v211
	v_add_f32_e32 v208, 1.0, v208
	v_add_f32_e32 v209, 1.0, v209
	v_add_f32_e32 v210, 1.0, v210
	v_add_f32_e32 v211, 1.0, v211
	v_rcp_f32_e32 v208, v208
	v_rcp_f32_e32 v209, v209
	v_rcp_f32_e32 v210, v210
	v_rcp_f32_e32 v211, v211
	v_mul_f32_e32 v10, v10, v208
	v_mul_f32_e32 v11, v11, v209
	v_mul_f32_e32 v12, v12, v210
	v_mul_f32_e32 v13, v13, v211
	v_mul_f32_e32 v10, v14, v10
	v_mul_f32_e32 v11, v15, v11
	v_mul_f32_e32 v12, v16, v12
	v_mul_f32_e32 v13, v17, v13
	v_cvt_pk_bf16_f32 v212, v10, v11
	v_cvt_pk_bf16_f32 v213, v12, v13
	v_mad_u32_u24 v221, v236, s29, v247
	s_and_saveexec_b64 s[30:31], s[24:25]
	global_store_dwordx2 v221, v[212:213], s[10:11] offset:8
	s_mov_b64 exec, s[30:31]
	v_mul_f32_e32 v208, 0xbfb8aa3b, v2
	v_mul_f32_e32 v209, 0xbfb8aa3b, v3
	v_mul_f32_e32 v210, 0xbfb8aa3b, v4
	v_mul_f32_e32 v211, 0xbfb8aa3b, v5
	v_exp_f32_e32 v208, v208
	v_exp_f32_e32 v209, v209
	v_exp_f32_e32 v210, v210
	v_exp_f32_e32 v211, v211
	v_add_f32_e32 v208, 1.0, v208
	v_add_f32_e32 v209, 1.0, v209
	v_add_f32_e32 v210, 1.0, v210
	v_add_f32_e32 v211, 1.0, v211
	v_rcp_f32_e32 v208, v208
	v_rcp_f32_e32 v209, v209
	v_rcp_f32_e32 v210, v210
	v_rcp_f32_e32 v211, v211
	v_mul_f32_e32 v2, v2, v208
	v_mul_f32_e32 v3, v3, v209
	v_mul_f32_e32 v4, v4, v210
	v_mul_f32_e32 v5, v5, v211
	v_mul_f32_e32 v2, v6, v2
	v_mul_f32_e32 v3, v7, v3
	v_mul_f32_e32 v4, v8, v4
	v_mul_f32_e32 v5, v9, v5
	v_cvt_pk_bf16_f32 v218, v2, v3
	v_cvt_pk_bf16_f32 v219, v4, v5
	v_mad_u32_u24 v40, v237, s29, v247
	s_and_saveexec_b64 s[30:31], s[26:27]
	global_store_dwordx2 v40, v[218:219], s[10:11] offset:8
	s_mov_b64 exec, s[30:31]
	s_branch .Lec_done
.Lec_edge:
	v_cmp_le_i32_e64 s[12:13], s54, v227
	v_cmp_gt_i32_e32 vcc, s55, v227
	s_and_b64 s[12:13], s[12:13], vcc
	v_add_u32_e32 v220, s48, v227
	v_cmp_gt_i32_e32 vcc, s93, v220
	s_and_b64 s[12:13], s[12:13], vcc
	v_cmp_le_i32_e64 s[14:15], s54, v231
	v_cmp_gt_i32_e32 vcc, s55, v231
	s_and_b64 s[14:15], s[14:15], vcc
	v_add_u32_e32 v220, s48, v231
	v_cmp_gt_i32_e32 vcc, s93, v220
	s_and_b64 s[14:15], s[14:15], vcc
	v_cmp_le_i32_e64 s[16:17], s54, v232
	v_cmp_gt_i32_e32 vcc, s55, v232
	s_and_b64 s[16:17], s[16:17], vcc
	v_add_u32_e32 v220, s48, v232
	v_cmp_gt_i32_e32 vcc, s93, v220
	s_and_b64 s[16:17], s[16:17], vcc
	v_cmp_le_i32_e64 s[18:19], s54, v233
	v_cmp_gt_i32_e32 vcc, s55, v233
	s_and_b64 s[18:19], s[18:19], vcc
	v_add_u32_e32 v220, s48, v233
	v_cmp_gt_i32_e32 vcc, s93, v220
	s_and_b64 s[18:19], s[18:19], vcc
	v_cmp_le_i32_e64 s[20:21], s54, v234
	v_cmp_gt_i32_e32 vcc, s55, v234
	s_and_b64 s[20:21], s[20:21], vcc
	v_add_u32_e32 v220, s48, v234
	v_cmp_gt_i32_e32 vcc, s93, v220
	s_and_b64 s[20:21], s[20:21], vcc
	v_cmp_le_i32_e64 s[22:23], s54, v235
	v_cmp_gt_i32_e32 vcc, s55, v235
	s_and_b64 s[22:23], s[22:23], vcc
	v_add_u32_e32 v220, s48, v235
	v_cmp_gt_i32_e32 vcc, s93, v220
	s_and_b64 s[22:23], s[22:23], vcc
	v_cmp_le_i32_e64 s[24:25], s54, v236
	v_cmp_gt_i32_e32 vcc, s55, v236
	s_and_b64 s[24:25], s[24:25], vcc
	v_add_u32_e32 v220, s48, v236
	v_cmp_gt_i32_e32 vcc, s93, v220
	s_and_b64 s[24:25], s[24:25], vcc
	v_cmp_le_i32_e64 s[26:27], s54, v237
	v_cmp_gt_i32_e32 vcc, s55, v237
	s_and_b64 s[26:27], s[26:27], vcc
	v_add_u32_e32 v220, s48, v237
	v_cmp_gt_i32_e32 vcc, s93, v220
	s_and_b64 s[26:27], s[26:27], vcc
	ds_write_b64 v243, v[166:167]
	ds_write_b64 v243, v[158:159] offset:512
	ds_write_b64 v243, v[150:151] offset:1024
	ds_write_b64 v243, v[142:143] offset:1536
	ds_read_b64 v[170:171], v244
	ds_read_b64 v[178:179], v243 offset:32
	ds_read_b64 v[198:199], v245
	ds_read_b64 v[172:173], v244 offset:512
	ds_read_b64 v[180:181], v243 offset:544
	ds_read_b64 v[174:175], v244 offset:1024
	ds_read_b64 v[194:195], v243 offset:1056
	ds_read_b64 v[176:177], v244 offset:1536
	ds_read_b64 v[196:197], v243 offset:1568
	ds_read_b64 v[200:201], v238 offset:2048
	s_waitcnt vmcnt(0)
; #define PG8_LAS __attribute__((address_space(3)))
; __device__ __forceinline__ unsigned cvt_pk_bf16(float lo, float hi) { unsigned r; asm volatile("v_cvt_pk_bf16_f32 %0, %1, %2" : "=v"(r) : "v"(lo), "v"(hi)); return r; }
;     __device__ __forceinline__ void operator()(const f32x4 (&acc)[2][2][4][2], const Unit& u, int wr, int wc, int fr, int fq) const {
;     ...
;                 for (int m = 0; m < 4; ++m) { const int r = 128 * ai + 64 * wr + 16 * m + fr, t = tstart + r;
;                     const bool upok = t >= 1, dnok = (t + 1) < T, store_ok = (r >= vlo) && (r < vhi) && (t < T);
;                     f32x4 res[2];
; #pragma unroll
;                     for (int bj = 0; bj < 2; ++bj) { const f32x4 cur = acc[ai][bj][m][n];
;                         f32x4 su = cur, sd = cur;
;                         if (m > 0) { if (fr == 15) su = acc[ai][bj][m > 0 ? m - 1 : 0][n]; }
;                         if (m < 3) { if (fr == 0) sd = acc[ai][bj][m < 3 ? m + 1 : 3][n]; }
;                         f32x4 up, dn;
;                         up[0] = dpp_ror1(su[0]); up[1] = dpp_ror1(su[1]); up[2] = dpp_ror1(su[2]); up[3] = dpp_ror1(su[3]);
;                         dn[0] = dpp_ror15(sd[0]); dn[1] = dpp_ror15(sd[1]); dn[2] = dpp_ror15(sd[2]); dn[3] = dpp_ror15(sd[3]);
;                         if (m == 0) { f32x4 halo = zero4; if (blk > 0) halo = *(const PG8_LAS f32x4*)(xb + (((((blk - 1) * 2 + 1) * 4 + wc) * 4 + fq) * 16 + (bj * 2 + n) * 4)); if (fr == 0) up = halo; }
;                         if (m == 3) { f32x4 halo = zero4; if (blk < 3) halo = *(const PG8_LAS f32x4*)(xb + (((((blk + 1) * 2 + 0) * 4 + wc) * 4 + fq) * 16 + (bj * 2 + n) * 4)); if (fr == 15) dn = halo; }
;                         if (edge) { if (!upok) up = zero4; if (!dnok) dn = zero4; }
;                         res[bj] = bb[bj] + w0[bj] * up + w1[bj] * cur + w2[bj] * dn; }
;                     if (store_ok) {
;                         float o[4];
; #pragma unroll
;                         for (int j = 0; j < 4; ++j) { const float gg = res[1][j]; o[j] = gg * __builtin_amdgcn_rcpf(1.f + __expf(-gg)) * res[0][j]; }
;                         u32x2 w; w.x = cvt_pk_bf16(o[0], o[1]); w.y = cvt_pk_bf16(o[2], o[3]);
;                         *(u32x2*)(ACT + (size_t)(seqrow + t) * 2816 + ch0 + 4 * n) = w; } } }
	ds_write_b64 v243, v[168:169]
	ds_write_b64 v243, v[160:161] offset:512
	ds_write_b64 v243, v[152:153] offset:1024
	ds_write_b64 v243, v[144:145] offset:1536
	s_waitcnt lgkmcnt(11)
	v_cndmask_b32_e64 v170, v170, v198, s[6:7]
	v_cndmask_b32_e64 v171, v171, v199, s[6:7]
	v_add_u32_e32 v220, s48, v227
	v_cmp_lt_i32_e32 vcc, 0, v220
	s_nop 1
	v_cndmask_b32_e32 v170, 0, v170, vcc
	v_cndmask_b32_e32 v171, 0, v171, vcc
	v_cmp_gt_i32_e32 vcc, s28, v220
	s_nop 1
	v_cndmask_b32_e32 v178, 0, v178, vcc
	v_cndmask_b32_e32 v179, 0, v179, vcc
	v_pk_fma_f32 v[202:203], v[106:107], v[170:171], v[118:119]
	v_pk_fma_f32 v[166:167], v[166:167], v[110:111], v[202:203]
	v_pk_fma_f32 v[166:167], v[114:115], v[178:179], v[166:167]
	ds_read_b64 v[170:171], v244
	ds_read_b64 v[178:179], v243 offset:32
	ds_read_b64 v[198:199], v245 offset:8
	s_waitcnt lgkmcnt(12)
	v_add_u32_e32 v220, s48, v231
	v_cmp_lt_i32_e32 vcc, 0, v220
	s_nop 1
	v_cndmask_b32_e32 v172, 0, v172, vcc
	v_cndmask_b32_e32 v173, 0, v173, vcc
	v_cmp_gt_i32_e32 vcc, s28, v220
	s_nop 1
	v_cndmask_b32_e32 v180, 0, v180, vcc
	v_cndmask_b32_e32 v181, 0, v181, vcc
	v_pk_fma_f32 v[202:203], v[106:107], v[172:173], v[118:119]
	v_pk_fma_f32 v[158:159], v[158:159], v[110:111], v[202:203]
	v_pk_fma_f32 v[158:159], v[114:115], v[180:181], v[158:159]
	ds_read_b64 v[172:173], v244 offset:512
	ds_read_b64 v[180:181], v243 offset:544
	s_waitcnt lgkmcnt(12)
	v_add_u32_e32 v220, s48, v232
	v_cmp_lt_i32_e32 vcc, 0, v220
	s_nop 1
	v_cndmask_b32_e32 v174, 0, v174, vcc
	v_cndmask_b32_e32 v175, 0, v175, vcc
	v_cmp_gt_i32_e32 vcc, s28, v220
	s_nop 1
	v_cndmask_b32_e32 v194, 0, v194, vcc
	v_cndmask_b32_e32 v195, 0, v195, vcc
	v_pk_fma_f32 v[202:203], v[106:107], v[174:175], v[118:119]
	v_pk_fma_f32 v[150:151], v[150:151], v[110:111], v[202:203]
	v_pk_fma_f32 v[150:151], v[114:115], v[194:195], v[150:151]
	ds_read_b64 v[174:175], v244 offset:1024
	ds_read_b64 v[194:195], v243 offset:1056
	s_waitcnt lgkmcnt(11)
	v_cndmask_b32_e64 v196, v196, v200, s[4:5]
	v_cndmask_b32_e64 v197, v197, v201, s[4:5]
	v_add_u32_e32 v220, s48, v233
	v_cmp_lt_i32_e32 vcc, 0, v220
	s_nop 1
	v_cndmask_b32_e32 v176, 0, v176, vcc
	v_cndmask_b32_e32 v177, 0, v177, vcc
	v_cmp_gt_i32_e32 vcc, s28, v220
	s_nop 1
	v_cndmask_b32_e32 v196, 0, v196, vcc
	v_cndmask_b32_e32 v197, 0, v197, vcc
	v_pk_fma_f32 v[202:203], v[106:107], v[176:177], v[118:119]
	v_pk_fma_f32 v[142:143], v[142:143], v[110:111], v[202:203]
	v_pk_fma_f32 v[142:143], v[114:115], v[196:197], v[142:143]
	ds_read_b64 v[176:177], v244 offset:1536
	ds_read_b64 v[196:197], v243 offset:1568
	ds_read_b64 v[200:201], v238 offset:2056
	ds_write_b64 v243, v[162:163]
	ds_write_b64 v243, v[154:155] offset:512
	ds_write_b64 v243, v[146:147] offset:1024
	ds_write_b64 v243, v[138:139] offset:1536
	s_waitcnt lgkmcnt(11)
	v_cndmask_b32_e64 v170, v170, v198, s[6:7]
	v_cndmask_b32_e64 v171, v171, v199, s[6:7]
	v_add_u32_e32 v220, s48, v227
	v_cmp_lt_i32_e32 vcc, 0, v220
	s_nop 1
	v_cndmask_b32_e32 v170, 0, v170, vcc
	v_cndmask_b32_e32 v171, 0, v171, vcc
	v_cmp_gt_i32_e32 vcc, s28, v220
	s_nop 1
	v_cndmask_b32_e32 v178, 0, v178, vcc
	v_cndmask_b32_e32 v179, 0, v179, vcc
	v_pk_fma_f32 v[202:203], v[108:109], v[170:171], v[120:121]
	v_pk_fma_f32 v[168:169], v[168:169], v[112:113], v[202:203]
	v_pk_fma_f32 v[168:169], v[116:117], v[178:179], v[168:169]
	ds_read_b64 v[170:171], v244
	ds_read_b64 v[178:179], v243 offset:32
	ds_read_b64 v[198:199], v245 offset:32
	s_waitcnt lgkmcnt(12)
	v_add_u32_e32 v220, s48, v231
	v_cmp_lt_i32_e32 vcc, 0, v220
	s_nop 1
	v_cndmask_b32_e32 v172, 0, v172, vcc
	v_cndmask_b32_e32 v173, 0, v173, vcc
	v_cmp_gt_i32_e32 vcc, s28, v220
	s_nop 1
	v_cndmask_b32_e32 v180, 0, v180, vcc
	v_cndmask_b32_e32 v181, 0, v181, vcc
	v_pk_fma_f32 v[202:203], v[108:109], v[172:173], v[120:121]
	v_pk_fma_f32 v[160:161], v[160:161], v[112:113], v[202:203]
	v_pk_fma_f32 v[160:161], v[116:117], v[180:181], v[160:161]
	ds_read_b64 v[172:173], v244 offset:512
	ds_read_b64 v[180:181], v243 offset:544
	s_waitcnt lgkmcnt(12)
	v_add_u32_e32 v220, s48, v232
	v_cmp_lt_i32_e32 vcc, 0, v220
	s_nop 1
	v_cndmask_b32_e32 v174, 0, v174, vcc
	v_cndmask_b32_e32 v175, 0, v175, vcc
	v_cmp_gt_i32_e32 vcc, s28, v220
	s_nop 1
	v_cndmask_b32_e32 v194, 0, v194, vcc
	v_cndmask_b32_e32 v195, 0, v195, vcc
	v_pk_fma_f32 v[202:203], v[108:109], v[174:175], v[120:121]
	v_pk_fma_f32 v[152:153], v[152:153], v[112:113], v[202:203]
	v_pk_fma_f32 v[152:153], v[116:117], v[194:195], v[152:153]
	ds_read_b64 v[174:175], v244 offset:1024
	ds_read_b64 v[194:195], v243 offset:1056
	s_waitcnt lgkmcnt(11)
	v_cndmask_b32_e64 v196, v196, v200, s[4:5]
	v_cndmask_b32_e64 v197, v197, v201, s[4:5]
	v_add_u32_e32 v220, s48, v233
	v_cmp_lt_i32_e32 vcc, 0, v220
	s_nop 1
	v_cndmask_b32_e32 v176, 0, v176, vcc
	v_cndmask_b32_e32 v177, 0, v177, vcc
	v_cmp_gt_i32_e32 vcc, s28, v220
	s_nop 1
	v_cndmask_b32_e32 v196, 0, v196, vcc
	v_cndmask_b32_e32 v197, 0, v197, vcc
	v_pk_fma_f32 v[202:203], v[108:109], v[176:177], v[120:121]
	v_pk_fma_f32 v[144:145], v[144:145], v[112:113], v[202:203]
	v_pk_fma_f32 v[144:145], v[116:117], v[196:197], v[144:145]
	ds_read_b64 v[176:177], v244 offset:1536
	ds_read_b64 v[196:197], v243 offset:1568
	ds_read_b64 v[200:201], v238 offset:2080
	ds_write_b64 v243, v[164:165]
	ds_write_b64 v243, v[156:157] offset:512
	ds_write_b64 v243, v[148:149] offset:1024
	ds_write_b64 v243, v[140:141] offset:1536
	s_waitcnt lgkmcnt(11)
; #define PG8_LAS __attribute__((address_space(3)))
; __device__ __forceinline__ unsigned cvt_pk_bf16(float lo, float hi) { unsigned r; asm volatile("v_cvt_pk_bf16_f32 %0, %1, %2" : "=v"(r) : "v"(lo), "v"(hi)); return r; }
;     __device__ __forceinline__ void operator()(const f32x4 (&acc)[2][2][4][2], const Unit& u, int wr, int wc, int fr, int fq) const {
;     ...
;                 for (int m = 0; m < 4; ++m) { const int r = 128 * ai + 64 * wr + 16 * m + fr, t = tstart + r;
;                     const bool upok = t >= 1, dnok = (t + 1) < T, store_ok = (r >= vlo) && (r < vhi) && (t < T);
;                     f32x4 res[2];
; #pragma unroll
;                     for (int bj = 0; bj < 2; ++bj) { const f32x4 cur = acc[ai][bj][m][n];
;                         f32x4 su = cur, sd = cur;
;                         if (m > 0) { if (fr == 15) su = acc[ai][bj][m > 0 ? m - 1 : 0][n]; }
;                         if (m < 3) { if (fr == 0) sd = acc[ai][bj][m < 3 ? m + 1 : 3][n]; }
;                         f32x4 up, dn;
;                         up[0] = dpp_ror1(su[0]); up[1] = dpp_ror1(su[1]); up[2] = dpp_ror1(su[2]); up[3] = dpp_ror1(su[3]);
;                         dn[0] = dpp_ror15(sd[0]); dn[1] = dpp_ror15(sd[1]); dn[2] = dpp_ror15(sd[2]); dn[3] = dpp_ror15(sd[3]);
;                         if (m == 0) { f32x4 halo = zero4; if (blk > 0) halo = *(const PG8_LAS f32x4*)(xb + (((((blk - 1) * 2 + 1) * 4 + wc) * 4 + fq) * 16 + (bj * 2 + n) * 4)); if (fr == 0) up = halo; }
;                         if (m == 3) { f32x4 halo = zero4; if (blk < 3) halo = *(const PG8_LAS f32x4*)(xb + (((((blk + 1) * 2 + 0) * 4 + wc) * 4 + fq) * 16 + (bj * 2 + n) * 4)); if (fr == 15) dn = halo; }
;                         if (edge) { if (!upok) up = zero4; if (!dnok) dn = zero4; }
;                         res[bj] = bb[bj] + w0[bj] * up + w1[bj] * cur + w2[bj] * dn; }
;                     if (store_ok) {
;                         float o[4];
; #pragma unroll
;                         for (int j = 0; j < 4; ++j) { const float gg = res[1][j]; o[j] = gg * __builtin_amdgcn_rcpf(1.f + __expf(-gg)) * res[0][j]; }
;                         u32x2 w; w.x = cvt_pk_bf16(o[0], o[1]); w.y = cvt_pk_bf16(o[2], o[3]);
;                         *(u32x2*)(ACT + (size_t)(seqrow + t) * 2816 + ch0 + 4 * n) = w; } } }
	v_cndmask_b32_e64 v170, v170, v198, s[6:7]
	v_cndmask_b32_e64 v171, v171, v199, s[6:7]
	v_add_u32_e32 v220, s48, v227
	v_cmp_lt_i32_e32 vcc, 0, v220
	s_nop 1
	v_cndmask_b32_e32 v170, 0, v170, vcc
	v_cndmask_b32_e32 v171, 0, v171, vcc
	v_cmp_gt_i32_e32 vcc, s28, v220
	s_nop 1
	v_cndmask_b32_e32 v178, 0, v178, vcc
	v_cndmask_b32_e32 v179, 0, v179, vcc
	v_pk_fma_f32 v[202:203], v[122:123], v[170:171], v[134:135]
	v_pk_fma_f32 v[162:163], v[162:163], v[126:127], v[202:203]
	v_pk_fma_f32 v[162:163], v[130:131], v[178:179], v[162:163]
	ds_read_b64 v[170:171], v244
	ds_read_b64 v[178:179], v243 offset:32
	ds_read_b64 v[198:199], v245 offset:40
	s_waitcnt lgkmcnt(12)
	v_add_u32_e32 v220, s48, v231
	v_cmp_lt_i32_e32 vcc, 0, v220
	s_nop 1
	v_cndmask_b32_e32 v172, 0, v172, vcc
	v_cndmask_b32_e32 v173, 0, v173, vcc
	v_cmp_gt_i32_e32 vcc, s28, v220
	s_nop 1
	v_cndmask_b32_e32 v180, 0, v180, vcc
	v_cndmask_b32_e32 v181, 0, v181, vcc
	v_pk_fma_f32 v[202:203], v[122:123], v[172:173], v[134:135]
	v_pk_fma_f32 v[154:155], v[154:155], v[126:127], v[202:203]
	v_pk_fma_f32 v[154:155], v[130:131], v[180:181], v[154:155]
	ds_read_b64 v[172:173], v244 offset:512
	ds_read_b64 v[180:181], v243 offset:544
	s_waitcnt lgkmcnt(12)
	v_add_u32_e32 v220, s48, v232
	v_cmp_lt_i32_e32 vcc, 0, v220
	s_nop 1
	v_cndmask_b32_e32 v174, 0, v174, vcc
	v_cndmask_b32_e32 v175, 0, v175, vcc
	v_cmp_gt_i32_e32 vcc, s28, v220
	s_nop 1
	v_cndmask_b32_e32 v194, 0, v194, vcc
	v_cndmask_b32_e32 v195, 0, v195, vcc
	v_pk_fma_f32 v[202:203], v[122:123], v[174:175], v[134:135]
	v_pk_fma_f32 v[146:147], v[146:147], v[126:127], v[202:203]
	v_pk_fma_f32 v[146:147], v[130:131], v[194:195], v[146:147]
	ds_read_b64 v[174:175], v244 offset:1024
	ds_read_b64 v[194:195], v243 offset:1056
	s_waitcnt lgkmcnt(11)
	v_cndmask_b32_e64 v196, v196, v200, s[4:5]
	v_cndmask_b32_e64 v197, v197, v201, s[4:5]
	v_add_u32_e32 v220, s48, v233
	v_cmp_lt_i32_e32 vcc, 0, v220
	s_nop 1
	v_cndmask_b32_e32 v176, 0, v176, vcc
	v_cndmask_b32_e32 v177, 0, v177, vcc
	v_cmp_gt_i32_e32 vcc, s28, v220
	s_nop 1
	v_cndmask_b32_e32 v196, 0, v196, vcc
	v_cndmask_b32_e32 v197, 0, v197, vcc
	v_pk_fma_f32 v[202:203], v[122:123], v[176:177], v[134:135]
	v_pk_fma_f32 v[138:139], v[138:139], v[126:127], v[202:203]
	v_pk_fma_f32 v[138:139], v[130:131], v[196:197], v[138:139]
	ds_read_b64 v[176:177], v244 offset:1536
	ds_read_b64 v[196:197], v243 offset:1568
	ds_read_b64 v[200:201], v238 offset:2088
	ds_write_b64 v243, v[102:103]
	ds_write_b64 v243, v[94:95] offset:512
	ds_write_b64 v243, v[86:87] offset:1024
	ds_write_b64 v243, v[78:79] offset:1536
	s_waitcnt lgkmcnt(11)
	v_cndmask_b32_e64 v170, v170, v198, s[6:7]
	v_cndmask_b32_e64 v171, v171, v199, s[6:7]
	v_add_u32_e32 v220, s48, v227
	v_cmp_lt_i32_e32 vcc, 0, v220
	s_nop 1
	v_cndmask_b32_e32 v170, 0, v170, vcc
	v_cndmask_b32_e32 v171, 0, v171, vcc
	v_cmp_gt_i32_e32 vcc, s28, v220
	s_nop 1
	v_cndmask_b32_e32 v178, 0, v178, vcc
	v_cndmask_b32_e32 v179, 0, v179, vcc
	v_pk_fma_f32 v[202:203], v[124:125], v[170:171], v[136:137]
	v_pk_fma_f32 v[164:165], v[164:165], v[128:129], v[202:203]
	v_pk_fma_f32 v[164:165], v[132:133], v[178:179], v[164:165]
	ds_read_b64 v[170:171], v244
	ds_read_b64 v[178:179], v243 offset:32
	ds_read_b64 v[198:199], v238 offset:3072
	s_waitcnt lgkmcnt(12)
	v_add_u32_e32 v220, s48, v231
	v_cmp_lt_i32_e32 vcc, 0, v220
	s_nop 1
	v_cndmask_b32_e32 v172, 0, v172, vcc
	v_cndmask_b32_e32 v173, 0, v173, vcc
	v_cmp_gt_i32_e32 vcc, s28, v220
	s_nop 1
	v_cndmask_b32_e32 v180, 0, v180, vcc
	v_cndmask_b32_e32 v181, 0, v181, vcc
	v_pk_fma_f32 v[202:203], v[124:125], v[172:173], v[136:137]
	v_pk_fma_f32 v[156:157], v[156:157], v[128:129], v[202:203]
	v_pk_fma_f32 v[156:157], v[132:133], v[180:181], v[156:157]
	ds_read_b64 v[172:173], v244 offset:512
	ds_read_b64 v[180:181], v243 offset:544
	s_waitcnt lgkmcnt(12)
	v_add_u32_e32 v220, s48, v232
	v_cmp_lt_i32_e32 vcc, 0, v220
	s_nop 1
	v_cndmask_b32_e32 v174, 0, v174, vcc
	v_cndmask_b32_e32 v175, 0, v175, vcc
	v_cmp_gt_i32_e32 vcc, s28, v220
	s_nop 1
	v_cndmask_b32_e32 v194, 0, v194, vcc
	v_cndmask_b32_e32 v195, 0, v195, vcc
	v_pk_fma_f32 v[202:203], v[124:125], v[174:175], v[136:137]
	v_pk_fma_f32 v[148:149], v[148:149], v[128:129], v[202:203]
	v_pk_fma_f32 v[148:149], v[132:133], v[194:195], v[148:149]
	ds_read_b64 v[174:175], v244 offset:1024
	ds_read_b64 v[194:195], v243 offset:1056
	s_waitcnt lgkmcnt(11)
; #define PG8_LAS __attribute__((address_space(3)))
; __device__ __forceinline__ unsigned cvt_pk_bf16(float lo, float hi) { unsigned r; asm volatile("v_cvt_pk_bf16_f32 %0, %1, %2" : "=v"(r) : "v"(lo), "v"(hi)); return r; }
;     __device__ __forceinline__ void operator()(const f32x4 (&acc)[2][2][4][2], const Unit& u, int wr, int wc, int fr, int fq) const {
;     ...
;                 for (int m = 0; m < 4; ++m) { const int r = 128 * ai + 64 * wr + 16 * m + fr, t = tstart + r;
;                     const bool upok = t >= 1, dnok = (t + 1) < T, store_ok = (r >= vlo) && (r < vhi) && (t < T);
;                     f32x4 res[2];
; #pragma unroll
;                     for (int bj = 0; bj < 2; ++bj) { const f32x4 cur = acc[ai][bj][m][n];
;                         f32x4 su = cur, sd = cur;
;                         if (m > 0) { if (fr == 15) su = acc[ai][bj][m > 0 ? m - 1 : 0][n]; }
;                         if (m < 3) { if (fr == 0) sd = acc[ai][bj][m < 3 ? m + 1 : 3][n]; }
;                         f32x4 up, dn;
;                         up[0] = dpp_ror1(su[0]); up[1] = dpp_ror1(su[1]); up[2] = dpp_ror1(su[2]); up[3] = dpp_ror1(su[3]);
;                         dn[0] = dpp_ror15(sd[0]); dn[1] = dpp_ror15(sd[1]); dn[2] = dpp_ror15(sd[2]); dn[3] = dpp_ror15(sd[3]);
;                         if (m == 0) { f32x4 halo = zero4; if (blk > 0) halo = *(const PG8_LAS f32x4*)(xb + (((((blk - 1) * 2 + 1) * 4 + wc) * 4 + fq) * 16 + (bj * 2 + n) * 4)); if (fr == 0) up = halo; }
;                         if (m == 3) { f32x4 halo = zero4; if (blk < 3) halo = *(const PG8_LAS f32x4*)(xb + (((((blk + 1) * 2 + 0) * 4 + wc) * 4 + fq) * 16 + (bj * 2 + n) * 4)); if (fr == 15) dn = halo; }
;                         if (edge) { if (!upok) up = zero4; if (!dnok) dn = zero4; }
;                         res[bj] = bb[bj] + w0[bj] * up + w1[bj] * cur + w2[bj] * dn; }
;                     if (store_ok) {
;                         float o[4];
; #pragma unroll
;                         for (int j = 0; j < 4; ++j) { const float gg = res[1][j]; o[j] = gg * __builtin_amdgcn_rcpf(1.f + __expf(-gg)) * res[0][j]; }
;                         u32x2 w; w.x = cvt_pk_bf16(o[0], o[1]); w.y = cvt_pk_bf16(o[2], o[3]);
;                         *(u32x2*)(ACT + (size_t)(seqrow + t) * 2816 + ch0 + 4 * n) = w; } } }
	v_cndmask_b32_e64 v196, v196, v200, s[4:5]
	v_cndmask_b32_e64 v197, v197, v201, s[4:5]
	v_add_u32_e32 v220, s48, v233
	v_cmp_lt_i32_e32 vcc, 0, v220
	s_nop 1
	v_cndmask_b32_e32 v176, 0, v176, vcc
	v_cndmask_b32_e32 v177, 0, v177, vcc
	v_cmp_gt_i32_e32 vcc, s28, v220
	s_nop 1
	v_cndmask_b32_e32 v196, 0, v196, vcc
	v_cndmask_b32_e32 v197, 0, v197, vcc
	v_pk_fma_f32 v[202:203], v[124:125], v[176:177], v[136:137]
	v_pk_fma_f32 v[140:141], v[140:141], v[128:129], v[202:203]
	v_pk_fma_f32 v[140:141], v[132:133], v[196:197], v[140:141]
	ds_read_b64 v[176:177], v244 offset:1536
	ds_read_b64 v[196:197], v243 offset:1568
	ds_read_b64 v[200:201], v246
	v_mul_f32_e32 v208, 0xbfb8aa3b, v162
	v_mul_f32_e32 v209, 0xbfb8aa3b, v163
	v_mul_f32_e32 v210, 0xbfb8aa3b, v164
	v_mul_f32_e32 v211, 0xbfb8aa3b, v165
	v_exp_f32_e32 v208, v208
	v_exp_f32_e32 v209, v209
	v_exp_f32_e32 v210, v210
	v_exp_f32_e32 v211, v211
	v_add_f32_e32 v208, 1.0, v208
	v_add_f32_e32 v209, 1.0, v209
	v_add_f32_e32 v210, 1.0, v210
	v_add_f32_e32 v211, 1.0, v211
	v_rcp_f32_e32 v208, v208
	v_rcp_f32_e32 v209, v209
	v_rcp_f32_e32 v210, v210
	v_rcp_f32_e32 v211, v211
	v_mul_f32_e32 v162, v162, v208
	v_mul_f32_e32 v163, v163, v209
	v_mul_f32_e32 v164, v164, v210
	v_mul_f32_e32 v165, v165, v211
	v_mul_f32_e32 v162, v166, v162
	v_mul_f32_e32 v163, v167, v163
	v_mul_f32_e32 v164, v168, v164
	v_mul_f32_e32 v165, v169, v165
	v_cvt_pk_bf16_f32 v212, v162, v163
	v_cvt_pk_bf16_f32 v213, v164, v165
	v_mad_u32_u24 v221, v227, s29, v247
	s_and_saveexec_b64 s[30:31], s[12:13]
	global_store_dwordx2 v221, v[212:213], s[10:11]
	s_mov_b64 exec, s[30:31]
	v_mul_f32_e32 v208, 0xbfb8aa3b, v154
	v_mul_f32_e32 v209, 0xbfb8aa3b, v155
	v_mul_f32_e32 v210, 0xbfb8aa3b, v156
	v_mul_f32_e32 v211, 0xbfb8aa3b, v157
	v_exp_f32_e32 v208, v208
	v_exp_f32_e32 v209, v209
	v_exp_f32_e32 v210, v210
	v_exp_f32_e32 v211, v211
	v_add_f32_e32 v208, 1.0, v208
	v_add_f32_e32 v209, 1.0, v209
	v_add_f32_e32 v210, 1.0, v210
	v_add_f32_e32 v211, 1.0, v211
	v_rcp_f32_e32 v208, v208
	v_rcp_f32_e32 v209, v209
	v_rcp_f32_e32 v210, v210
	v_rcp_f32_e32 v211, v211
	v_mul_f32_e32 v154, v154, v208
	v_mul_f32_e32 v155, v155, v209
	v_mul_f32_e32 v156, v156, v210
	v_mul_f32_e32 v157, v157, v211
	v_mul_f32_e32 v154, v158, v154
	v_mul_f32_e32 v155, v159, v155
	v_mul_f32_e32 v156, v160, v156
	v_mul_f32_e32 v157, v161, v157
	v_cvt_pk_bf16_f32 v218, v154, v155
	v_cvt_pk_bf16_f32 v219, v156, v157
	v_mad_u32_u24 v40, v231, s29, v247
	s_and_saveexec_b64 s[30:31], s[14:15]
	global_store_dwordx2 v40, v[218:219], s[10:11]
	s_mov_b64 exec, s[30:31]
	v_mul_f32_e32 v208, 0xbfb8aa3b, v146
	v_mul_f32_e32 v209, 0xbfb8aa3b, v147
	v_mul_f32_e32 v210, 0xbfb8aa3b, v148
	v_mul_f32_e32 v211, 0xbfb8aa3b, v149
	v_exp_f32_e32 v208, v208
	v_exp_f32_e32 v209, v209
	v_exp_f32_e32 v210, v210
	v_exp_f32_e32 v211, v211
	v_add_f32_e32 v208, 1.0, v208
	v_add_f32_e32 v209, 1.0, v209
	v_add_f32_e32 v210, 1.0, v210
	v_add_f32_e32 v211, 1.0, v211
	v_rcp_f32_e32 v208, v208
	v_rcp_f32_e32 v209, v209
	v_rcp_f32_e32 v210, v210
	v_rcp_f32_e32 v211, v211
	v_mul_f32_e32 v146, v146, v208
	v_mul_f32_e32 v147, v147, v209
	v_mul_f32_e32 v148, v148, v210
	v_mul_f32_e32 v149, v149, v211
	v_mul_f32_e32 v146, v150, v146
	v_mul_f32_e32 v147, v151, v147
	v_mul_f32_e32 v148, v152, v148
	v_mul_f32_e32 v149, v153, v149
	v_cvt_pk_bf16_f32 v212, v146, v147
	v_cvt_pk_bf16_f32 v213, v148, v149
	v_mad_u32_u24 v221, v232, s29, v247
	s_and_saveexec_b64 s[30:31], s[16:17]
	global_store_dwordx2 v221, v[212:213], s[10:11]
	s_mov_b64 exec, s[30:31]
	v_mul_f32_e32 v208, 0xbfb8aa3b, v138
	v_mul_f32_e32 v209, 0xbfb8aa3b, v139
	v_mul_f32_e32 v210, 0xbfb8aa3b, v140
	v_mul_f32_e32 v211, 0xbfb8aa3b, v141
	v_exp_f32_e32 v208, v208
	v_exp_f32_e32 v209, v209
	v_exp_f32_e32 v210, v210
	v_exp_f32_e32 v211, v211
	v_add_f32_e32 v208, 1.0, v208
	v_add_f32_e32 v209, 1.0, v209
	v_add_f32_e32 v210, 1.0, v210
	v_add_f32_e32 v211, 1.0, v211
	v_rcp_f32_e32 v208, v208
	v_rcp_f32_e32 v209, v209
	v_rcp_f32_e32 v210, v210
	v_rcp_f32_e32 v211, v211
	v_mul_f32_e32 v138, v138, v208
	v_mul_f32_e32 v139, v139, v209
	v_mul_f32_e32 v140, v140, v210
	v_mul_f32_e32 v141, v141, v211
	v_mul_f32_e32 v138, v142, v138
	v_mul_f32_e32 v139, v143, v139
	v_mul_f32_e32 v140, v144, v140
	v_mul_f32_e32 v141, v145, v141
	v_cvt_pk_bf16_f32 v218, v138, v139
	v_cvt_pk_bf16_f32 v219, v140, v141
	v_mad_u32_u24 v40, v233, s29, v247
	s_and_saveexec_b64 s[30:31], s[18:19]
	global_store_dwordx2 v40, v[218:219], s[10:11]
	s_mov_b64 exec, s[30:31]
	global_load_dwordx4 v[138:141], v248, s[62:63] offset:16
	global_load_dwordx4 v[142:145], v248, s[66:67] offset:16
	global_load_dwordx4 v[146:149], v248, s[68:69] offset:16
	global_load_dwordx4 v[150:153], v248, s[64:65] offset:16
	global_load_dwordx4 v[154:157], v249, s[62:63] offset:16
	global_load_dwordx4 v[158:161], v249, s[66:67] offset:16
	global_load_dwordx4 v[162:165], v249, s[68:69] offset:16
	global_load_dwordx4 v[166:169], v249, s[64:65] offset:16
	ds_write_b64 v243, v[104:105]
	ds_write_b64 v243, v[96:97] offset:512
	ds_write_b64 v243, v[88:89] offset:1024
	ds_write_b64 v243, v[80:81] offset:1536
	s_waitcnt lgkmcnt(11)
	v_cndmask_b32_e64 v170, v170, v198, s[6:7]
	v_cndmask_b32_e64 v171, v171, v199, s[6:7]
	v_add_u32_e32 v220, s48, v234
	v_cmp_lt_i32_e32 vcc, 0, v220
	s_nop 1
	v_cndmask_b32_e32 v170, 0, v170, vcc
	v_cndmask_b32_e32 v171, 0, v171, vcc
	v_cmp_gt_i32_e32 vcc, s28, v220
	s_nop 1
	v_cndmask_b32_e32 v178, 0, v178, vcc
	v_cndmask_b32_e32 v179, 0, v179, vcc
	v_pk_fma_f32 v[202:203], v[106:107], v[170:171], v[118:119]
	v_pk_fma_f32 v[102:103], v[102:103], v[110:111], v[202:203]
	v_pk_fma_f32 v[102:103], v[114:115], v[178:179], v[102:103]
	ds_read_b64 v[170:171], v244
	ds_read_b64 v[178:179], v243 offset:32
	ds_read_b64 v[198:199], v238 offset:3080
	s_waitcnt lgkmcnt(12)
; #define PG8_LAS __attribute__((address_space(3)))
; __device__ __forceinline__ unsigned cvt_pk_bf16(float lo, float hi) { unsigned r; asm volatile("v_cvt_pk_bf16_f32 %0, %1, %2" : "=v"(r) : "v"(lo), "v"(hi)); return r; }
;     __device__ __forceinline__ void operator()(const f32x4 (&acc)[2][2][4][2], const Unit& u, int wr, int wc, int fr, int fq) const {
;     ...
;                 for (int m = 0; m < 4; ++m) { const int r = 128 * ai + 64 * wr + 16 * m + fr, t = tstart + r;
;                     const bool upok = t >= 1, dnok = (t + 1) < T, store_ok = (r >= vlo) && (r < vhi) && (t < T);
;                     f32x4 res[2];
; #pragma unroll
;                     for (int bj = 0; bj < 2; ++bj) { const f32x4 cur = acc[ai][bj][m][n];
;                         f32x4 su = cur, sd = cur;
;                         if (m > 0) { if (fr == 15) su = acc[ai][bj][m > 0 ? m - 1 : 0][n]; }
;                         if (m < 3) { if (fr == 0) sd = acc[ai][bj][m < 3 ? m + 1 : 3][n]; }
;                         f32x4 up, dn;
;                         up[0] = dpp_ror1(su[0]); up[1] = dpp_ror1(su[1]); up[2] = dpp_ror1(su[2]); up[3] = dpp_ror1(su[3]);
;                         dn[0] = dpp_ror15(sd[0]); dn[1] = dpp_ror15(sd[1]); dn[2] = dpp_ror15(sd[2]); dn[3] = dpp_ror15(sd[3]);
;                         if (m == 0) { f32x4 halo = zero4; if (blk > 0) halo = *(const PG8_LAS f32x4*)(xb + (((((blk - 1) * 2 + 1) * 4 + wc) * 4 + fq) * 16 + (bj * 2 + n) * 4)); if (fr == 0) up = halo; }
;                         if (m == 3) { f32x4 halo = zero4; if (blk < 3) halo = *(const PG8_LAS f32x4*)(xb + (((((blk + 1) * 2 + 0) * 4 + wc) * 4 + fq) * 16 + (bj * 2 + n) * 4)); if (fr == 15) dn = halo; }
;                         if (edge) { if (!upok) up = zero4; if (!dnok) dn = zero4; }
;                         res[bj] = bb[bj] + w0[bj] * up + w1[bj] * cur + w2[bj] * dn; }
;                     if (store_ok) {
;                         float o[4];
; #pragma unroll
;                         for (int j = 0; j < 4; ++j) { const float gg = res[1][j]; o[j] = gg * __builtin_amdgcn_rcpf(1.f + __expf(-gg)) * res[0][j]; }
;                         u32x2 w; w.x = cvt_pk_bf16(o[0], o[1]); w.y = cvt_pk_bf16(o[2], o[3]);
;                         *(u32x2*)(ACT + (size_t)(seqrow + t) * 2816 + ch0 + 4 * n) = w; } } }
	v_add_u32_e32 v220, s48, v235
	v_cmp_lt_i32_e32 vcc, 0, v220
	s_nop 1
	v_cndmask_b32_e32 v172, 0, v172, vcc
	v_cndmask_b32_e32 v173, 0, v173, vcc
	v_cmp_gt_i32_e32 vcc, s28, v220
	s_nop 1
	v_cndmask_b32_e32 v180, 0, v180, vcc
	v_cndmask_b32_e32 v181, 0, v181, vcc
	v_pk_fma_f32 v[202:203], v[106:107], v[172:173], v[118:119]
	v_pk_fma_f32 v[94:95], v[94:95], v[110:111], v[202:203]
	v_pk_fma_f32 v[94:95], v[114:115], v[180:181], v[94:95]
	ds_read_b64 v[172:173], v244 offset:512
	ds_read_b64 v[180:181], v243 offset:544
	s_waitcnt lgkmcnt(12)
	v_add_u32_e32 v220, s48, v236
	v_cmp_lt_i32_e32 vcc, 0, v220
	s_nop 1
	v_cndmask_b32_e32 v174, 0, v174, vcc
	v_cndmask_b32_e32 v175, 0, v175, vcc
	v_cmp_gt_i32_e32 vcc, s28, v220
	s_nop 1
	v_cndmask_b32_e32 v194, 0, v194, vcc
	v_cndmask_b32_e32 v195, 0, v195, vcc
	v_pk_fma_f32 v[202:203], v[106:107], v[174:175], v[118:119]
	v_pk_fma_f32 v[86:87], v[86:87], v[110:111], v[202:203]
	v_pk_fma_f32 v[86:87], v[114:115], v[194:195], v[86:87]
	ds_read_b64 v[174:175], v244 offset:1024
	ds_read_b64 v[194:195], v243 offset:1056
	s_waitcnt lgkmcnt(11)
	v_cndmask_b32_e64 v196, v196, v200, s[4:5]
	v_cndmask_b32_e64 v197, v197, v201, s[4:5]
	v_add_u32_e32 v220, s48, v237
	v_cmp_lt_i32_e32 vcc, 0, v220
	s_nop 1
	v_cndmask_b32_e32 v176, 0, v176, vcc
	v_cndmask_b32_e32 v177, 0, v177, vcc
	v_cmp_gt_i32_e32 vcc, s28, v220
	s_nop 1
	v_cndmask_b32_e32 v196, 0, v196, vcc
	v_cndmask_b32_e32 v197, 0, v197, vcc
	v_pk_fma_f32 v[202:203], v[106:107], v[176:177], v[118:119]
	v_pk_fma_f32 v[78:79], v[78:79], v[110:111], v[202:203]
	v_pk_fma_f32 v[78:79], v[114:115], v[196:197], v[78:79]
	ds_read_b64 v[176:177], v244 offset:1536
	ds_read_b64 v[196:197], v243 offset:1568
	ds_read_b64 v[200:201], v246 offset:8
	ds_write_b64 v243, v[98:99]
	ds_write_b64 v243, v[90:91] offset:512
	ds_write_b64 v243, v[82:83] offset:1024
	ds_write_b64 v243, v[74:75] offset:1536
	s_waitcnt lgkmcnt(11)
	v_cndmask_b32_e64 v170, v170, v198, s[6:7]
	v_cndmask_b32_e64 v171, v171, v199, s[6:7]
	v_add_u32_e32 v220, s48, v234
	v_cmp_lt_i32_e32 vcc, 0, v220
	s_nop 1
	v_cndmask_b32_e32 v170, 0, v170, vcc
	v_cndmask_b32_e32 v171, 0, v171, vcc
	v_cmp_gt_i32_e32 vcc, s28, v220
	s_nop 1
	v_cndmask_b32_e32 v178, 0, v178, vcc
	v_cndmask_b32_e32 v179, 0, v179, vcc
	v_pk_fma_f32 v[202:203], v[108:109], v[170:171], v[120:121]
	v_pk_fma_f32 v[104:105], v[104:105], v[112:113], v[202:203]
	v_pk_fma_f32 v[104:105], v[116:117], v[178:179], v[104:105]
	ds_read_b64 v[170:171], v244
	ds_read_b64 v[178:179], v243 offset:32
	ds_read_b64 v[198:199], v238 offset:3104
	s_waitcnt lgkmcnt(12)
	v_add_u32_e32 v220, s48, v235
	v_cmp_lt_i32_e32 vcc, 0, v220
	s_nop 1
	v_cndmask_b32_e32 v172, 0, v172, vcc
	v_cndmask_b32_e32 v173, 0, v173, vcc
	v_cmp_gt_i32_e32 vcc, s28, v220
	s_nop 1
	v_cndmask_b32_e32 v180, 0, v180, vcc
	v_cndmask_b32_e32 v181, 0, v181, vcc
	v_pk_fma_f32 v[202:203], v[108:109], v[172:173], v[120:121]
	v_pk_fma_f32 v[96:97], v[96:97], v[112:113], v[202:203]
	v_pk_fma_f32 v[96:97], v[116:117], v[180:181], v[96:97]
	ds_read_b64 v[172:173], v244 offset:512
	ds_read_b64 v[180:181], v243 offset:544
	s_waitcnt lgkmcnt(12)
	v_add_u32_e32 v220, s48, v236
	v_cmp_lt_i32_e32 vcc, 0, v220
	s_nop 1
	v_cndmask_b32_e32 v174, 0, v174, vcc
	v_cndmask_b32_e32 v175, 0, v175, vcc
	v_cmp_gt_i32_e32 vcc, s28, v220
	s_nop 1
	v_cndmask_b32_e32 v194, 0, v194, vcc
	v_cndmask_b32_e32 v195, 0, v195, vcc
	v_pk_fma_f32 v[202:203], v[108:109], v[174:175], v[120:121]
	v_pk_fma_f32 v[88:89], v[88:89], v[112:113], v[202:203]
	v_pk_fma_f32 v[88:89], v[116:117], v[194:195], v[88:89]
	ds_read_b64 v[174:175], v244 offset:1024
	ds_read_b64 v[194:195], v243 offset:1056
	s_waitcnt lgkmcnt(11)
	v_cndmask_b32_e64 v196, v196, v200, s[4:5]
	v_cndmask_b32_e64 v197, v197, v201, s[4:5]
	v_add_u32_e32 v220, s48, v237
	v_cmp_lt_i32_e32 vcc, 0, v220
	s_nop 1
	v_cndmask_b32_e32 v176, 0, v176, vcc
	v_cndmask_b32_e32 v177, 0, v177, vcc
	v_cmp_gt_i32_e32 vcc, s28, v220
	s_nop 1
	v_cndmask_b32_e32 v196, 0, v196, vcc
	v_cndmask_b32_e32 v197, 0, v197, vcc
	v_pk_fma_f32 v[202:203], v[108:109], v[176:177], v[120:121]
	v_pk_fma_f32 v[80:81], v[80:81], v[112:113], v[202:203]
	v_pk_fma_f32 v[80:81], v[116:117], v[196:197], v[80:81]
	ds_read_b64 v[176:177], v244 offset:1536
	ds_read_b64 v[196:197], v243 offset:1568
	ds_read_b64 v[200:201], v246 offset:32
	ds_write_b64 v243, v[100:101]
	ds_write_b64 v243, v[92:93] offset:512
	ds_write_b64 v243, v[84:85] offset:1024
	ds_write_b64 v243, v[76:77] offset:1536
	s_waitcnt lgkmcnt(11)
	v_cndmask_b32_e64 v170, v170, v198, s[6:7]
	v_cndmask_b32_e64 v171, v171, v199, s[6:7]
	v_add_u32_e32 v220, s48, v234
	v_cmp_lt_i32_e32 vcc, 0, v220
	s_nop 1
	v_cndmask_b32_e32 v170, 0, v170, vcc
	v_cndmask_b32_e32 v171, 0, v171, vcc
	v_cmp_gt_i32_e32 vcc, s28, v220
	s_nop 1
	v_cndmask_b32_e32 v178, 0, v178, vcc
	v_cndmask_b32_e32 v179, 0, v179, vcc
	v_pk_fma_f32 v[202:203], v[122:123], v[170:171], v[134:135]
	v_pk_fma_f32 v[98:99], v[98:99], v[126:127], v[202:203]
	v_pk_fma_f32 v[98:99], v[130:131], v[178:179], v[98:99]
	ds_read_b64 v[170:171], v244
	ds_read_b64 v[178:179], v243 offset:32
	ds_read_b64 v[198:199], v238 offset:3112
	s_waitcnt lgkmcnt(12)
	v_add_u32_e32 v220, s48, v235
	v_cmp_lt_i32_e32 vcc, 0, v220
	s_nop 1
	v_cndmask_b32_e32 v172, 0, v172, vcc
	v_cndmask_b32_e32 v173, 0, v173, vcc
	v_cmp_gt_i32_e32 vcc, s28, v220
	s_nop 1
	v_cndmask_b32_e32 v180, 0, v180, vcc
	v_cndmask_b32_e32 v181, 0, v181, vcc
	v_pk_fma_f32 v[202:203], v[122:123], v[172:173], v[134:135]
	v_pk_fma_f32 v[90:91], v[90:91], v[126:127], v[202:203]
	v_pk_fma_f32 v[90:91], v[130:131], v[180:181], v[90:91]
	ds_read_b64 v[172:173], v244 offset:512
	ds_read_b64 v[180:181], v243 offset:544
	s_waitcnt lgkmcnt(12)
; #define PG8_LAS __attribute__((address_space(3)))
; __device__ __forceinline__ unsigned cvt_pk_bf16(float lo, float hi) { unsigned r; asm volatile("v_cvt_pk_bf16_f32 %0, %1, %2" : "=v"(r) : "v"(lo), "v"(hi)); return r; }
;     __device__ __forceinline__ void operator()(const f32x4 (&acc)[2][2][4][2], const Unit& u, int wr, int wc, int fr, int fq) const {
;     ...
;                 for (int m = 0; m < 4; ++m) { const int r = 128 * ai + 64 * wr + 16 * m + fr, t = tstart + r;
;                     const bool upok = t >= 1, dnok = (t + 1) < T, store_ok = (r >= vlo) && (r < vhi) && (t < T);
;                     f32x4 res[2];
; #pragma unroll
;                     for (int bj = 0; bj < 2; ++bj) { const f32x4 cur = acc[ai][bj][m][n];
;                         f32x4 su = cur, sd = cur;
;                         if (m > 0) { if (fr == 15) su = acc[ai][bj][m > 0 ? m - 1 : 0][n]; }
;                         if (m < 3) { if (fr == 0) sd = acc[ai][bj][m < 3 ? m + 1 : 3][n]; }
;                         f32x4 up, dn;
;                         up[0] = dpp_ror1(su[0]); up[1] = dpp_ror1(su[1]); up[2] = dpp_ror1(su[2]); up[3] = dpp_ror1(su[3]);
;                         dn[0] = dpp_ror15(sd[0]); dn[1] = dpp_ror15(sd[1]); dn[2] = dpp_ror15(sd[2]); dn[3] = dpp_ror15(sd[3]);
;                         if (m == 0) { f32x4 halo = zero4; if (blk > 0) halo = *(const PG8_LAS f32x4*)(xb + (((((blk - 1) * 2 + 1) * 4 + wc) * 4 + fq) * 16 + (bj * 2 + n) * 4)); if (fr == 0) up = halo; }
;                         if (m == 3) { f32x4 halo = zero4; if (blk < 3) halo = *(const PG8_LAS f32x4*)(xb + (((((blk + 1) * 2 + 0) * 4 + wc) * 4 + fq) * 16 + (bj * 2 + n) * 4)); if (fr == 15) dn = halo; }
;                         if (edge) { if (!upok) up = zero4; if (!dnok) dn = zero4; }
;                         res[bj] = bb[bj] + w0[bj] * up + w1[bj] * cur + w2[bj] * dn; }
;                     if (store_ok) {
;                         float o[4];
; #pragma unroll
;                         for (int j = 0; j < 4; ++j) { const float gg = res[1][j]; o[j] = gg * __builtin_amdgcn_rcpf(1.f + __expf(-gg)) * res[0][j]; }
;                         u32x2 w; w.x = cvt_pk_bf16(o[0], o[1]); w.y = cvt_pk_bf16(o[2], o[3]);
;                         *(u32x2*)(ACT + (size_t)(seqrow + t) * 2816 + ch0 + 4 * n) = w; } } }
	v_add_u32_e32 v220, s48, v236
	v_cmp_lt_i32_e32 vcc, 0, v220
	s_nop 1
	v_cndmask_b32_e32 v174, 0, v174, vcc
	v_cndmask_b32_e32 v175, 0, v175, vcc
	v_cmp_gt_i32_e32 vcc, s28, v220
	s_nop 1
	v_cndmask_b32_e32 v194, 0, v194, vcc
	v_cndmask_b32_e32 v195, 0, v195, vcc
	v_pk_fma_f32 v[202:203], v[122:123], v[174:175], v[134:135]
	v_pk_fma_f32 v[82:83], v[82:83], v[126:127], v[202:203]
	v_pk_fma_f32 v[82:83], v[130:131], v[194:195], v[82:83]
	ds_read_b64 v[174:175], v244 offset:1024
	ds_read_b64 v[194:195], v243 offset:1056
	s_waitcnt lgkmcnt(11)
	v_cndmask_b32_e64 v196, v196, v200, s[4:5]
	v_cndmask_b32_e64 v197, v197, v201, s[4:5]
	v_add_u32_e32 v220, s48, v237
	v_cmp_lt_i32_e32 vcc, 0, v220
	s_nop 1
	v_cndmask_b32_e32 v176, 0, v176, vcc
	v_cndmask_b32_e32 v177, 0, v177, vcc
	v_cmp_gt_i32_e32 vcc, s28, v220
	s_nop 1
	v_cndmask_b32_e32 v196, 0, v196, vcc
	v_cndmask_b32_e32 v197, 0, v197, vcc
	v_pk_fma_f32 v[202:203], v[122:123], v[176:177], v[134:135]
	v_pk_fma_f32 v[74:75], v[74:75], v[126:127], v[202:203]
	v_pk_fma_f32 v[74:75], v[130:131], v[196:197], v[74:75]
	ds_read_b64 v[176:177], v244 offset:1536
	ds_read_b64 v[196:197], v243 offset:1568
	ds_read_b64 v[200:201], v246 offset:40
	ds_write_b64 v243, v[70:71]
	ds_write_b64 v243, v[62:63] offset:512
	ds_write_b64 v243, v[54:55] offset:1024
	ds_write_b64 v243, v[46:47] offset:1536
	s_waitcnt lgkmcnt(11)
	v_cndmask_b32_e64 v170, v170, v198, s[6:7]
	v_cndmask_b32_e64 v171, v171, v199, s[6:7]
	v_add_u32_e32 v220, s48, v234
	v_cmp_lt_i32_e32 vcc, 0, v220
	s_nop 1
	v_cndmask_b32_e32 v170, 0, v170, vcc
	v_cndmask_b32_e32 v171, 0, v171, vcc
	v_cmp_gt_i32_e32 vcc, s28, v220
	s_nop 1
	v_cndmask_b32_e32 v178, 0, v178, vcc
	v_cndmask_b32_e32 v179, 0, v179, vcc
	v_pk_fma_f32 v[202:203], v[124:125], v[170:171], v[136:137]
	v_pk_fma_f32 v[100:101], v[100:101], v[128:129], v[202:203]
	v_pk_fma_f32 v[100:101], v[132:133], v[178:179], v[100:101]
	ds_read_b64 v[170:171], v244
	ds_read_b64 v[178:179], v243 offset:32
	ds_read_b64 v[198:199], v245 offset:16
	s_waitcnt lgkmcnt(12)
	v_add_u32_e32 v220, s48, v235
	v_cmp_lt_i32_e32 vcc, 0, v220
	s_nop 1
	v_cndmask_b32_e32 v172, 0, v172, vcc
	v_cndmask_b32_e32 v173, 0, v173, vcc
	v_cmp_gt_i32_e32 vcc, s28, v220
	s_nop 1
	v_cndmask_b32_e32 v180, 0, v180, vcc
	v_cndmask_b32_e32 v181, 0, v181, vcc
	v_pk_fma_f32 v[202:203], v[124:125], v[172:173], v[136:137]
	v_pk_fma_f32 v[92:93], v[92:93], v[128:129], v[202:203]
	v_pk_fma_f32 v[92:93], v[132:133], v[180:181], v[92:93]
	ds_read_b64 v[172:173], v244 offset:512
	ds_read_b64 v[180:181], v243 offset:544
	s_waitcnt lgkmcnt(12)
	v_add_u32_e32 v220, s48, v236
	v_cmp_lt_i32_e32 vcc, 0, v220
	s_nop 1
	v_cndmask_b32_e32 v174, 0, v174, vcc
	v_cndmask_b32_e32 v175, 0, v175, vcc
	v_cmp_gt_i32_e32 vcc, s28, v220
	s_nop 1
	v_cndmask_b32_e32 v194, 0, v194, vcc
	v_cndmask_b32_e32 v195, 0, v195, vcc
	v_pk_fma_f32 v[202:203], v[124:125], v[174:175], v[136:137]
	v_pk_fma_f32 v[84:85], v[84:85], v[128:129], v[202:203]
	v_pk_fma_f32 v[84:85], v[132:133], v[194:195], v[84:85]
	ds_read_b64 v[174:175], v244 offset:1024
	ds_read_b64 v[194:195], v243 offset:1056
	s_waitcnt lgkmcnt(11)
	v_cndmask_b32_e64 v196, v196, v200, s[4:5]
	v_cndmask_b32_e64 v197, v197, v201, s[4:5]
	v_add_u32_e32 v220, s48, v237
	v_cmp_lt_i32_e32 vcc, 0, v220
	s_nop 1
	v_cndmask_b32_e32 v176, 0, v176, vcc
	v_cndmask_b32_e32 v177, 0, v177, vcc
	v_cmp_gt_i32_e32 vcc, s28, v220
	s_nop 1
	v_cndmask_b32_e32 v196, 0, v196, vcc
	v_cndmask_b32_e32 v197, 0, v197, vcc
	v_pk_fma_f32 v[202:203], v[124:125], v[176:177], v[136:137]
	v_pk_fma_f32 v[76:77], v[76:77], v[128:129], v[202:203]
	v_pk_fma_f32 v[76:77], v[132:133], v[196:197], v[76:77]
	ds_read_b64 v[176:177], v244 offset:1536
	ds_read_b64 v[196:197], v243 offset:1568
	ds_read_b64 v[200:201], v238 offset:2064
	v_mul_f32_e32 v208, 0xbfb8aa3b, v98
	v_mul_f32_e32 v209, 0xbfb8aa3b, v99
	v_mul_f32_e32 v210, 0xbfb8aa3b, v100
	v_mul_f32_e32 v211, 0xbfb8aa3b, v101
	v_exp_f32_e32 v208, v208
	v_exp_f32_e32 v209, v209
	v_exp_f32_e32 v210, v210
	v_exp_f32_e32 v211, v211
	v_add_f32_e32 v208, 1.0, v208
	v_add_f32_e32 v209, 1.0, v209
	v_add_f32_e32 v210, 1.0, v210
	v_add_f32_e32 v211, 1.0, v211
	v_rcp_f32_e32 v208, v208
	v_rcp_f32_e32 v209, v209
	v_rcp_f32_e32 v210, v210
	v_rcp_f32_e32 v211, v211
	v_mul_f32_e32 v98, v98, v208
	v_mul_f32_e32 v99, v99, v209
	v_mul_f32_e32 v100, v100, v210
	v_mul_f32_e32 v101, v101, v211
	v_mul_f32_e32 v98, v102, v98
	v_mul_f32_e32 v99, v103, v99
	v_mul_f32_e32 v100, v104, v100
	v_mul_f32_e32 v101, v105, v101
	v_cvt_pk_bf16_f32 v212, v98, v99
	v_cvt_pk_bf16_f32 v213, v100, v101
	v_mad_u32_u24 v221, v234, s29, v247
	s_and_saveexec_b64 s[30:31], s[20:21]
	global_store_dwordx2 v221, v[212:213], s[10:11]
	s_mov_b64 exec, s[30:31]
	v_mul_f32_e32 v208, 0xbfb8aa3b, v90
	v_mul_f32_e32 v209, 0xbfb8aa3b, v91
	v_mul_f32_e32 v210, 0xbfb8aa3b, v92
	v_mul_f32_e32 v211, 0xbfb8aa3b, v93
	v_exp_f32_e32 v208, v208
	v_exp_f32_e32 v209, v209
	v_exp_f32_e32 v210, v210
	v_exp_f32_e32 v211, v211
	v_add_f32_e32 v208, 1.0, v208
	v_add_f32_e32 v209, 1.0, v209
	v_add_f32_e32 v210, 1.0, v210
	v_add_f32_e32 v211, 1.0, v211
	v_rcp_f32_e32 v208, v208
	v_rcp_f32_e32 v209, v209
	v_rcp_f32_e32 v210, v210
	v_rcp_f32_e32 v211, v211
	v_mul_f32_e32 v90, v90, v208
	v_mul_f32_e32 v91, v91, v209
	v_mul_f32_e32 v92, v92, v210
	v_mul_f32_e32 v93, v93, v211
	v_mul_f32_e32 v90, v94, v90
	v_mul_f32_e32 v91, v95, v91
	v_mul_f32_e32 v92, v96, v92
	v_mul_f32_e32 v93, v97, v93
	v_cvt_pk_bf16_f32 v218, v90, v91
	v_cvt_pk_bf16_f32 v219, v92, v93
	v_mad_u32_u24 v40, v235, s29, v247
	s_and_saveexec_b64 s[30:31], s[22:23]
	global_store_dwordx2 v40, v[218:219], s[10:11]
; #define PG8_LAS __attribute__((address_space(3)))
; __device__ __forceinline__ unsigned cvt_pk_bf16(float lo, float hi) { unsigned r; asm volatile("v_cvt_pk_bf16_f32 %0, %1, %2" : "=v"(r) : "v"(lo), "v"(hi)); return r; }
;     __device__ __forceinline__ void operator()(const f32x4 (&acc)[2][2][4][2], const Unit& u, int wr, int wc, int fr, int fq) const {
;     ...
;                 for (int m = 0; m < 4; ++m) { const int r = 128 * ai + 64 * wr + 16 * m + fr, t = tstart + r;
;                     const bool upok = t >= 1, dnok = (t + 1) < T, store_ok = (r >= vlo) && (r < vhi) && (t < T);
;                     f32x4 res[2];
; #pragma unroll
;                     for (int bj = 0; bj < 2; ++bj) { const f32x4 cur = acc[ai][bj][m][n];
;                         f32x4 su = cur, sd = cur;
;                         if (m > 0) { if (fr == 15) su = acc[ai][bj][m > 0 ? m - 1 : 0][n]; }
;                         if (m < 3) { if (fr == 0) sd = acc[ai][bj][m < 3 ? m + 1 : 3][n]; }
;                         f32x4 up, dn;
;                         up[0] = dpp_ror1(su[0]); up[1] = dpp_ror1(su[1]); up[2] = dpp_ror1(su[2]); up[3] = dpp_ror1(su[3]);
;                         dn[0] = dpp_ror15(sd[0]); dn[1] = dpp_ror15(sd[1]); dn[2] = dpp_ror15(sd[2]); dn[3] = dpp_ror15(sd[3]);
;                         if (m == 0) { f32x4 halo = zero4; if (blk > 0) halo = *(const PG8_LAS f32x4*)(xb + (((((blk - 1) * 2 + 1) * 4 + wc) * 4 + fq) * 16 + (bj * 2 + n) * 4)); if (fr == 0) up = halo; }
;                         if (m == 3) { f32x4 halo = zero4; if (blk < 3) halo = *(const PG8_LAS f32x4*)(xb + (((((blk + 1) * 2 + 0) * 4 + wc) * 4 + fq) * 16 + (bj * 2 + n) * 4)); if (fr == 15) dn = halo; }
;                         if (edge) { if (!upok) up = zero4; if (!dnok) dn = zero4; }
;                         res[bj] = bb[bj] + w0[bj] * up + w1[bj] * cur + w2[bj] * dn; }
;                     if (store_ok) {
;                         float o[4];
; #pragma unroll
;                         for (int j = 0; j < 4; ++j) { const float gg = res[1][j]; o[j] = gg * __builtin_amdgcn_rcpf(1.f + __expf(-gg)) * res[0][j]; }
;                         u32x2 w; w.x = cvt_pk_bf16(o[0], o[1]); w.y = cvt_pk_bf16(o[2], o[3]);
;                         *(u32x2*)(ACT + (size_t)(seqrow + t) * 2816 + ch0 + 4 * n) = w; } } }
	s_mov_b64 exec, s[30:31]
	v_mul_f32_e32 v208, 0xbfb8aa3b, v82
	v_mul_f32_e32 v209, 0xbfb8aa3b, v83
	v_mul_f32_e32 v210, 0xbfb8aa3b, v84
	v_mul_f32_e32 v211, 0xbfb8aa3b, v85
	v_exp_f32_e32 v208, v208
	v_exp_f32_e32 v209, v209
	v_exp_f32_e32 v210, v210
	v_exp_f32_e32 v211, v211
	v_add_f32_e32 v208, 1.0, v208
	v_add_f32_e32 v209, 1.0, v209
	v_add_f32_e32 v210, 1.0, v210
	v_add_f32_e32 v211, 1.0, v211
	v_rcp_f32_e32 v208, v208
	v_rcp_f32_e32 v209, v209
	v_rcp_f32_e32 v210, v210
	v_rcp_f32_e32 v211, v211
	v_mul_f32_e32 v82, v82, v208
	v_mul_f32_e32 v83, v83, v209
	v_mul_f32_e32 v84, v84, v210
	v_mul_f32_e32 v85, v85, v211
	v_mul_f32_e32 v82, v86, v82
	v_mul_f32_e32 v83, v87, v83
	v_mul_f32_e32 v84, v88, v84
	v_mul_f32_e32 v85, v89, v85
	v_cvt_pk_bf16_f32 v212, v82, v83
	v_cvt_pk_bf16_f32 v213, v84, v85
	v_mad_u32_u24 v221, v236, s29, v247
	s_and_saveexec_b64 s[30:31], s[24:25]
	global_store_dwordx2 v221, v[212:213], s[10:11]
	s_mov_b64 exec, s[30:31]
	v_mul_f32_e32 v208, 0xbfb8aa3b, v74
	v_mul_f32_e32 v209, 0xbfb8aa3b, v75
	v_mul_f32_e32 v210, 0xbfb8aa3b, v76
	v_mul_f32_e32 v211, 0xbfb8aa3b, v77
	v_exp_f32_e32 v208, v208
	v_exp_f32_e32 v209, v209
	v_exp_f32_e32 v210, v210
	v_exp_f32_e32 v211, v211
	v_add_f32_e32 v208, 1.0, v208
	v_add_f32_e32 v209, 1.0, v209
	v_add_f32_e32 v210, 1.0, v210
	v_add_f32_e32 v211, 1.0, v211
	v_rcp_f32_e32 v208, v208
	v_rcp_f32_e32 v209, v209
	v_rcp_f32_e32 v210, v210
	v_rcp_f32_e32 v211, v211
	v_mul_f32_e32 v74, v74, v208
	v_mul_f32_e32 v75, v75, v209
	v_mul_f32_e32 v76, v76, v210
	v_mul_f32_e32 v77, v77, v211
	v_mul_f32_e32 v74, v78, v74
	v_mul_f32_e32 v75, v79, v75
	v_mul_f32_e32 v76, v80, v76
	v_mul_f32_e32 v77, v81, v77
	v_cvt_pk_bf16_f32 v218, v74, v75
	v_cvt_pk_bf16_f32 v219, v76, v77
	v_mad_u32_u24 v40, v237, s29, v247
	s_and_saveexec_b64 s[30:31], s[26:27]
	global_store_dwordx2 v40, v[218:219], s[10:11]
	s_mov_b64 exec, s[30:31]
	s_waitcnt vmcnt(4)
	ds_write_b64 v243, v[72:73]
	ds_write_b64 v243, v[64:65] offset:512
	ds_write_b64 v243, v[56:57] offset:1024
	ds_write_b64 v243, v[48:49] offset:1536
	s_waitcnt lgkmcnt(11)
	v_cndmask_b32_e64 v170, v170, v198, s[6:7]
	v_cndmask_b32_e64 v171, v171, v199, s[6:7]
	v_add_u32_e32 v220, s48, v227
	v_cmp_lt_i32_e32 vcc, 0, v220
	s_nop 1
	v_cndmask_b32_e32 v170, 0, v170, vcc
	v_cndmask_b32_e32 v171, 0, v171, vcc
	v_cmp_gt_i32_e32 vcc, s28, v220
	s_nop 1
	v_cndmask_b32_e32 v178, 0, v178, vcc
	v_cndmask_b32_e32 v179, 0, v179, vcc
	v_pk_fma_f32 v[202:203], v[138:139], v[170:171], v[150:151]
	v_pk_fma_f32 v[70:71], v[70:71], v[142:143], v[202:203]
	v_pk_fma_f32 v[70:71], v[146:147], v[178:179], v[70:71]
	ds_read_b64 v[170:171], v244
	ds_read_b64 v[178:179], v243 offset:32
	ds_read_b64 v[198:199], v245 offset:24
	s_waitcnt lgkmcnt(12)
	v_add_u32_e32 v220, s48, v231
	v_cmp_lt_i32_e32 vcc, 0, v220
	s_nop 1
	v_cndmask_b32_e32 v172, 0, v172, vcc
	v_cndmask_b32_e32 v173, 0, v173, vcc
	v_cmp_gt_i32_e32 vcc, s28, v220
	s_nop 1
	v_cndmask_b32_e32 v180, 0, v180, vcc
	v_cndmask_b32_e32 v181, 0, v181, vcc
	v_pk_fma_f32 v[202:203], v[138:139], v[172:173], v[150:151]
	v_pk_fma_f32 v[62:63], v[62:63], v[142:143], v[202:203]
	v_pk_fma_f32 v[62:63], v[146:147], v[180:181], v[62:63]
	ds_read_b64 v[172:173], v244 offset:512
	ds_read_b64 v[180:181], v243 offset:544
	s_waitcnt lgkmcnt(12)
	v_add_u32_e32 v220, s48, v232
	v_cmp_lt_i32_e32 vcc, 0, v220
	s_nop 1
	v_cndmask_b32_e32 v174, 0, v174, vcc
	v_cndmask_b32_e32 v175, 0, v175, vcc
	v_cmp_gt_i32_e32 vcc, s28, v220
	s_nop 1
	v_cndmask_b32_e32 v194, 0, v194, vcc
	v_cndmask_b32_e32 v195, 0, v195, vcc
	v_pk_fma_f32 v[202:203], v[138:139], v[174:175], v[150:151]
	v_pk_fma_f32 v[54:55], v[54:55], v[142:143], v[202:203]
	v_pk_fma_f32 v[54:55], v[146:147], v[194:195], v[54:55]
	ds_read_b64 v[174:175], v244 offset:1024
	ds_read_b64 v[194:195], v243 offset:1056
	s_waitcnt lgkmcnt(11)
	v_cndmask_b32_e64 v196, v196, v200, s[4:5]
	v_cndmask_b32_e64 v197, v197, v201, s[4:5]
	v_add_u32_e32 v220, s48, v233
	v_cmp_lt_i32_e32 vcc, 0, v220
	s_nop 1
	v_cndmask_b32_e32 v176, 0, v176, vcc
	v_cndmask_b32_e32 v177, 0, v177, vcc
	v_cmp_gt_i32_e32 vcc, s28, v220
	s_nop 1
	v_cndmask_b32_e32 v196, 0, v196, vcc
	v_cndmask_b32_e32 v197, 0, v197, vcc
	v_pk_fma_f32 v[202:203], v[138:139], v[176:177], v[150:151]
	v_pk_fma_f32 v[46:47], v[46:47], v[142:143], v[202:203]
	v_pk_fma_f32 v[46:47], v[146:147], v[196:197], v[46:47]
	ds_read_b64 v[176:177], v244 offset:1536
	ds_read_b64 v[196:197], v243 offset:1568
	ds_read_b64 v[200:201], v238 offset:2072
	ds_write_b64 v243, v[66:67]
	ds_write_b64 v243, v[58:59] offset:512
	ds_write_b64 v243, v[50:51] offset:1024
	ds_write_b64 v243, v[42:43] offset:1536
	s_waitcnt lgkmcnt(11)
	v_cndmask_b32_e64 v170, v170, v198, s[6:7]
	v_cndmask_b32_e64 v171, v171, v199, s[6:7]
	v_add_u32_e32 v220, s48, v227
	v_cmp_lt_i32_e32 vcc, 0, v220
	s_nop 1
	v_cndmask_b32_e32 v170, 0, v170, vcc
	v_cndmask_b32_e32 v171, 0, v171, vcc
	v_cmp_gt_i32_e32 vcc, s28, v220
	s_nop 1
	v_cndmask_b32_e32 v178, 0, v178, vcc
	v_cndmask_b32_e32 v179, 0, v179, vcc
	v_pk_fma_f32 v[202:203], v[140:141], v[170:171], v[152:153]
	v_pk_fma_f32 v[72:73], v[72:73], v[144:145], v[202:203]
	v_pk_fma_f32 v[72:73], v[148:149], v[178:179], v[72:73]
	ds_read_b64 v[170:171], v244
	ds_read_b64 v[178:179], v243 offset:32
	ds_read_b64 v[198:199], v245 offset:48
	s_waitcnt lgkmcnt(12)
	v_add_u32_e32 v220, s48, v231
	v_cmp_lt_i32_e32 vcc, 0, v220
	s_nop 1
	v_cndmask_b32_e32 v172, 0, v172, vcc
	v_cndmask_b32_e32 v173, 0, v173, vcc
	v_cmp_gt_i32_e32 vcc, s28, v220
	s_nop 1
	v_cndmask_b32_e32 v180, 0, v180, vcc
	v_cndmask_b32_e32 v181, 0, v181, vcc
	v_pk_fma_f32 v[202:203], v[140:141], v[172:173], v[152:153]
	v_pk_fma_f32 v[64:65], v[64:65], v[144:145], v[202:203]
	v_pk_fma_f32 v[64:65], v[148:149], v[180:181], v[64:65]
	ds_read_b64 v[172:173], v244 offset:512
	ds_read_b64 v[180:181], v243 offset:544
	s_waitcnt lgkmcnt(12)
; #define PG8_LAS __attribute__((address_space(3)))
; __device__ __forceinline__ unsigned cvt_pk_bf16(float lo, float hi) { unsigned r; asm volatile("v_cvt_pk_bf16_f32 %0, %1, %2" : "=v"(r) : "v"(lo), "v"(hi)); return r; }
;     __device__ __forceinline__ void operator()(const f32x4 (&acc)[2][2][4][2], const Unit& u, int wr, int wc, int fr, int fq) const {
;     ...
;                 for (int m = 0; m < 4; ++m) { const int r = 128 * ai + 64 * wr + 16 * m + fr, t = tstart + r;
;                     const bool upok = t >= 1, dnok = (t + 1) < T, store_ok = (r >= vlo) && (r < vhi) && (t < T);
;                     f32x4 res[2];
; #pragma unroll
;                     for (int bj = 0; bj < 2; ++bj) { const f32x4 cur = acc[ai][bj][m][n];
;                         f32x4 su = cur, sd = cur;
;                         if (m > 0) { if (fr == 15) su = acc[ai][bj][m > 0 ? m - 1 : 0][n]; }
;                         if (m < 3) { if (fr == 0) sd = acc[ai][bj][m < 3 ? m + 1 : 3][n]; }
;                         f32x4 up, dn;
;                         up[0] = dpp_ror1(su[0]); up[1] = dpp_ror1(su[1]); up[2] = dpp_ror1(su[2]); up[3] = dpp_ror1(su[3]);
;                         dn[0] = dpp_ror15(sd[0]); dn[1] = dpp_ror15(sd[1]); dn[2] = dpp_ror15(sd[2]); dn[3] = dpp_ror15(sd[3]);
;                         if (m == 0) { f32x4 halo = zero4; if (blk > 0) halo = *(const PG8_LAS f32x4*)(xb + (((((blk - 1) * 2 + 1) * 4 + wc) * 4 + fq) * 16 + (bj * 2 + n) * 4)); if (fr == 0) up = halo; }
;                         if (m == 3) { f32x4 halo = zero4; if (blk < 3) halo = *(const PG8_LAS f32x4*)(xb + (((((blk + 1) * 2 + 0) * 4 + wc) * 4 + fq) * 16 + (bj * 2 + n) * 4)); if (fr == 15) dn = halo; }
;                         if (edge) { if (!upok) up = zero4; if (!dnok) dn = zero4; }
;                         res[bj] = bb[bj] + w0[bj] * up + w1[bj] * cur + w2[bj] * dn; }
;                     if (store_ok) {
;                         float o[4];
; #pragma unroll
;                         for (int j = 0; j < 4; ++j) { const float gg = res[1][j]; o[j] = gg * __builtin_amdgcn_rcpf(1.f + __expf(-gg)) * res[0][j]; }
;                         u32x2 w; w.x = cvt_pk_bf16(o[0], o[1]); w.y = cvt_pk_bf16(o[2], o[3]);
;                         *(u32x2*)(ACT + (size_t)(seqrow + t) * 2816 + ch0 + 4 * n) = w; } } }
	v_add_u32_e32 v220, s48, v232
	v_cmp_lt_i32_e32 vcc, 0, v220
	s_nop 1
	v_cndmask_b32_e32 v174, 0, v174, vcc
	v_cndmask_b32_e32 v175, 0, v175, vcc
	v_cmp_gt_i32_e32 vcc, s28, v220
	s_nop 1
	v_cndmask_b32_e32 v194, 0, v194, vcc
	v_cndmask_b32_e32 v195, 0, v195, vcc
	v_pk_fma_f32 v[202:203], v[140:141], v[174:175], v[152:153]
	v_pk_fma_f32 v[56:57], v[56:57], v[144:145], v[202:203]
	v_pk_fma_f32 v[56:57], v[148:149], v[194:195], v[56:57]
	ds_read_b64 v[174:175], v244 offset:1024
	ds_read_b64 v[194:195], v243 offset:1056
	s_waitcnt lgkmcnt(11)
	v_cndmask_b32_e64 v196, v196, v200, s[4:5]
	v_cndmask_b32_e64 v197, v197, v201, s[4:5]
	v_add_u32_e32 v220, s48, v233
	v_cmp_lt_i32_e32 vcc, 0, v220
	s_nop 1
	v_cndmask_b32_e32 v176, 0, v176, vcc
	v_cndmask_b32_e32 v177, 0, v177, vcc
	v_cmp_gt_i32_e32 vcc, s28, v220
	s_nop 1
	v_cndmask_b32_e32 v196, 0, v196, vcc
	v_cndmask_b32_e32 v197, 0, v197, vcc
	v_pk_fma_f32 v[202:203], v[140:141], v[176:177], v[152:153]
	v_pk_fma_f32 v[48:49], v[48:49], v[144:145], v[202:203]
	v_pk_fma_f32 v[48:49], v[148:149], v[196:197], v[48:49]
	ds_read_b64 v[176:177], v244 offset:1536
	ds_read_b64 v[196:197], v243 offset:1568
	ds_read_b64 v[200:201], v238 offset:2096
	ds_write_b64 v243, v[68:69]
	ds_write_b64 v243, v[60:61] offset:512
	ds_write_b64 v243, v[52:53] offset:1024
	ds_write_b64 v243, v[44:45] offset:1536
	s_waitcnt lgkmcnt(11)
	v_cndmask_b32_e64 v170, v170, v198, s[6:7]
	v_cndmask_b32_e64 v171, v171, v199, s[6:7]
	v_add_u32_e32 v220, s48, v227
	v_cmp_lt_i32_e32 vcc, 0, v220
	s_nop 1
	v_cndmask_b32_e32 v170, 0, v170, vcc
	v_cndmask_b32_e32 v171, 0, v171, vcc
	v_cmp_gt_i32_e32 vcc, s28, v220
	s_nop 1
	v_cndmask_b32_e32 v178, 0, v178, vcc
	v_cndmask_b32_e32 v179, 0, v179, vcc
	v_pk_fma_f32 v[202:203], v[154:155], v[170:171], v[166:167]
	v_pk_fma_f32 v[66:67], v[66:67], v[158:159], v[202:203]
	v_pk_fma_f32 v[66:67], v[162:163], v[178:179], v[66:67]
	ds_read_b64 v[170:171], v244
	ds_read_b64 v[178:179], v243 offset:32
	ds_read_b64 v[198:199], v245 offset:56
	s_waitcnt lgkmcnt(12)
	v_add_u32_e32 v220, s48, v231
	v_cmp_lt_i32_e32 vcc, 0, v220
	s_nop 1
	v_cndmask_b32_e32 v172, 0, v172, vcc
	v_cndmask_b32_e32 v173, 0, v173, vcc
	v_cmp_gt_i32_e32 vcc, s28, v220
	s_nop 1
	v_cndmask_b32_e32 v180, 0, v180, vcc
	v_cndmask_b32_e32 v181, 0, v181, vcc
	v_pk_fma_f32 v[202:203], v[154:155], v[172:173], v[166:167]
	v_pk_fma_f32 v[58:59], v[58:59], v[158:159], v[202:203]
	v_pk_fma_f32 v[58:59], v[162:163], v[180:181], v[58:59]
	ds_read_b64 v[172:173], v244 offset:512
	ds_read_b64 v[180:181], v243 offset:544
	s_waitcnt lgkmcnt(12)
	v_add_u32_e32 v220, s48, v232
	v_cmp_lt_i32_e32 vcc, 0, v220
	s_nop 1
	v_cndmask_b32_e32 v174, 0, v174, vcc
	v_cndmask_b32_e32 v175, 0, v175, vcc
	v_cmp_gt_i32_e32 vcc, s28, v220
	s_nop 1
	v_cndmask_b32_e32 v194, 0, v194, vcc
	v_cndmask_b32_e32 v195, 0, v195, vcc
	v_pk_fma_f32 v[202:203], v[154:155], v[174:175], v[166:167]
	v_pk_fma_f32 v[50:51], v[50:51], v[158:159], v[202:203]
	v_pk_fma_f32 v[50:51], v[162:163], v[194:195], v[50:51]
	ds_read_b64 v[174:175], v244 offset:1024
	ds_read_b64 v[194:195], v243 offset:1056
	s_waitcnt lgkmcnt(11)
	v_cndmask_b32_e64 v196, v196, v200, s[4:5]
	v_cndmask_b32_e64 v197, v197, v201, s[4:5]
	v_add_u32_e32 v220, s48, v233
	v_cmp_lt_i32_e32 vcc, 0, v220
	s_nop 1
	v_cndmask_b32_e32 v176, 0, v176, vcc
	v_cndmask_b32_e32 v177, 0, v177, vcc
	v_cmp_gt_i32_e32 vcc, s28, v220
	s_nop 1
	v_cndmask_b32_e32 v196, 0, v196, vcc
	v_cndmask_b32_e32 v197, 0, v197, vcc
	v_pk_fma_f32 v[202:203], v[154:155], v[176:177], v[166:167]
	v_pk_fma_f32 v[42:43], v[42:43], v[158:159], v[202:203]
	v_pk_fma_f32 v[42:43], v[162:163], v[196:197], v[42:43]
	ds_read_b64 v[176:177], v244 offset:1536
	ds_read_b64 v[196:197], v243 offset:1568
	ds_read_b64 v[200:201], v238 offset:2104
	ds_write_b64 v243, v[30:31]
	ds_write_b64 v243, v[22:23] offset:512
	ds_write_b64 v243, v[14:15] offset:1024
	ds_write_b64 v243, v[6:7] offset:1536
	s_waitcnt lgkmcnt(11)
	v_cndmask_b32_e64 v170, v170, v198, s[6:7]
	v_cndmask_b32_e64 v171, v171, v199, s[6:7]
	v_add_u32_e32 v220, s48, v227
	v_cmp_lt_i32_e32 vcc, 0, v220
	s_nop 1
	v_cndmask_b32_e32 v170, 0, v170, vcc
	v_cndmask_b32_e32 v171, 0, v171, vcc
	v_cmp_gt_i32_e32 vcc, s28, v220
	s_nop 1
	v_cndmask_b32_e32 v178, 0, v178, vcc
	v_cndmask_b32_e32 v179, 0, v179, vcc
	v_pk_fma_f32 v[202:203], v[156:157], v[170:171], v[168:169]
	v_pk_fma_f32 v[68:69], v[68:69], v[160:161], v[202:203]
	v_pk_fma_f32 v[68:69], v[164:165], v[178:179], v[68:69]
	ds_read_b64 v[170:171], v244
	ds_read_b64 v[178:179], v243 offset:32
	ds_read_b64 v[198:199], v238 offset:3088
	s_waitcnt lgkmcnt(12)
	v_add_u32_e32 v220, s48, v231
	v_cmp_lt_i32_e32 vcc, 0, v220
	s_nop 1
	v_cndmask_b32_e32 v172, 0, v172, vcc
	v_cndmask_b32_e32 v173, 0, v173, vcc
	v_cmp_gt_i32_e32 vcc, s28, v220
	s_nop 1
	v_cndmask_b32_e32 v180, 0, v180, vcc
	v_cndmask_b32_e32 v181, 0, v181, vcc
	v_pk_fma_f32 v[202:203], v[156:157], v[172:173], v[168:169]
	v_pk_fma_f32 v[60:61], v[60:61], v[160:161], v[202:203]
	v_pk_fma_f32 v[60:61], v[164:165], v[180:181], v[60:61]
	ds_read_b64 v[172:173], v244 offset:512
	ds_read_b64 v[180:181], v243 offset:544
	s_waitcnt lgkmcnt(12)
	v_add_u32_e32 v220, s48, v232
	v_cmp_lt_i32_e32 vcc, 0, v220
	s_nop 1
	v_cndmask_b32_e32 v174, 0, v174, vcc
	v_cndmask_b32_e32 v175, 0, v175, vcc
	v_cmp_gt_i32_e32 vcc, s28, v220
	s_nop 1
	v_cndmask_b32_e32 v194, 0, v194, vcc
	v_cndmask_b32_e32 v195, 0, v195, vcc
	v_pk_fma_f32 v[202:203], v[156:157], v[174:175], v[168:169]
	v_pk_fma_f32 v[52:53], v[52:53], v[160:161], v[202:203]
	v_pk_fma_f32 v[52:53], v[164:165], v[194:195], v[52:53]
	ds_read_b64 v[174:175], v244 offset:1024
	ds_read_b64 v[194:195], v243 offset:1056
	s_waitcnt lgkmcnt(11)
; #define PG8_LAS __attribute__((address_space(3)))
; __device__ __forceinline__ unsigned cvt_pk_bf16(float lo, float hi) { unsigned r; asm volatile("v_cvt_pk_bf16_f32 %0, %1, %2" : "=v"(r) : "v"(lo), "v"(hi)); return r; }
;     __device__ __forceinline__ void operator()(const f32x4 (&acc)[2][2][4][2], const Unit& u, int wr, int wc, int fr, int fq) const {
;     ...
;                 for (int m = 0; m < 4; ++m) { const int r = 128 * ai + 64 * wr + 16 * m + fr, t = tstart + r;
;                     const bool upok = t >= 1, dnok = (t + 1) < T, store_ok = (r >= vlo) && (r < vhi) && (t < T);
;                     f32x4 res[2];
; #pragma unroll
;                     for (int bj = 0; bj < 2; ++bj) { const f32x4 cur = acc[ai][bj][m][n];
;                         f32x4 su = cur, sd = cur;
;                         if (m > 0) { if (fr == 15) su = acc[ai][bj][m > 0 ? m - 1 : 0][n]; }
;                         if (m < 3) { if (fr == 0) sd = acc[ai][bj][m < 3 ? m + 1 : 3][n]; }
;                         f32x4 up, dn;
;                         up[0] = dpp_ror1(su[0]); up[1] = dpp_ror1(su[1]); up[2] = dpp_ror1(su[2]); up[3] = dpp_ror1(su[3]);
;                         dn[0] = dpp_ror15(sd[0]); dn[1] = dpp_ror15(sd[1]); dn[2] = dpp_ror15(sd[2]); dn[3] = dpp_ror15(sd[3]);
;                         if (m == 0) { f32x4 halo = zero4; if (blk > 0) halo = *(const PG8_LAS f32x4*)(xb + (((((blk - 1) * 2 + 1) * 4 + wc) * 4 + fq) * 16 + (bj * 2 + n) * 4)); if (fr == 0) up = halo; }
;                         if (m == 3) { f32x4 halo = zero4; if (blk < 3) halo = *(const PG8_LAS f32x4*)(xb + (((((blk + 1) * 2 + 0) * 4 + wc) * 4 + fq) * 16 + (bj * 2 + n) * 4)); if (fr == 15) dn = halo; }
;                         if (edge) { if (!upok) up = zero4; if (!dnok) dn = zero4; }
;                         res[bj] = bb[bj] + w0[bj] * up + w1[bj] * cur + w2[bj] * dn; }
;                     if (store_ok) {
;                         float o[4];
; #pragma unroll
;                         for (int j = 0; j < 4; ++j) { const float gg = res[1][j]; o[j] = gg * __builtin_amdgcn_rcpf(1.f + __expf(-gg)) * res[0][j]; }
;                         u32x2 w; w.x = cvt_pk_bf16(o[0], o[1]); w.y = cvt_pk_bf16(o[2], o[3]);
;                         *(u32x2*)(ACT + (size_t)(seqrow + t) * 2816 + ch0 + 4 * n) = w; } } }
	v_cndmask_b32_e64 v196, v196, v200, s[4:5]
	v_cndmask_b32_e64 v197, v197, v201, s[4:5]
	v_add_u32_e32 v220, s48, v233
	v_cmp_lt_i32_e32 vcc, 0, v220
	s_nop 1
	v_cndmask_b32_e32 v176, 0, v176, vcc
	v_cndmask_b32_e32 v177, 0, v177, vcc
	v_cmp_gt_i32_e32 vcc, s28, v220
	s_nop 1
	v_cndmask_b32_e32 v196, 0, v196, vcc
	v_cndmask_b32_e32 v197, 0, v197, vcc
	v_pk_fma_f32 v[202:203], v[156:157], v[176:177], v[168:169]
	v_pk_fma_f32 v[44:45], v[44:45], v[160:161], v[202:203]
	v_pk_fma_f32 v[44:45], v[164:165], v[196:197], v[44:45]
	ds_read_b64 v[176:177], v244 offset:1536
	ds_read_b64 v[196:197], v243 offset:1568
	ds_read_b64 v[200:201], v246 offset:16
	v_mul_f32_e32 v208, 0xbfb8aa3b, v66
	v_mul_f32_e32 v209, 0xbfb8aa3b, v67
	v_mul_f32_e32 v210, 0xbfb8aa3b, v68
	v_mul_f32_e32 v211, 0xbfb8aa3b, v69
	v_exp_f32_e32 v208, v208
	v_exp_f32_e32 v209, v209
	v_exp_f32_e32 v210, v210
	v_exp_f32_e32 v211, v211
	v_add_f32_e32 v208, 1.0, v208
	v_add_f32_e32 v209, 1.0, v209
	v_add_f32_e32 v210, 1.0, v210
	v_add_f32_e32 v211, 1.0, v211
	v_rcp_f32_e32 v208, v208
	v_rcp_f32_e32 v209, v209
	v_rcp_f32_e32 v210, v210
	v_rcp_f32_e32 v211, v211
	v_mul_f32_e32 v66, v66, v208
	v_mul_f32_e32 v67, v67, v209
	v_mul_f32_e32 v68, v68, v210
	v_mul_f32_e32 v69, v69, v211
	v_mul_f32_e32 v66, v70, v66
	v_mul_f32_e32 v67, v71, v67
	v_mul_f32_e32 v68, v72, v68
	v_mul_f32_e32 v69, v73, v69
	v_cvt_pk_bf16_f32 v212, v66, v67
	v_cvt_pk_bf16_f32 v213, v68, v69
	v_mad_u32_u24 v221, v227, s29, v247
	s_and_saveexec_b64 s[30:31], s[12:13]
	global_store_dwordx2 v221, v[212:213], s[10:11] offset:8
	s_mov_b64 exec, s[30:31]
	v_mul_f32_e32 v208, 0xbfb8aa3b, v58
	v_mul_f32_e32 v209, 0xbfb8aa3b, v59
	v_mul_f32_e32 v210, 0xbfb8aa3b, v60
	v_mul_f32_e32 v211, 0xbfb8aa3b, v61
	v_exp_f32_e32 v208, v208
	v_exp_f32_e32 v209, v209
	v_exp_f32_e32 v210, v210
	v_exp_f32_e32 v211, v211
	v_add_f32_e32 v208, 1.0, v208
	v_add_f32_e32 v209, 1.0, v209
	v_add_f32_e32 v210, 1.0, v210
	v_add_f32_e32 v211, 1.0, v211
	v_rcp_f32_e32 v208, v208
	v_rcp_f32_e32 v209, v209
	v_rcp_f32_e32 v210, v210
	v_rcp_f32_e32 v211, v211
	v_mul_f32_e32 v58, v58, v208
	v_mul_f32_e32 v59, v59, v209
	v_mul_f32_e32 v60, v60, v210
	v_mul_f32_e32 v61, v61, v211
	v_mul_f32_e32 v58, v62, v58
	v_mul_f32_e32 v59, v63, v59
	v_mul_f32_e32 v60, v64, v60
	v_mul_f32_e32 v61, v65, v61
	v_cvt_pk_bf16_f32 v218, v58, v59
	v_cvt_pk_bf16_f32 v219, v60, v61
	v_mad_u32_u24 v40, v231, s29, v247
	s_and_saveexec_b64 s[30:31], s[14:15]
	global_store_dwordx2 v40, v[218:219], s[10:11] offset:8
	s_mov_b64 exec, s[30:31]
	v_mul_f32_e32 v208, 0xbfb8aa3b, v50
	v_mul_f32_e32 v209, 0xbfb8aa3b, v51
	v_mul_f32_e32 v210, 0xbfb8aa3b, v52
	v_mul_f32_e32 v211, 0xbfb8aa3b, v53
	v_exp_f32_e32 v208, v208
	v_exp_f32_e32 v209, v209
	v_exp_f32_e32 v210, v210
	v_exp_f32_e32 v211, v211
	v_add_f32_e32 v208, 1.0, v208
	v_add_f32_e32 v209, 1.0, v209
	v_add_f32_e32 v210, 1.0, v210
	v_add_f32_e32 v211, 1.0, v211
	v_rcp_f32_e32 v208, v208
	v_rcp_f32_e32 v209, v209
	v_rcp_f32_e32 v210, v210
	v_rcp_f32_e32 v211, v211
	v_mul_f32_e32 v50, v50, v208
	v_mul_f32_e32 v51, v51, v209
	v_mul_f32_e32 v52, v52, v210
	v_mul_f32_e32 v53, v53, v211
	v_mul_f32_e32 v50, v54, v50
	v_mul_f32_e32 v51, v55, v51
	v_mul_f32_e32 v52, v56, v52
	v_mul_f32_e32 v53, v57, v53
	v_cvt_pk_bf16_f32 v212, v50, v51
	v_cvt_pk_bf16_f32 v213, v52, v53
	v_mad_u32_u24 v221, v232, s29, v247
	s_and_saveexec_b64 s[30:31], s[16:17]
	global_store_dwordx2 v221, v[212:213], s[10:11] offset:8
	s_mov_b64 exec, s[30:31]
	v_mul_f32_e32 v208, 0xbfb8aa3b, v42
	v_mul_f32_e32 v209, 0xbfb8aa3b, v43
	v_mul_f32_e32 v210, 0xbfb8aa3b, v44
	v_mul_f32_e32 v211, 0xbfb8aa3b, v45
	v_exp_f32_e32 v208, v208
	v_exp_f32_e32 v209, v209
	v_exp_f32_e32 v210, v210
	v_exp_f32_e32 v211, v211
	v_add_f32_e32 v208, 1.0, v208
	v_add_f32_e32 v209, 1.0, v209
	v_add_f32_e32 v210, 1.0, v210
	v_add_f32_e32 v211, 1.0, v211
	v_rcp_f32_e32 v208, v208
	v_rcp_f32_e32 v209, v209
	v_rcp_f32_e32 v210, v210
	v_rcp_f32_e32 v211, v211
	v_mul_f32_e32 v42, v42, v208
	v_mul_f32_e32 v43, v43, v209
	v_mul_f32_e32 v44, v44, v210
	v_mul_f32_e32 v45, v45, v211
	v_mul_f32_e32 v42, v46, v42
	v_mul_f32_e32 v43, v47, v43
	v_mul_f32_e32 v44, v48, v44
	v_mul_f32_e32 v45, v49, v45
	v_cvt_pk_bf16_f32 v218, v42, v43
	v_cvt_pk_bf16_f32 v219, v44, v45
	v_mad_u32_u24 v40, v233, s29, v247
	s_and_saveexec_b64 s[30:31], s[18:19]
	global_store_dwordx2 v40, v[218:219], s[10:11] offset:8
	s_mov_b64 exec, s[30:31]
	ds_write_b64 v243, v[32:33]
	ds_write_b64 v243, v[24:25] offset:512
	ds_write_b64 v243, v[16:17] offset:1024
	ds_write_b64 v243, v[8:9] offset:1536
	s_waitcnt lgkmcnt(11)
	v_cndmask_b32_e64 v170, v170, v198, s[6:7]
	v_cndmask_b32_e64 v171, v171, v199, s[6:7]
	v_add_u32_e32 v220, s48, v234
	v_cmp_lt_i32_e32 vcc, 0, v220
	s_nop 1
	v_cndmask_b32_e32 v170, 0, v170, vcc
	v_cndmask_b32_e32 v171, 0, v171, vcc
	v_cmp_gt_i32_e32 vcc, s28, v220
	s_nop 1
	v_cndmask_b32_e32 v178, 0, v178, vcc
	v_cndmask_b32_e32 v179, 0, v179, vcc
	v_pk_fma_f32 v[202:203], v[138:139], v[170:171], v[150:151]
	v_pk_fma_f32 v[30:31], v[30:31], v[142:143], v[202:203]
	v_pk_fma_f32 v[30:31], v[146:147], v[178:179], v[30:31]
	ds_read_b64 v[170:171], v244
	ds_read_b64 v[178:179], v243 offset:32
	ds_read_b64 v[198:199], v238 offset:3096
	s_waitcnt lgkmcnt(12)
	v_add_u32_e32 v220, s48, v235
	v_cmp_lt_i32_e32 vcc, 0, v220
	s_nop 1
	v_cndmask_b32_e32 v172, 0, v172, vcc
	v_cndmask_b32_e32 v173, 0, v173, vcc
	v_cmp_gt_i32_e32 vcc, s28, v220
	s_nop 1
	v_cndmask_b32_e32 v180, 0, v180, vcc
	v_cndmask_b32_e32 v181, 0, v181, vcc
	v_pk_fma_f32 v[202:203], v[138:139], v[172:173], v[150:151]
	v_pk_fma_f32 v[22:23], v[22:23], v[142:143], v[202:203]
	v_pk_fma_f32 v[22:23], v[146:147], v[180:181], v[22:23]
	ds_read_b64 v[172:173], v244 offset:512
	ds_read_b64 v[180:181], v243 offset:544
	s_waitcnt lgkmcnt(12)
; #define PG8_LAS __attribute__((address_space(3)))
; __device__ __forceinline__ unsigned cvt_pk_bf16(float lo, float hi) { unsigned r; asm volatile("v_cvt_pk_bf16_f32 %0, %1, %2" : "=v"(r) : "v"(lo), "v"(hi)); return r; }
;     __device__ __forceinline__ void operator()(const f32x4 (&acc)[2][2][4][2], const Unit& u, int wr, int wc, int fr, int fq) const {
;     ...
;                 for (int m = 0; m < 4; ++m) { const int r = 128 * ai + 64 * wr + 16 * m + fr, t = tstart + r;
;                     const bool upok = t >= 1, dnok = (t + 1) < T, store_ok = (r >= vlo) && (r < vhi) && (t < T);
;                     f32x4 res[2];
; #pragma unroll
;                     for (int bj = 0; bj < 2; ++bj) { const f32x4 cur = acc[ai][bj][m][n];
;                         f32x4 su = cur, sd = cur;
;                         if (m > 0) { if (fr == 15) su = acc[ai][bj][m > 0 ? m - 1 : 0][n]; }
;                         if (m < 3) { if (fr == 0) sd = acc[ai][bj][m < 3 ? m + 1 : 3][n]; }
;                         f32x4 up, dn;
;                         up[0] = dpp_ror1(su[0]); up[1] = dpp_ror1(su[1]); up[2] = dpp_ror1(su[2]); up[3] = dpp_ror1(su[3]);
;                         dn[0] = dpp_ror15(sd[0]); dn[1] = dpp_ror15(sd[1]); dn[2] = dpp_ror15(sd[2]); dn[3] = dpp_ror15(sd[3]);
;                         if (m == 0) { f32x4 halo = zero4; if (blk > 0) halo = *(const PG8_LAS f32x4*)(xb + (((((blk - 1) * 2 + 1) * 4 + wc) * 4 + fq) * 16 + (bj * 2 + n) * 4)); if (fr == 0) up = halo; }
;                         if (m == 3) { f32x4 halo = zero4; if (blk < 3) halo = *(const PG8_LAS f32x4*)(xb + (((((blk + 1) * 2 + 0) * 4 + wc) * 4 + fq) * 16 + (bj * 2 + n) * 4)); if (fr == 15) dn = halo; }
;                         if (edge) { if (!upok) up = zero4; if (!dnok) dn = zero4; }
;                         res[bj] = bb[bj] + w0[bj] * up + w1[bj] * cur + w2[bj] * dn; }
;                     if (store_ok) {
;                         float o[4];
; #pragma unroll
;                         for (int j = 0; j < 4; ++j) { const float gg = res[1][j]; o[j] = gg * __builtin_amdgcn_rcpf(1.f + __expf(-gg)) * res[0][j]; }
;                         u32x2 w; w.x = cvt_pk_bf16(o[0], o[1]); w.y = cvt_pk_bf16(o[2], o[3]);
;                         *(u32x2*)(ACT + (size_t)(seqrow + t) * 2816 + ch0 + 4 * n) = w; } } }
	v_add_u32_e32 v220, s48, v236
	v_cmp_lt_i32_e32 vcc, 0, v220
	s_nop 1
	v_cndmask_b32_e32 v174, 0, v174, vcc
	v_cndmask_b32_e32 v175, 0, v175, vcc
	v_cmp_gt_i32_e32 vcc, s28, v220
	s_nop 1
	v_cndmask_b32_e32 v194, 0, v194, vcc
	v_cndmask_b32_e32 v195, 0, v195, vcc
	v_pk_fma_f32 v[202:203], v[138:139], v[174:175], v[150:151]
	v_pk_fma_f32 v[14:15], v[14:15], v[142:143], v[202:203]
	v_pk_fma_f32 v[14:15], v[146:147], v[194:195], v[14:15]
	ds_read_b64 v[174:175], v244 offset:1024
	ds_read_b64 v[194:195], v243 offset:1056
	s_waitcnt lgkmcnt(11)
	v_cndmask_b32_e64 v196, v196, v200, s[4:5]
	v_cndmask_b32_e64 v197, v197, v201, s[4:5]
	v_add_u32_e32 v220, s48, v237
	v_cmp_lt_i32_e32 vcc, 0, v220
	s_nop 1
	v_cndmask_b32_e32 v176, 0, v176, vcc
	v_cndmask_b32_e32 v177, 0, v177, vcc
	v_cmp_gt_i32_e32 vcc, s28, v220
	s_nop 1
	v_cndmask_b32_e32 v196, 0, v196, vcc
	v_cndmask_b32_e32 v197, 0, v197, vcc
	v_pk_fma_f32 v[202:203], v[138:139], v[176:177], v[150:151]
	v_pk_fma_f32 v[6:7], v[6:7], v[142:143], v[202:203]
	v_pk_fma_f32 v[6:7], v[146:147], v[196:197], v[6:7]
	ds_read_b64 v[176:177], v244 offset:1536
	ds_read_b64 v[196:197], v243 offset:1568
	ds_read_b64 v[200:201], v246 offset:24
	ds_write_b64 v243, v[26:27]
	ds_write_b64 v243, v[18:19] offset:512
	ds_write_b64 v243, v[10:11] offset:1024
	ds_write_b64 v243, v[2:3] offset:1536
	s_waitcnt lgkmcnt(11)
	v_cndmask_b32_e64 v170, v170, v198, s[6:7]
	v_cndmask_b32_e64 v171, v171, v199, s[6:7]
	v_add_u32_e32 v220, s48, v234
	v_cmp_lt_i32_e32 vcc, 0, v220
	s_nop 1
	v_cndmask_b32_e32 v170, 0, v170, vcc
	v_cndmask_b32_e32 v171, 0, v171, vcc
	v_cmp_gt_i32_e32 vcc, s28, v220
	s_nop 1
	v_cndmask_b32_e32 v178, 0, v178, vcc
	v_cndmask_b32_e32 v179, 0, v179, vcc
	v_pk_fma_f32 v[202:203], v[140:141], v[170:171], v[152:153]
	v_pk_fma_f32 v[32:33], v[32:33], v[144:145], v[202:203]
	v_pk_fma_f32 v[32:33], v[148:149], v[178:179], v[32:33]
	ds_read_b64 v[170:171], v244
	ds_read_b64 v[178:179], v243 offset:32
	ds_read_b64 v[198:199], v238 offset:3120
	s_waitcnt lgkmcnt(12)
	v_add_u32_e32 v220, s48, v235
	v_cmp_lt_i32_e32 vcc, 0, v220
	s_nop 1
	v_cndmask_b32_e32 v172, 0, v172, vcc
	v_cndmask_b32_e32 v173, 0, v173, vcc
	v_cmp_gt_i32_e32 vcc, s28, v220
	s_nop 1
	v_cndmask_b32_e32 v180, 0, v180, vcc
	v_cndmask_b32_e32 v181, 0, v181, vcc
	v_pk_fma_f32 v[202:203], v[140:141], v[172:173], v[152:153]
	v_pk_fma_f32 v[24:25], v[24:25], v[144:145], v[202:203]
	v_pk_fma_f32 v[24:25], v[148:149], v[180:181], v[24:25]
	ds_read_b64 v[172:173], v244 offset:512
	ds_read_b64 v[180:181], v243 offset:544
	s_waitcnt lgkmcnt(12)
	v_add_u32_e32 v220, s48, v236
	v_cmp_lt_i32_e32 vcc, 0, v220
	s_nop 1
	v_cndmask_b32_e32 v174, 0, v174, vcc
	v_cndmask_b32_e32 v175, 0, v175, vcc
	v_cmp_gt_i32_e32 vcc, s28, v220
	s_nop 1
	v_cndmask_b32_e32 v194, 0, v194, vcc
	v_cndmask_b32_e32 v195, 0, v195, vcc
	v_pk_fma_f32 v[202:203], v[140:141], v[174:175], v[152:153]
	v_pk_fma_f32 v[16:17], v[16:17], v[144:145], v[202:203]
	v_pk_fma_f32 v[16:17], v[148:149], v[194:195], v[16:17]
	ds_read_b64 v[174:175], v244 offset:1024
	ds_read_b64 v[194:195], v243 offset:1056
	s_waitcnt lgkmcnt(11)
	v_cndmask_b32_e64 v196, v196, v200, s[4:5]
	v_cndmask_b32_e64 v197, v197, v201, s[4:5]
	v_add_u32_e32 v220, s48, v237
	v_cmp_lt_i32_e32 vcc, 0, v220
	s_nop 1
	v_cndmask_b32_e32 v176, 0, v176, vcc
	v_cndmask_b32_e32 v177, 0, v177, vcc
	v_cmp_gt_i32_e32 vcc, s28, v220
	s_nop 1
	v_cndmask_b32_e32 v196, 0, v196, vcc
	v_cndmask_b32_e32 v197, 0, v197, vcc
	v_pk_fma_f32 v[202:203], v[140:141], v[176:177], v[152:153]
	v_pk_fma_f32 v[8:9], v[8:9], v[144:145], v[202:203]
	v_pk_fma_f32 v[8:9], v[148:149], v[196:197], v[8:9]
	ds_read_b64 v[176:177], v244 offset:1536
	ds_read_b64 v[196:197], v243 offset:1568
	ds_read_b64 v[200:201], v246 offset:48
	ds_write_b64 v243, v[28:29]
	ds_write_b64 v243, v[20:21] offset:512
	ds_write_b64 v243, v[12:13] offset:1024
	ds_write_b64 v243, v[4:5] offset:1536
	s_waitcnt lgkmcnt(11)
	v_cndmask_b32_e64 v170, v170, v198, s[6:7]
	v_cndmask_b32_e64 v171, v171, v199, s[6:7]
	v_add_u32_e32 v220, s48, v234
	v_cmp_lt_i32_e32 vcc, 0, v220
	s_nop 1
	v_cndmask_b32_e32 v170, 0, v170, vcc
	v_cndmask_b32_e32 v171, 0, v171, vcc
	v_cmp_gt_i32_e32 vcc, s28, v220
	s_nop 1
	v_cndmask_b32_e32 v178, 0, v178, vcc
	v_cndmask_b32_e32 v179, 0, v179, vcc
	v_pk_fma_f32 v[202:203], v[154:155], v[170:171], v[166:167]
	v_pk_fma_f32 v[26:27], v[26:27], v[158:159], v[202:203]
	v_pk_fma_f32 v[26:27], v[162:163], v[178:179], v[26:27]
	ds_read_b64 v[170:171], v244
	ds_read_b64 v[178:179], v243 offset:32
	ds_read_b64 v[198:199], v238 offset:3128
	s_waitcnt lgkmcnt(12)
	v_add_u32_e32 v220, s48, v235
	v_cmp_lt_i32_e32 vcc, 0, v220
	s_nop 1
	v_cndmask_b32_e32 v172, 0, v172, vcc
	v_cndmask_b32_e32 v173, 0, v173, vcc
	v_cmp_gt_i32_e32 vcc, s28, v220
	s_nop 1
	v_cndmask_b32_e32 v180, 0, v180, vcc
	v_cndmask_b32_e32 v181, 0, v181, vcc
	v_pk_fma_f32 v[202:203], v[154:155], v[172:173], v[166:167]
	v_pk_fma_f32 v[18:19], v[18:19], v[158:159], v[202:203]
	v_pk_fma_f32 v[18:19], v[162:163], v[180:181], v[18:19]
	ds_read_b64 v[172:173], v244 offset:512
	ds_read_b64 v[180:181], v243 offset:544
	s_waitcnt lgkmcnt(12)
	v_add_u32_e32 v220, s48, v236
	v_cmp_lt_i32_e32 vcc, 0, v220
	s_nop 1
	v_cndmask_b32_e32 v174, 0, v174, vcc
	v_cndmask_b32_e32 v175, 0, v175, vcc
	v_cmp_gt_i32_e32 vcc, s28, v220
	s_nop 1
	v_cndmask_b32_e32 v194, 0, v194, vcc
	v_cndmask_b32_e32 v195, 0, v195, vcc
	v_pk_fma_f32 v[202:203], v[154:155], v[174:175], v[166:167]
	v_pk_fma_f32 v[10:11], v[10:11], v[158:159], v[202:203]
	v_pk_fma_f32 v[10:11], v[162:163], v[194:195], v[10:11]
	ds_read_b64 v[174:175], v244 offset:1024
	ds_read_b64 v[194:195], v243 offset:1056
	s_waitcnt lgkmcnt(11)
; #define PG8_LAS __attribute__((address_space(3)))
; __device__ __forceinline__ unsigned cvt_pk_bf16(float lo, float hi) { unsigned r; asm volatile("v_cvt_pk_bf16_f32 %0, %1, %2" : "=v"(r) : "v"(lo), "v"(hi)); return r; }
;     __device__ __forceinline__ void operator()(const f32x4 (&acc)[2][2][4][2], const Unit& u, int wr, int wc, int fr, int fq) const {
;     ...
;                 for (int m = 0; m < 4; ++m) { const int r = 128 * ai + 64 * wr + 16 * m + fr, t = tstart + r;
;                     const bool upok = t >= 1, dnok = (t + 1) < T, store_ok = (r >= vlo) && (r < vhi) && (t < T);
;                     f32x4 res[2];
; #pragma unroll
;                     for (int bj = 0; bj < 2; ++bj) { const f32x4 cur = acc[ai][bj][m][n];
;                         f32x4 su = cur, sd = cur;
;                         if (m > 0) { if (fr == 15) su = acc[ai][bj][m > 0 ? m - 1 : 0][n]; }
;                         if (m < 3) { if (fr == 0) sd = acc[ai][bj][m < 3 ? m + 1 : 3][n]; }
;                         f32x4 up, dn;
;                         up[0] = dpp_ror1(su[0]); up[1] = dpp_ror1(su[1]); up[2] = dpp_ror1(su[2]); up[3] = dpp_ror1(su[3]);
;                         dn[0] = dpp_ror15(sd[0]); dn[1] = dpp_ror15(sd[1]); dn[2] = dpp_ror15(sd[2]); dn[3] = dpp_ror15(sd[3]);
;                         if (m == 0) { f32x4 halo = zero4; if (blk > 0) halo = *(const PG8_LAS f32x4*)(xb + (((((blk - 1) * 2 + 1) * 4 + wc) * 4 + fq) * 16 + (bj * 2 + n) * 4)); if (fr == 0) up = halo; }
;                         if (m == 3) { f32x4 halo = zero4; if (blk < 3) halo = *(const PG8_LAS f32x4*)(xb + (((((blk + 1) * 2 + 0) * 4 + wc) * 4 + fq) * 16 + (bj * 2 + n) * 4)); if (fr == 15) dn = halo; }
;                         if (edge) { if (!upok) up = zero4; if (!dnok) dn = zero4; }
;                         res[bj] = bb[bj] + w0[bj] * up + w1[bj] * cur + w2[bj] * dn; }
;                     if (store_ok) {
;                         float o[4];
; #pragma unroll
;                         for (int j = 0; j < 4; ++j) { const float gg = res[1][j]; o[j] = gg * __builtin_amdgcn_rcpf(1.f + __expf(-gg)) * res[0][j]; }
;                         u32x2 w; w.x = cvt_pk_bf16(o[0], o[1]); w.y = cvt_pk_bf16(o[2], o[3]);
;                         *(u32x2*)(ACT + (size_t)(seqrow + t) * 2816 + ch0 + 4 * n) = w; } } }
	v_cndmask_b32_e64 v196, v196, v200, s[4:5]
	v_cndmask_b32_e64 v197, v197, v201, s[4:5]
	v_add_u32_e32 v220, s48, v237
	v_cmp_lt_i32_e32 vcc, 0, v220
	s_nop 1
	v_cndmask_b32_e32 v176, 0, v176, vcc
	v_cndmask_b32_e32 v177, 0, v177, vcc
	v_cmp_gt_i32_e32 vcc, s28, v220
	s_nop 1
	v_cndmask_b32_e32 v196, 0, v196, vcc
	v_cndmask_b32_e32 v197, 0, v197, vcc
	v_pk_fma_f32 v[202:203], v[154:155], v[176:177], v[166:167]
	v_pk_fma_f32 v[2:3], v[2:3], v[158:159], v[202:203]
	v_pk_fma_f32 v[2:3], v[162:163], v[196:197], v[2:3]
	ds_read_b64 v[176:177], v244 offset:1536
	ds_read_b64 v[196:197], v243 offset:1568
	ds_read_b64 v[200:201], v246 offset:56
	s_waitcnt lgkmcnt(7)
	v_cndmask_b32_e64 v170, v170, v198, s[6:7]
	v_cndmask_b32_e64 v171, v171, v199, s[6:7]
	v_add_u32_e32 v220, s48, v234
	v_cmp_lt_i32_e32 vcc, 0, v220
	s_nop 1
	v_cndmask_b32_e32 v170, 0, v170, vcc
	v_cndmask_b32_e32 v171, 0, v171, vcc
	v_cmp_gt_i32_e32 vcc, s28, v220
	s_nop 1
	v_cndmask_b32_e32 v178, 0, v178, vcc
	v_cndmask_b32_e32 v179, 0, v179, vcc
	v_pk_fma_f32 v[202:203], v[156:157], v[170:171], v[168:169]
	v_pk_fma_f32 v[28:29], v[28:29], v[160:161], v[202:203]
	v_pk_fma_f32 v[28:29], v[164:165], v[178:179], v[28:29]
	s_waitcnt lgkmcnt(5)
	v_add_u32_e32 v220, s48, v235
	v_cmp_lt_i32_e32 vcc, 0, v220
	s_nop 1
	v_cndmask_b32_e32 v172, 0, v172, vcc
	v_cndmask_b32_e32 v173, 0, v173, vcc
	v_cmp_gt_i32_e32 vcc, s28, v220
	s_nop 1
	v_cndmask_b32_e32 v180, 0, v180, vcc
	v_cndmask_b32_e32 v181, 0, v181, vcc
	v_pk_fma_f32 v[202:203], v[156:157], v[172:173], v[168:169]
	v_pk_fma_f32 v[20:21], v[20:21], v[160:161], v[202:203]
	v_pk_fma_f32 v[20:21], v[164:165], v[180:181], v[20:21]
	s_waitcnt lgkmcnt(3)
	v_add_u32_e32 v220, s48, v236
	v_cmp_lt_i32_e32 vcc, 0, v220
	s_nop 1
	v_cndmask_b32_e32 v174, 0, v174, vcc
	v_cndmask_b32_e32 v175, 0, v175, vcc
	v_cmp_gt_i32_e32 vcc, s28, v220
	s_nop 1
	v_cndmask_b32_e32 v194, 0, v194, vcc
	v_cndmask_b32_e32 v195, 0, v195, vcc
	v_pk_fma_f32 v[202:203], v[156:157], v[174:175], v[168:169]
	v_pk_fma_f32 v[12:13], v[12:13], v[160:161], v[202:203]
	v_pk_fma_f32 v[12:13], v[164:165], v[194:195], v[12:13]
	s_waitcnt lgkmcnt(0)
	v_cndmask_b32_e64 v196, v196, v200, s[4:5]
	v_cndmask_b32_e64 v197, v197, v201, s[4:5]
	v_add_u32_e32 v220, s48, v237
	v_cmp_lt_i32_e32 vcc, 0, v220
	s_nop 1
	v_cndmask_b32_e32 v176, 0, v176, vcc
	v_cndmask_b32_e32 v177, 0, v177, vcc
	v_cmp_gt_i32_e32 vcc, s28, v220
	s_nop 1
	v_cndmask_b32_e32 v196, 0, v196, vcc
	v_cndmask_b32_e32 v197, 0, v197, vcc
	v_pk_fma_f32 v[202:203], v[156:157], v[176:177], v[168:169]
	v_pk_fma_f32 v[4:5], v[4:5], v[160:161], v[202:203]
	v_pk_fma_f32 v[4:5], v[164:165], v[196:197], v[4:5]
	v_mul_f32_e32 v208, 0xbfb8aa3b, v26
	v_mul_f32_e32 v209, 0xbfb8aa3b, v27
	v_mul_f32_e32 v210, 0xbfb8aa3b, v28
	v_mul_f32_e32 v211, 0xbfb8aa3b, v29
	v_exp_f32_e32 v208, v208
	v_exp_f32_e32 v209, v209
	v_exp_f32_e32 v210, v210
	v_exp_f32_e32 v211, v211
	v_add_f32_e32 v208, 1.0, v208
	v_add_f32_e32 v209, 1.0, v209
	v_add_f32_e32 v210, 1.0, v210
	v_add_f32_e32 v211, 1.0, v211
	v_rcp_f32_e32 v208, v208
	v_rcp_f32_e32 v209, v209
	v_rcp_f32_e32 v210, v210
	v_rcp_f32_e32 v211, v211
	v_mul_f32_e32 v26, v26, v208
	v_mul_f32_e32 v27, v27, v209
	v_mul_f32_e32 v28, v28, v210
	v_mul_f32_e32 v29, v29, v211
	v_mul_f32_e32 v26, v30, v26
	v_mul_f32_e32 v27, v31, v27
	v_mul_f32_e32 v28, v32, v28
	v_mul_f32_e32 v29, v33, v29
	v_cvt_pk_bf16_f32 v212, v26, v27
	v_cvt_pk_bf16_f32 v213, v28, v29
	v_mad_u32_u24 v221, v234, s29, v247
	s_and_saveexec_b64 s[30:31], s[20:21]
	global_store_dwordx2 v221, v[212:213], s[10:11] offset:8
	s_mov_b64 exec, s[30:31]
	v_mul_f32_e32 v208, 0xbfb8aa3b, v18
	v_mul_f32_e32 v209, 0xbfb8aa3b, v19
	v_mul_f32_e32 v210, 0xbfb8aa3b, v20
	v_mul_f32_e32 v211, 0xbfb8aa3b, v21
	v_exp_f32_e32 v208, v208
	v_exp_f32_e32 v209, v209
	v_exp_f32_e32 v210, v210
	v_exp_f32_e32 v211, v211
	v_add_f32_e32 v208, 1.0, v208
	v_add_f32_e32 v209, 1.0, v209
	v_add_f32_e32 v210, 1.0, v210
	v_add_f32_e32 v211, 1.0, v211
	v_rcp_f32_e32 v208, v208
	v_rcp_f32_e32 v209, v209
	v_rcp_f32_e32 v210, v210
	v_rcp_f32_e32 v211, v211
	v_mul_f32_e32 v18, v18, v208
	v_mul_f32_e32 v19, v19, v209
	v_mul_f32_e32 v20, v20, v210
	v_mul_f32_e32 v21, v21, v211
	v_mul_f32_e32 v18, v22, v18
	v_mul_f32_e32 v19, v23, v19
	v_mul_f32_e32 v20, v24, v20
	v_mul_f32_e32 v21, v25, v21
	v_cvt_pk_bf16_f32 v218, v18, v19
	v_cvt_pk_bf16_f32 v219, v20, v21
	v_mad_u32_u24 v40, v235, s29, v247
	s_and_saveexec_b64 s[30:31], s[22:23]
	global_store_dwordx2 v40, v[218:219], s[10:11] offset:8
	s_mov_b64 exec, s[30:31]
	v_mul_f32_e32 v208, 0xbfb8aa3b, v10
	v_mul_f32_e32 v209, 0xbfb8aa3b, v11
	v_mul_f32_e32 v210, 0xbfb8aa3b, v12
	v_mul_f32_e32 v211, 0xbfb8aa3b, v13
	v_exp_f32_e32 v208, v208
	v_exp_f32_e32 v209, v209
	v_exp_f32_e32 v210, v210
	v_exp_f32_e32 v211, v211
	v_add_f32_e32 v208, 1.0, v208
	v_add_f32_e32 v209, 1.0, v209
	v_add_f32_e32 v210, 1.0, v210
	v_add_f32_e32 v211, 1.0, v211
	v_rcp_f32_e32 v208, v208
	v_rcp_f32_e32 v209, v209
	v_rcp_f32_e32 v210, v210
	v_rcp_f32_e32 v211, v211
	v_mul_f32_e32 v10, v10, v208
	v_mul_f32_e32 v11, v11, v209
	v_mul_f32_e32 v12, v12, v210
	v_mul_f32_e32 v13, v13, v211
	v_mul_f32_e32 v10, v14, v10
	v_mul_f32_e32 v11, v15, v11
	v_mul_f32_e32 v12, v16, v12
	v_mul_f32_e32 v13, v17, v13
	v_cvt_pk_bf16_f32 v212, v10, v11
	v_cvt_pk_bf16_f32 v213, v12, v13
	v_mad_u32_u24 v221, v236, s29, v247
	s_and_saveexec_b64 s[30:31], s[24:25]
	global_store_dwordx2 v221, v[212:213], s[10:11] offset:8
	s_mov_b64 exec, s[30:31]
	v_mul_f32_e32 v208, 0xbfb8aa3b, v2
	v_mul_f32_e32 v209, 0xbfb8aa3b, v3
	v_mul_f32_e32 v210, 0xbfb8aa3b, v4
	v_mul_f32_e32 v211, 0xbfb8aa3b, v5
	v_exp_f32_e32 v208, v208
	v_exp_f32_e32 v209, v209
	v_exp_f32_e32 v210, v210
	v_exp_f32_e32 v211, v211
	v_add_f32_e32 v208, 1.0, v208
	v_add_f32_e32 v209, 1.0, v209
	v_add_f32_e32 v210, 1.0, v210
	v_add_f32_e32 v211, 1.0, v211
	v_rcp_f32_e32 v208, v208
	v_rcp_f32_e32 v209, v209
	v_rcp_f32_e32 v210, v210
	v_rcp_f32_e32 v211, v211
	v_mul_f32_e32 v2, v2, v208
	v_mul_f32_e32 v3, v3, v209
	v_mul_f32_e32 v4, v4, v210
	v_mul_f32_e32 v5, v5, v211
	v_mul_f32_e32 v2, v6, v2
	v_mul_f32_e32 v3, v7, v3
	v_mul_f32_e32 v4, v8, v4
	v_mul_f32_e32 v5, v9, v5
	v_cvt_pk_bf16_f32 v218, v2, v3
	v_cvt_pk_bf16_f32 v219, v4, v5
	v_mad_u32_u24 v40, v237, s29, v247
	s_and_saveexec_b64 s[30:31], s[26:27]
	global_store_dwordx2 v40, v[218:219], s[10:11] offset:8
	s_mov_b64 exec, s[30:31]
.Lec_done:
	s_mov_b64 s[2:3], exec
.LBB0_916:
	s_or_b64 exec, exec, s[2:3]
	s_and_b64 vcc, exec, s[8:9]
	s_mov_b64 s[0:1], -1
	s_cbranch_vccnz .LBB0_687
	v_readlane_b32 s0, v255, 23
	v_readlane_b32 s1, v255, 24
	s_andn2_b64 vcc, exec, s[0:1]
	s_cbranch_vccnz .LBB0_686
	s_barrier
	s_branch .LBB0_686
